# v6_attn
# baseline (speedup 1.0000x reference)
; #define MFMA32(a, b, c) __builtin_amdgcn_mfma_f32_32x32x16_bf16((a), (b), (c), 0, 0, 0)
; template <int DQK, int MODE>
; DI void attn_core(const u16* __restrict__ Qg, int ldq, const u16* __restrict__ Kg, int ldk, const u16* __restrict__ Vtg,
;                   const u64* __restrict__ maskg, int q0, float scale, char* smem, int* sflags, f32x16 (&o)[4], float& l_run) {
;     ...
;       const float m_new = fmaxf(m_run, mx);
;       const float alpha = __builtin_amdgcn_exp2f((m_run - m_new) * sc);
;       m_run = m_new;
;       const float msc = -m_new * sc;
;       float ls = 0.f;
; #pragma unroll
;       for (int kt = 0; kt < 2; ++kt)
; #pragma unroll
;         for (int i = 0; i < 16; ++i) {
;           float pv = __builtin_amdgcn_exp2f(__builtin_fmaf(s[kt][i], sc, msc));
;           if (MODE == 1) pv = (s[kt][i] > -1e29f) ? pv : 0.f;
;           s[kt][i] = pv;
;           ls += pv;
;         }
;       if (__any(alpha != 1.0f)) {
;         l_run *= alpha;
; #pragma unroll
;         for (int t = 0; t < 4; ++t)
; #pragma unroll
;           for (int i = 0; i < 16; ++i) o[t][i] *= alpha;
;       }
;       l_run += ls;
;     ...
; #pragma unroll
;     for (int kt = 0; kt < 2; ++kt)
; #pragma unroll
;       for (int sb = 0; sb < 2; ++sb) {
;         const bf16x8 pf = pack8(s[kt][8 * sb + 0], s[kt][8 * sb + 1], s[kt][8 * sb + 2], s[kt][8 * sb + 3],
;                                 s[kt][8 * sb + 4], s[kt][8 * sb + 5], s[kt][8 * sb + 6], s[kt][8 * sb + 7]);
; #pragma unroll
;         for (int t = 0; t < 4; ++t) {
;           const bf16x8 vf = *(const bf16x8*)(Vs + (32 * t + l31) * 72 + 32 * kt + 16 * sb + hh * 8);
;           o[t] = MFMA32(vf, pf, o[t]);
;         }
;       }
.LBB0_154:
	v_mul_f32_e32 v106, 0xbe0293ee, v2
	v_fmamk_f32 v0, v200, 0x3e0293ee, v106
	v_exp_f32_e32 v0, v0
	v_fmamk_f32 v82, v187, 0x3e0293ee, v106
	v_exp_f32_e32 v82, v82
	v_cmp_lt_f32_e32 vcc, s18, v200
	v_fmamk_f32 v84, v105, 0x3e0293ee, v106
	v_exp_f32_e32 v84, v84
	v_cndmask_b32_e32 v83, 0, v0, vcc
	v_cmp_lt_f32_e32 vcc, s18, v187
	v_fmamk_f32 v85, v104, 0x3e0293ee, v106
	v_exp_f32_e32 v85, v85
	v_cndmask_b32_e32 v86, 0, v82, vcc
	v_fmamk_f32 v82, v199, 0x3e0293ee, v106
	v_exp_f32_e32 v82, v82
	v_cmp_lt_f32_e32 vcc, s18, v199
	v_fmamk_f32 v88, v103, 0x3e0293ee, v106
	v_exp_f32_e32 v88, v88
	v_cndmask_b32_e32 v87, 0, v82, vcc
	v_fmamk_f32 v82, v198, 0x3e0293ee, v106
	v_exp_f32_e32 v82, v82
	v_cmp_lt_f32_e32 vcc, s18, v198
	v_fmamk_f32 v89, v102, 0x3e0293ee, v106
	v_exp_f32_e32 v89, v89
	v_cndmask_b32_e32 v90, 0, v82, vcc
	v_fmamk_f32 v82, v201, 0x3e0293ee, v106
	v_exp_f32_e32 v82, v82
	v_cmp_lt_f32_e32 vcc, s18, v201
	v_fmamk_f32 v92, v10, 0x3e0293ee, v106
	v_exp_f32_e32 v92, v92
	v_cndmask_b32_e32 v91, 0, v82, vcc
	v_fmamk_f32 v82, v96, 0x3e0293ee, v106
	v_exp_f32_e32 v82, v82
	v_cmp_lt_f32_e32 vcc, s18, v96
	v_add_f32_e32 v0, 0, v83
	v_add_f32_e32 v0, v86, v0
	v_cndmask_b32_e32 v95, 0, v82, vcc
	v_fmamk_f32 v82, v186, 0x3e0293ee, v106
	v_exp_f32_e32 v82, v82
	v_cmp_lt_f32_e32 vcc, s18, v186
	v_add_f32_e32 v0, v87, v0
	v_add_f32_e32 v0, v90, v0
	v_cndmask_b32_e32 v96, 0, v82, vcc
	v_fmamk_f32 v82, v97, 0x3e0293ee, v106
	v_exp_f32_e32 v82, v82
	v_cmp_lt_f32_e32 vcc, s18, v97
	v_add_f32_e32 v0, v91, v0
	v_add_f32_e32 v0, v95, v0
	v_cndmask_b32_e32 v97, 0, v82, vcc
	v_fmamk_f32 v82, v185, 0x3e0293ee, v106
	v_exp_f32_e32 v82, v82
	v_cmp_lt_f32_e32 vcc, s18, v185
	v_add_f32_e32 v0, v96, v0
	v_add_f32_e32 v0, v97, v0
	v_cndmask_b32_e32 v82, 0, v82, vcc
	v_cmp_lt_f32_e32 vcc, s18, v105
	v_add_f32_e32 v0, v82, v0
	v_mov_b32_e32 v184, v2
	v_cndmask_b32_e32 v84, 0, v84, vcc
	v_cmp_lt_f32_e32 vcc, s18, v104
	v_add_f32_e32 v0, v84, v0
	s_nop 0
	v_cndmask_b32_e32 v85, 0, v85, vcc
	v_cmp_lt_f32_e32 vcc, s18, v103
	v_add_f32_e32 v0, v85, v0
	s_nop 0
	v_cndmask_b32_e32 v88, 0, v88, vcc
	v_cmp_lt_f32_e32 vcc, s18, v102
	v_add_f32_e32 v0, v88, v0
	s_nop 0
	v_cndmask_b32_e32 v89, 0, v89, vcc
	v_cmp_lt_f32_e32 vcc, s18, v10
	v_fmamk_f32 v10, v100, 0x3e0293ee, v106
	v_exp_f32_e32 v10, v10
	v_cndmask_b32_e32 v92, 0, v92, vcc
	v_cmp_lt_f32_e32 vcc, s18, v100
	v_add_f32_e32 v0, v89, v0
	v_add_f32_e32 v0, v92, v0
	v_cndmask_b32_e32 v93, 0, v10, vcc
	v_fmamk_f32 v10, v11, 0x3e0293ee, v106
	v_exp_f32_e32 v10, v10
	v_cmp_lt_f32_e32 vcc, s18, v11
	v_fmamk_f32 v11, v99, 0x3e0293ee, v106
	v_exp_f32_e32 v11, v11
	v_cndmask_b32_e32 v94, 0, v10, vcc
	v_fmamk_f32 v10, v101, 0x3e0293ee, v106
	v_exp_f32_e32 v10, v10
	v_cmp_lt_f32_e32 vcc, s18, v101
	v_add_f32_e32 v0, v93, v0
	v_add_f32_e32 v0, v94, v0
	v_cndmask_b32_e32 v10, 0, v10, vcc
	v_cmp_lt_f32_e32 vcc, s18, v99
	v_fmamk_f32 v99, v12, 0x3e0293ee, v106
	v_exp_f32_e32 v99, v99
	v_cndmask_b32_e32 v11, 0, v11, vcc
	v_cmp_lt_f32_e32 vcc, s18, v12
	v_add_f32_e32 v0, v10, v0
	v_add_f32_e32 v0, v11, v0
	v_cndmask_b32_e32 v12, 0, v99, vcc
	v_fmamk_f32 v99, v13, 0x3e0293ee, v106
	v_exp_f32_e32 v99, v99
	v_cmp_lt_f32_e32 vcc, s18, v13
	v_add_f32_e32 v0, v12, v0
	s_nop 0
	v_cndmask_b32_e32 v13, 0, v99, vcc
	v_fmamk_f32 v99, v14, 0x3e0293ee, v106
	v_exp_f32_e32 v99, v99
	v_cmp_lt_f32_e32 vcc, s18, v14
	v_add_f32_e32 v0, v13, v0
	s_nop 0
	v_cndmask_b32_e32 v14, 0, v99, vcc
	v_fmamk_f32 v99, v15, 0x3e0293ee, v106
	v_exp_f32_e32 v99, v99
	v_cmp_lt_f32_e32 vcc, s18, v15
	v_add_f32_e32 v0, v14, v0
	s_nop 0
	v_cndmask_b32_e32 v15, 0, v99, vcc
	v_fmamk_f32 v99, v80, 0x3e0293ee, v106
	v_exp_f32_e32 v99, v99
	v_cmp_lt_f32_e32 vcc, s18, v80
	v_add_f32_e32 v0, v15, v0
	s_nop 0
	v_cndmask_b32_e32 v80, 0, v99, vcc
	v_fmamk_f32 v99, v81, 0x3e0293ee, v106
	v_exp_f32_e32 v99, v99
	v_cmp_lt_f32_e32 vcc, s18, v81
	v_add_f32_e32 v0, v80, v0
	s_nop 0
	v_cndmask_b32_e32 v81, 0, v99, vcc
	v_add_f32_e32 v99, v81, v0
	v_fmamk_f32 v0, v98, 0x3e0293ee, v106
	v_exp_f32_e32 v0, v0
	v_cmp_lt_f32_e32 vcc, s18, v98
	s_nop 1
	v_cndmask_b32_e32 v0, 0, v0, vcc
	v_add_f32_e32 v98, v0, v99
	v_fmamk_f32 v99, v3, 0x3e0293ee, v106
	v_exp_f32_e32 v99, v99
	v_cmp_lt_f32_e32 vcc, s18, v3
	s_nop 1
	v_cndmask_b32_e32 v3, 0, v99, vcc
	v_fmamk_f32 v99, v4, 0x3e0293ee, v106
	v_exp_f32_e32 v99, v99
	v_cmp_lt_f32_e32 vcc, s18, v4
	v_add_f32_e32 v98, v3, v98
	s_nop 0
	v_cndmask_b32_e32 v4, 0, v99, vcc
	v_fmamk_f32 v99, v5, 0x3e0293ee, v106
	v_exp_f32_e32 v99, v99
	v_cmp_lt_f32_e32 vcc, s18, v5
	v_add_f32_e32 v98, v4, v98
	s_nop 0
	v_cndmask_b32_e32 v5, 0, v99, vcc
	v_fmamk_f32 v99, v6, 0x3e0293ee, v106
	v_exp_f32_e32 v99, v99
	v_cmp_lt_f32_e32 vcc, s18, v6
	v_add_f32_e32 v98, v5, v98
	s_nop 0
	v_cndmask_b32_e32 v6, 0, v99, vcc
	v_fmamk_f32 v99, v7, 0x3e0293ee, v106
	v_exp_f32_e32 v99, v99
	v_cmp_lt_f32_e32 vcc, s18, v7
	v_add_f32_e32 v98, v6, v98
	s_nop 0
	v_cndmask_b32_e32 v7, 0, v99, vcc
	v_fmamk_f32 v99, v8, 0x3e0293ee, v106
	v_exp_f32_e32 v99, v99
	v_cmp_lt_f32_e32 vcc, s18, v8
	v_fmac_f32_e32 v106, 0x3e0293ee, v9
	v_add_f32_e32 v98, v7, v98
	v_cndmask_b32_e32 v8, 0, v99, vcc
	v_exp_f32_e32 v99, v106
	v_cmp_lt_f32_e32 vcc, s18, v9
	v_add_f32_e32 v98, v8, v98
	s_nop 0
	v_cndmask_b32_e32 v9, 0, v99, vcc
	v_add_f32_e32 v98, v9, v98
	v_add_f32_e32 v161, v98, v161
	v_cvt_pk_bf16_f32 v98, v83, v86
	v_cvt_pk_bf16_f32 v99, v87, v90
	v_cvt_pk_bf16_f32 v100, v91, v95
	v_cvt_pk_bf16_f32 v101, v96, v97
	s_nop 1
	v_add_u32_e32 v83, v174, v175
	ds_read_b128 v[198:201], v83 offset:17408
	ds_read_b128 v[202:205], v83 offset:22016
	ds_read_b128 v[210:213], v83 offset:26624
	ds_read_b128 v[214:217], v83 offset:31232
	ds_read_b128 v[218:221], v83 offset:17440
	ds_read_b128 v[226:229], v83 offset:22048
	s_waitcnt lgkmcnt(5)
; #define MFMA32(a, b, c) __builtin_amdgcn_mfma_f32_32x32x16_bf16((a), (b), (c), 0, 0, 0)
; template <int DQK, int MODE>
; DI void attn_core(const u16* __restrict__ Qg, int ldq, const u16* __restrict__ Kg, int ldk, const u16* __restrict__ Vtg,
;                   const u64* __restrict__ maskg, int q0, float scale, char* smem, int* sflags, f32x16 (&o)[4], float& l_run) {
;     ...
; #pragma unroll
;     for (int kt = 0; kt < 2; ++kt)
; #pragma unroll
;       for (int sb = 0; sb < 2; ++sb) {
;         const bf16x8 pf = pack8(s[kt][8 * sb + 0], s[kt][8 * sb + 1], s[kt][8 * sb + 2], s[kt][8 * sb + 3],
;                                 s[kt][8 * sb + 4], s[kt][8 * sb + 5], s[kt][8 * sb + 6], s[kt][8 * sb + 7]);
; #pragma unroll
;         for (int t = 0; t < 4; ++t) {
;           const bf16x8 vf = *(const bf16x8*)(Vs + (32 * t + l31) * 72 + 32 * kt + 16 * sb + hh * 8);
;           o[t] = MFMA32(vf, pf, o[t]);
;         }
;       }
	v_mfma_f32_32x32x16_bf16 v[64:79], v[198:201], v[98:101], v[64:79]
	ds_read_b128 v[198:201], v83 offset:26656
	s_waitcnt lgkmcnt(5)
	v_mfma_f32_32x32x16_bf16 v[48:63], v[202:205], v[98:101], v[48:63]
	ds_read_b128 v[202:205], v83 offset:31264
	s_waitcnt lgkmcnt(5)
	v_mfma_f32_32x32x16_bf16 v[32:47], v[210:213], v[98:101], v[32:47]
	ds_read_b128 v[210:213], v83 offset:17472
	s_waitcnt lgkmcnt(5)
	v_mfma_f32_32x32x16_bf16 v[16:31], v[214:217], v[98:101], v[16:31]
	ds_read_b128 v[214:217], v83 offset:22080
	v_cvt_pk_bf16_f32 v96, v82, v84
	v_cvt_pk_bf16_f32 v97, v85, v88
	v_cvt_pk_bf16_f32 v98, v89, v92
	v_cvt_pk_bf16_f32 v99, v93, v94
	s_nop 1
	s_waitcnt lgkmcnt(5)
	v_mfma_f32_32x32x16_bf16 v[64:79], v[218:221], v[96:99], v[64:79]
	ds_read_b128 v[218:221], v83 offset:26688
	s_waitcnt lgkmcnt(5)
	v_mfma_f32_32x32x16_bf16 v[48:63], v[226:229], v[96:99], v[48:63]
	ds_read_b128 v[226:229], v83 offset:31296
	s_waitcnt lgkmcnt(5)
	v_mfma_f32_32x32x16_bf16 v[32:47], v[198:201], v[96:99], v[32:47]
	ds_read_b128 v[198:201], v83 offset:17504
	s_waitcnt lgkmcnt(5)
	v_mfma_f32_32x32x16_bf16 v[16:31], v[202:205], v[96:99], v[16:31]
	ds_read_b128 v[202:205], v83 offset:22112
	v_cvt_pk_bf16_f32 v84, v10, v11
	v_cvt_pk_bf16_f32 v85, v12, v13
	v_cvt_pk_bf16_f32 v86, v14, v15
	v_cvt_pk_bf16_f32 v87, v80, v81
	s_nop 1
	s_waitcnt lgkmcnt(5)
	v_mfma_f32_32x32x16_bf16 v[64:79], v[210:213], v[84:87], v[64:79]
	ds_read_b128 v[210:213], v83 offset:26720
	s_waitcnt lgkmcnt(5)
	v_mfma_f32_32x32x16_bf16 v[48:63], v[214:217], v[84:87], v[48:63]
	ds_read_b128 v[214:217], v83 offset:31328
	s_waitcnt lgkmcnt(5)
	v_mfma_f32_32x32x16_bf16 v[32:47], v[218:221], v[84:87], v[32:47]
	s_waitcnt lgkmcnt(4)
	v_mfma_f32_32x32x16_bf16 v[16:31], v[226:229], v[84:87], v[16:31]
	v_cvt_pk_bf16_f32 v10, v0, v3
	v_cvt_pk_bf16_f32 v11, v4, v5
	v_cvt_pk_bf16_f32 v12, v6, v7
	v_cvt_pk_bf16_f32 v13, v8, v9
	s_nop 1
	s_waitcnt lgkmcnt(3)
	v_mfma_f32_32x32x16_bf16 v[64:79], v[198:201], v[10:13], v[64:79]
	s_waitcnt lgkmcnt(2)
	v_mfma_f32_32x32x16_bf16 v[48:63], v[202:205], v[10:13], v[48:63]
	s_waitcnt lgkmcnt(1)
	v_mfma_f32_32x32x16_bf16 v[32:47], v[210:213], v[10:13], v[32:47]
	s_waitcnt lgkmcnt(0)
	v_mfma_f32_32x32x16_bf16 v[16:31], v[214:217], v[10:13], v[16:31]

; #define MFMA32(a, b, c) __builtin_amdgcn_mfma_f32_32x32x16_bf16((a), (b), (c), 0, 0, 0)
; DI f32x16 zero16() { f32x16 z; for (int i = 0; i < 16; ++i) z[i] = 0.f; return z; }
; template <int DQK, int MODE>
; DI void attn_core(const u16* __restrict__ Qg, int ldq, const u16* __restrict__ Kg, int ldk, const u16* __restrict__ Vtg,
;                   const u64* __restrict__ maskg, int q0, float scale, char* smem, int* sflags, f32x16 (&o)[4], float& l_run) {
;     ...
;   for (int it = 0; it < ntiles; ++it, tau += step) {
;     __syncthreads();
;     if (MODE == 2 && it > 0) {
;       if (!(sflags[0] | sflags[1] | sflags[2] | sflags[3] | sflags[4] | sflags[5] | sflags[6] | sflags[7])) break;
;     }
;     if (MODE == 2) gload(tau);
; #pragma unroll
;     for (int i = 0; i < NVK; ++i) {
;       const int v = tid + NT * i, row = v / VPR, c = v % VPR;
;       *(u32x4*)(Ks + row * KSTR + c * 8) = rk[i];
;     }
; #pragma unroll
;     for (int i = 0; i < 2; ++i) {
;       const int v = tid + NT * i, row = v >> 3, c = v & 7;
;       *(u32x4*)(Vs + row * 72 + c * 8) = rv[i];
;     }
;     __syncthreads();
;     if (MODE != 2 && it + 1 < ntiles) gload(tau + step);
;     if (tau * 64 > q0 + 32 * wid + 31) {
;       if (MODE == 2 && lane == 0) sflags[wid] = 1;
;       continue;
;     }
;     u64 mbits = 0;
;     if (MODE == 1) mbits = maskg[(long)qrow * 64 + tau] >> (8 * hh);
;     f32x16 s[2];
;     s[0] = zero16(); s[1] = zero16();
; #pragma unroll
;     for (int kt = 0; kt < 2; ++kt)
; #pragma unroll
;       for (int ks = 0; ks < NKS; ++ks) {
;         const bf16x8 kf = *(const bf16x8*)(Ks + (32 * kt + krow) * KSTR + ks * 16 + hh * 8);
;         s[kt] = MFMA32(kf, qf[ks], s[kt]);
;       }
;     const int kbase = tau * 64 + 8 * hh;
;     if (MODE == 0 || MODE == 1) {
;       const bool need_mask = (MODE == 1) || (tau * 64 + 63 > q0 + 32 * wid);
;       float mx = -1e30f;
;       if (need_mask) {
; #pragma unroll
;         for (int kt = 0; kt < 2; ++kt)
; #pragma unroll
;           for (int i = 0; i < 16; ++i) {
;             bool valid;
;             if (MODE == 1) valid = (mbits >> (32 * kt + 16 * (i >> 3) + (i & 7))) & 1ull;
;             else valid = (kbase + 32 * kt + 16 * (i >> 3) + (i & 7)) <= qrow;
;             s[kt][i] = valid ? s[kt][i] : -1e30f;
;           }
.LBB0_156:
	v_add_u32_e32 v0, s0, v176
	v_mad_i64_i32 v[2:3], s[4:5], v0, s75, v[168:169]
	v_add_u32_e32 v0, s0, v177
	v_mad_i64_i32 v[4:5], s[4:5], v0, s75, v[170:171]
	s_ashr_i32 s1, s0, 31
	s_lshl_b64 s[4:5], s[0:1], 1
	s_barrier
	s_waitcnt vmcnt(0)
	ds_write_b128 v180, v[156:159]
	ds_write_b128 v181, v[152:155]
	ds_write_b128 v182, v[148:151] offset:17408
	ds_write_b128 v183, v[144:147] offset:17408
	s_waitcnt lgkmcnt(0)
	s_barrier
	global_load_dwordx4 v[156:159], v[2:3], off
	global_load_dwordx4 v[152:155], v[4:5], off
	v_lshl_add_u64 v[2:3], v[162:163], 0, s[4:5]
	v_lshl_add_u64 v[4:5], v[166:167], 0, s[4:5]
	global_load_dwordx4 v[148:151], v[2:3], off
	global_load_dwordx4 v[144:147], v[4:5], off
	s_sub_i32 s1, s0, 64
	v_cmp_le_i32_e32 vcc, s1, v179
	s_and_saveexec_b64 s[4:5], vcc
	s_cbranch_execz .LBB0_155
	v_add_u32_e32 v0, v174, v178
	global_load_dwordx2 v[10:11], v[172:173], off
	ds_read_b128 v[12:15], v0
	ds_read_b128 v[202:205], v0 offset:32
	ds_read_b128 v[210:213], v0 offset:64
	ds_read_b128 v[214:217], v0 offset:96
	ds_read_b128 v[218:221], v0 offset:128
	ds_read_b128 v[226:229], v0 offset:160
	s_waitcnt lgkmcnt(5)
	v_mfma_f32_32x32x16_bf16 v[96:111], v[12:15], v[140:143], 0
	ds_read_b128 v[12:15], v0 offset:192
	s_waitcnt lgkmcnt(5)
	v_mfma_f32_32x32x16_bf16 v[96:111], v[202:205], v[136:139], v[96:111]
	ds_read_b128 v[202:205], v0 offset:224
	s_waitcnt vmcnt(0)
	v_lshrrev_b64 v[8:9], v160, v[10:11]
	s_waitcnt lgkmcnt(5)
	v_mfma_f32_32x32x16_bf16 v[96:111], v[210:213], v[132:135], v[96:111]
	ds_read_b128 v[210:213], v0 offset:8704
	s_waitcnt lgkmcnt(5)
	v_mfma_f32_32x32x16_bf16 v[96:111], v[214:217], v[128:131], v[96:111]
	ds_read_b128 v[214:217], v0 offset:8736
	s_waitcnt lgkmcnt(5)
	v_mfma_f32_32x32x16_bf16 v[96:111], v[218:221], v[124:127], v[96:111]
	ds_read_b128 v[218:221], v0 offset:8768
	s_waitcnt lgkmcnt(5)
	v_mfma_f32_32x32x16_bf16 v[96:111], v[226:229], v[120:123], v[96:111]
	ds_read_b128 v[226:229], v0 offset:8800
	s_waitcnt lgkmcnt(5)
	v_mfma_f32_32x32x16_bf16 v[96:111], v[12:15], v[116:119], v[96:111]
	ds_read_b128 v[12:15], v0 offset:8832
	s_waitcnt lgkmcnt(5)
	v_mfma_f32_32x32x16_bf16 v[96:111], v[202:205], v[112:115], v[96:111]
	ds_read_b128 v[202:205], v0 offset:8864
	s_waitcnt lgkmcnt(5)
	v_mfma_f32_32x32x16_bf16 v[80:95], v[210:213], v[140:143], 0
	ds_read_b128 v[210:213], v0 offset:8896
	s_waitcnt lgkmcnt(5)
	v_mfma_f32_32x32x16_bf16 v[80:95], v[214:217], v[136:139], v[80:95]
	ds_read_b128 v[214:217], v0 offset:8928
	s_waitcnt lgkmcnt(5)
	v_mfma_f32_32x32x16_bf16 v[80:95], v[218:221], v[132:135], v[80:95]
	s_waitcnt lgkmcnt(4)
	v_mfma_f32_32x32x16_bf16 v[80:95], v[226:229], v[128:131], v[80:95]
	s_waitcnt lgkmcnt(3)
	v_mfma_f32_32x32x16_bf16 v[80:95], v[12:15], v[124:127], v[80:95]
	s_waitcnt lgkmcnt(2)
	v_mfma_f32_32x32x16_bf16 v[80:95], v[202:205], v[120:123], v[80:95]
	s_waitcnt lgkmcnt(1)
	v_mfma_f32_32x32x16_bf16 v[80:95], v[210:213], v[116:119], v[80:95]
	v_lshrrev_b32_e32 v0, v160, v10
	v_and_b32_e32 v0, 1, v0
	v_cmp_eq_u32_e32 vcc, 1, v0
	v_and_b32_e32 v0, 2, v8
	s_nop 0
	v_cndmask_b32_e32 v200, v225, v96, vcc
	v_cmp_ne_u32_e32 vcc, 0, v0
	v_and_b32_e32 v0, 4, v8
	s_waitcnt lgkmcnt(0)
	v_mfma_f32_32x32x16_bf16 v[80:95], v[214:217], v[112:115], v[80:95]
	v_cndmask_b32_e32 v187, v225, v97, vcc
	v_cmp_ne_u32_e32 vcc, 0, v0
	v_and_b32_e32 v0, 8, v8
	v_mbcnt_hi_u32_b32 v2, -1, v223
	v_cndmask_b32_e32 v199, v225, v98, vcc
	v_cmp_ne_u32_e32 vcc, 0, v0
	v_and_b32_e32 v0, 16, v8
	s_nop 0
	v_cndmask_b32_e32 v198, v225, v99, vcc
	v_cmp_ne_u32_e32 vcc, 0, v0
	v_and_b32_e32 v0, 32, v8
	s_nop 0
	v_cndmask_b32_e32 v201, v225, v100, vcc
	v_cmp_ne_u32_e32 vcc, 0, v0
	v_and_b32_e32 v0, 64, v8
	s_nop 0
	v_cndmask_b32_e32 v96, v225, v101, vcc
	v_cmp_ne_u32_e32 vcc, 0, v0
	v_and_b32_e32 v0, 0x80, v8
	s_nop 0
	v_cndmask_b32_e32 v186, v225, v102, vcc
	v_cmp_ne_u32_e32 vcc, 0, v0
	v_and_b32_e32 v0, 0x10000, v8
	s_nop 0
	v_cndmask_b32_e32 v97, v225, v103, vcc
	v_cmp_ne_u32_e32 vcc, 0, v0
	v_and_b32_e32 v0, 0x20000, v8
	s_nop 0
	v_cndmask_b32_e32 v185, v225, v104, vcc
	v_cmp_ne_u32_e32 vcc, 0, v0
	v_and_b32_e32 v0, 0x40000, v8
	s_nop 0
	v_cndmask_b32_e32 v105, v225, v105, vcc
	v_cmp_ne_u32_e32 vcc, 0, v0
	v_and_b32_e32 v0, 0x80000, v8
	s_nop 0
	v_cndmask_b32_e32 v104, v225, v106, vcc
	v_cmp_ne_u32_e32 vcc, 0, v0
	v_and_b32_e32 v0, 0x100000, v8
	s_nop 0
	v_cndmask_b32_e32 v103, v225, v107, vcc
	v_cmp_ne_u32_e32 vcc, 0, v0
	v_and_b32_e32 v0, 0x200000, v8
	s_nop 0
	v_cndmask_b32_e32 v102, v225, v108, vcc
	v_cmp_ne_u32_e32 vcc, 0, v0
	v_and_b32_e32 v0, 0x400000, v8
	s_nop 0
	v_cndmask_b32_e32 v10, v225, v109, vcc
	v_cmp_ne_u32_e32 vcc, 0, v0
	v_and_b32_e32 v0, 0x800000, v8
	s_nop 0
	v_cndmask_b32_e32 v100, v225, v110, vcc
	v_cmp_ne_u32_e32 vcc, 0, v0
	v_and_b32_e32 v0, 1, v9
	s_nop 0
	v_cndmask_b32_e32 v11, v225, v111, vcc
	v_cmp_eq_u32_e32 vcc, 1, v0
	v_and_b32_e32 v0, 2, v9
	s_nop 0
	v_cndmask_b32_e32 v101, v225, v80, vcc
	v_cmp_ne_u32_e32 vcc, 0, v0
	v_and_b32_e32 v0, 4, v9
	s_nop 0
	v_cndmask_b32_e32 v99, v225, v81, vcc
	v_cmp_ne_u32_e32 vcc, 0, v0
	v_and_b32_e32 v0, 8, v9
	s_nop 0
	v_cndmask_b32_e32 v12, v225, v82, vcc
	v_cmp_ne_u32_e32 vcc, 0, v0
	v_and_b32_e32 v0, 16, v9
	v_xor_b32_e32 v82, 32, v2
	v_cndmask_b32_e32 v13, v225, v83, vcc
	v_cmp_ne_u32_e32 vcc, 0, v0
	v_and_b32_e32 v0, 32, v9
	v_and_b32_e32 v83, 64, v2
	v_cndmask_b32_e32 v14, v225, v84, vcc
	v_cmp_ne_u32_e32 vcc, 0, v0
	v_and_b32_e32 v0, 64, v9
	v_add_u32_e32 v83, 64, v83
	v_cndmask_b32_e32 v15, v225, v85, vcc
	v_cmp_ne_u32_e32 vcc, 0, v0
	v_and_b32_e32 v0, 0x80, v9
	s_nop 0
	v_cndmask_b32_e32 v80, v225, v86, vcc
	v_cmp_ne_u32_e32 vcc, 0, v0
; template <int DQK, int MODE>
; DI void attn_core(const u16* __restrict__ Qg, int ldq, const u16* __restrict__ Kg, int ldk, const u16* __restrict__ Vtg,
;                   const u64* __restrict__ maskg, int q0, float scale, char* smem, int* sflags, f32x16 (&o)[4], float& l_run) {
;     ...
;     __syncthreads();
;     if (MODE == 2 && it > 0) {
;       if (!(sflags[0] | sflags[1] | sflags[2] | sflags[3] | sflags[4] | sflags[5] | sflags[6] | sflags[7])) break;
;     }
;     if (MODE == 2) gload(tau);
; #pragma unroll
;     for (int i = 0; i < NVK; ++i) {
;       const int v = tid + NT * i, row = v / VPR, c = v % VPR;
;       *(u32x4*)(Ks + row * KSTR + c * 8) = rk[i];
;     }
; #pragma unroll
;     for (int i = 0; i < 2; ++i) {
;       const int v = tid + NT * i, row = v >> 3, c = v & 7;
;       *(u32x4*)(Vs + row * 72 + c * 8) = rv[i];
;     }
;     __syncthreads();
;     if (MODE != 2 && it + 1 < ntiles) gload(tau + step);
;     if (tau * 64 > q0 + 32 * wid + 31) {
;       if (MODE == 2 && lane == 0) sflags[wid] = 1;
;       continue;
;     }
;     ...
;       if (need_mask) {
; #pragma unroll
;         for (int kt = 0; kt < 2; ++kt)
; #pragma unroll
;           for (int i = 0; i < 16; ++i) {
;             bool valid;
;             if (MODE == 1) valid = (mbits >> (32 * kt + 16 * (i >> 3) + (i & 7))) & 1ull;
;             else valid = (kbase + 32 * kt + 16 * (i >> 3) + (i & 7)) <= qrow;
;             s[kt][i] = valid ? s[kt][i] : -1e30f;
;           }
;       }
; #pragma unroll
;       for (int kt = 0; kt < 2; ++kt)
; #pragma unroll
;         for (int i = 0; i < 16; ++i) mx = fmaxf(mx, s[kt][i]);
;       mx = fmaxf(mx, __shfl_xor(mx, 32));
;       const float m_new = fmaxf(m_run, mx);
;       const float alpha = __builtin_amdgcn_exp2f((m_run - m_new) * sc);
;       m_run = m_new;
;       const float msc = -m_new * sc;
;       float ls = 0.f;
; #pragma unroll
;       for (int kt = 0; kt < 2; ++kt)
; #pragma unroll
;         for (int i = 0; i < 16; ++i) {
;           float pv = __builtin_amdgcn_exp2f(__builtin_fmaf(s[kt][i], sc, msc));
;           if (MODE == 1) pv = (s[kt][i] > -1e29f) ? pv : 0.f;
;           s[kt][i] = pv;
;           ls += pv;
;         }
;       if (__any(alpha != 1.0f)) {
;         l_run *= alpha;
; #pragma unroll
;         for (int t = 0; t < 4; ++t)
; #pragma unroll
;           for (int i = 0; i < 16; ++i) o[t][i] *= alpha;
;       }
	v_and_b32_e32 v0, 0x10000, v9
	s_nop 0
	v_cndmask_b32_e32 v81, v225, v87, vcc
	v_cmp_ne_u32_e32 vcc, 0, v0
	v_and_b32_e32 v0, 0x20000, v9
	s_nop 0
	v_cndmask_b32_e32 v98, v225, v88, vcc
	v_cmp_ne_u32_e32 vcc, 0, v0
	v_and_b32_e32 v0, 0x40000, v9
	s_nop 0
	v_cndmask_b32_e32 v3, v225, v89, vcc
	v_cmp_ne_u32_e32 vcc, 0, v0
	v_and_b32_e32 v0, 0x80000, v9
	s_nop 0
	v_cndmask_b32_e32 v4, v225, v90, vcc
	v_cmp_ne_u32_e32 vcc, 0, v0
	v_and_b32_e32 v0, 0x100000, v9
	s_nop 0
	v_cndmask_b32_e32 v5, v225, v91, vcc
	v_cmp_ne_u32_e32 vcc, 0, v0
	v_and_b32_e32 v0, 0x200000, v9
	s_nop 0
	v_cndmask_b32_e32 v6, v225, v92, vcc
	v_cmp_ne_u32_e32 vcc, 0, v0
	v_and_b32_e32 v0, 0x400000, v9
	s_nop 0
	v_cndmask_b32_e32 v7, v225, v93, vcc
	v_cmp_ne_u32_e32 vcc, 0, v0
	v_and_b32_e32 v0, 0x800000, v9
	s_nop 0
	v_cndmask_b32_e32 v8, v225, v94, vcc
	v_cmp_ne_u32_e32 vcc, 0, v0
	v_max3_f32 v0, v200, s58, v187
	v_max3_f32 v0, v0, v199, v198
	v_max3_f32 v0, v0, v201, v96
	v_max3_f32 v0, v0, v186, v97
	v_max3_f32 v0, v0, v185, v105
	v_max3_f32 v0, v0, v104, v103
	v_max3_f32 v0, v0, v102, v10
	v_max3_f32 v0, v0, v100, v11
	v_max3_f32 v0, v0, v101, v99
	v_max3_f32 v0, v0, v12, v13
	v_max3_f32 v0, v0, v14, v15
	v_max3_f32 v0, v0, v80, v81
	v_max3_f32 v0, v0, v98, v3
	v_cndmask_b32_e32 v9, v225, v95, vcc
	v_max3_f32 v0, v0, v4, v5
	v_cmp_lt_i32_e32 vcc, v82, v83
	v_max3_f32 v0, v0, v6, v7
	v_max3_f32 v0, v0, v8, v9
	v_cndmask_b32_e32 v2, v2, v82, vcc
	v_lshlrev_b32_e32 v2, 2, v2
	ds_bpermute_b32 v2, v2, v0
	s_waitcnt lgkmcnt(0)
	v_max3_f32 v2, v184, v0, v2
	v_sub_f32_e32 v0, v184, v2
	v_mul_f32_e32 v0, 0x3e0293ee, v0
	v_exp_f32_e32 v0, v0
	s_nop 0
	v_cmp_neq_f32_e32 vcc, 1.0, v0
	s_cbranch_vccz .LBB0_154
	v_mul_f32_e32 v161, v161, v0
	v_pk_mul_f32 v[78:79], v[0:1], v[78:79] op_sel_hi:[0,1]
	v_pk_mul_f32 v[76:77], v[0:1], v[76:77] op_sel_hi:[0,1]
	v_pk_mul_f32 v[74:75], v[0:1], v[74:75] op_sel_hi:[0,1]
	v_pk_mul_f32 v[72:73], v[0:1], v[72:73] op_sel_hi:[0,1]
	v_pk_mul_f32 v[70:71], v[0:1], v[70:71] op_sel_hi:[0,1]
	v_pk_mul_f32 v[68:69], v[0:1], v[68:69] op_sel_hi:[0,1]
	v_pk_mul_f32 v[66:67], v[0:1], v[66:67] op_sel_hi:[0,1]
	v_pk_mul_f32 v[64:65], v[0:1], v[64:65] op_sel_hi:[0,1]
	v_pk_mul_f32 v[62:63], v[0:1], v[62:63] op_sel_hi:[0,1]
	v_pk_mul_f32 v[60:61], v[0:1], v[60:61] op_sel_hi:[0,1]
	v_pk_mul_f32 v[58:59], v[0:1], v[58:59] op_sel_hi:[0,1]
	v_pk_mul_f32 v[56:57], v[0:1], v[56:57] op_sel_hi:[0,1]
	v_pk_mul_f32 v[54:55], v[0:1], v[54:55] op_sel_hi:[0,1]
	v_pk_mul_f32 v[52:53], v[0:1], v[52:53] op_sel_hi:[0,1]
	v_pk_mul_f32 v[50:51], v[0:1], v[50:51] op_sel_hi:[0,1]
	v_pk_mul_f32 v[48:49], v[0:1], v[48:49] op_sel_hi:[0,1]
	v_pk_mul_f32 v[46:47], v[0:1], v[46:47] op_sel_hi:[0,1]
	v_pk_mul_f32 v[44:45], v[0:1], v[44:45] op_sel_hi:[0,1]
	v_pk_mul_f32 v[42:43], v[0:1], v[42:43] op_sel_hi:[0,1]
	v_pk_mul_f32 v[40:41], v[0:1], v[40:41] op_sel_hi:[0,1]
	v_pk_mul_f32 v[38:39], v[0:1], v[38:39] op_sel_hi:[0,1]
	v_pk_mul_f32 v[36:37], v[0:1], v[36:37] op_sel_hi:[0,1]
	v_pk_mul_f32 v[34:35], v[0:1], v[34:35] op_sel_hi:[0,1]
	v_pk_mul_f32 v[32:33], v[0:1], v[32:33] op_sel_hi:[0,1]
	v_pk_mul_f32 v[30:31], v[0:1], v[30:31] op_sel_hi:[0,1]
	v_pk_mul_f32 v[28:29], v[0:1], v[28:29] op_sel_hi:[0,1]
	v_pk_mul_f32 v[26:27], v[0:1], v[26:27] op_sel_hi:[0,1]
	v_pk_mul_f32 v[24:25], v[0:1], v[24:25] op_sel_hi:[0,1]
	v_pk_mul_f32 v[22:23], v[0:1], v[22:23] op_sel_hi:[0,1]
	v_pk_mul_f32 v[20:21], v[0:1], v[20:21] op_sel_hi:[0,1]
	v_pk_mul_f32 v[18:19], v[0:1], v[18:19] op_sel_hi:[0,1]
	v_pk_mul_f32 v[16:17], v[0:1], v[16:17] op_sel_hi:[0,1]
	s_branch .LBB0_154
.LBB0_159:
	s_lshl_b32 s0, s14, 6
	v_cmp_le_i32_e32 vcc, s0, v179
	s_barrier
	s_waitcnt vmcnt(3)
	ds_write_b128 v180, v[156:159]
	s_waitcnt vmcnt(2)
	ds_write_b128 v181, v[152:155]
	s_waitcnt vmcnt(1)
	ds_write_b128 v182, v[148:151] offset:17408
	s_waitcnt vmcnt(0)
	ds_write_b128 v183, v[144:147] offset:17408
	s_waitcnt lgkmcnt(0)
	s_barrier
	s_and_saveexec_b64 s[0:1], vcc
	s_xor_b64 s[0:1], exec, s[0:1]
	s_cbranch_execz .LBB0_164
	v_readlane_b32 s4, v249, 29
	v_readlane_b32 s5, v249, 30
	s_mov_b32 s15, s5
	s_add_i32 s14, s13, -2
	v_lshl_add_u64 v[2:3], s[14:15], 3, v[164:165]
	v_add_u32_e32 v0, v174, v178
	global_load_dwordx2 v[10:11], v[2:3], off offset:8
	ds_read_b128 v[12:15], v0
	ds_read_b128 v[144:147], v0 offset:32
	ds_read_b128 v[148:151], v0 offset:64
	ds_read_b128 v[152:155], v0 offset:96
	ds_read_b128 v[156:159], v0 offset:128
	ds_read_b128 v[162:165], v0 offset:160
	s_waitcnt lgkmcnt(5)
	v_mfma_f32_32x32x16_bf16 v[80:95], v[12:15], v[140:143], 0
	ds_read_b128 v[12:15], v0 offset:192
	v_writelane_b32 v249, s4, 29
	s_nop 1
	v_writelane_b32 v249, s5, 30
	s_waitcnt lgkmcnt(5)
	v_mfma_f32_32x32x16_bf16 v[80:95], v[144:147], v[136:139], v[80:95]
	ds_read_b128 v[144:147], v0 offset:224
	s_waitcnt lgkmcnt(5)
	v_mfma_f32_32x32x16_bf16 v[80:95], v[148:151], v[132:135], v[80:95]
	ds_read_b128 v[148:151], v0 offset:8704
	s_waitcnt lgkmcnt(5)
	v_mfma_f32_32x32x16_bf16 v[80:95], v[152:155], v[128:131], v[80:95]
	ds_read_b128 v[152:155], v0 offset:8736
	s_waitcnt lgkmcnt(5)
	v_mfma_f32_32x32x16_bf16 v[80:95], v[156:159], v[124:127], v[80:95]
	ds_read_b128 v[156:159], v0 offset:8768
	s_waitcnt lgkmcnt(5)
	v_mfma_f32_32x32x16_bf16 v[80:95], v[162:165], v[120:123], v[80:95]
	ds_read_b128 v[162:165], v0 offset:8800
	s_waitcnt lgkmcnt(5)
	v_mfma_f32_32x32x16_bf16 v[80:95], v[12:15], v[116:119], v[80:95]
	ds_read_b128 v[12:15], v0 offset:8832
	s_waitcnt lgkmcnt(5)
	v_mfma_f32_32x32x16_bf16 v[80:95], v[144:147], v[112:115], v[80:95]
	ds_read_b128 v[144:147], v0 offset:8864
	s_waitcnt lgkmcnt(5)
; #define MFMA32(a, b, c) __builtin_amdgcn_mfma_f32_32x32x16_bf16((a), (b), (c), 0, 0, 0)
; DI f32x16 zero16() { f32x16 z; for (int i = 0; i < 16; ++i) z[i] = 0.f; return z; }
; template <int DQK, int MODE>
; DI void attn_core(const u16* __restrict__ Qg, int ldq, const u16* __restrict__ Kg, int ldk, const u16* __restrict__ Vtg,
;                   const u64* __restrict__ maskg, int q0, float scale, char* smem, int* sflags, f32x16 (&o)[4], float& l_run) {
;     ...
;     f32x16 s[2];
;     s[0] = zero16(); s[1] = zero16();
; #pragma unroll
;     for (int kt = 0; kt < 2; ++kt)
; #pragma unroll
;       for (int ks = 0; ks < NKS; ++ks) {
;         const bf16x8 kf = *(const bf16x8*)(Ks + (32 * kt + krow) * KSTR + ks * 16 + hh * 8);
;         s[kt] = MFMA32(kf, qf[ks], s[kt]);
;       }
;     const int kbase = tau * 64 + 8 * hh;
;     if (MODE == 0 || MODE == 1) {
;       const bool need_mask = (MODE == 1) || (tau * 64 + 63 > q0 + 32 * wid);
;       float mx = -1e30f;
;       if (need_mask) {
; #pragma unroll
;         for (int kt = 0; kt < 2; ++kt)
; #pragma unroll
;           for (int i = 0; i < 16; ++i) {
;             bool valid;
;             if (MODE == 1) valid = (mbits >> (32 * kt + 16 * (i >> 3) + (i & 7))) & 1ull;
;             else valid = (kbase + 32 * kt + 16 * (i >> 3) + (i & 7)) <= qrow;
;             s[kt][i] = valid ? s[kt][i] : -1e30f;
;           }
;       }
; #pragma unroll
;       for (int kt = 0; kt < 2; ++kt)
; #pragma unroll
;         for (int i = 0; i < 16; ++i) mx = fmaxf(mx, s[kt][i]);
;       mx = fmaxf(mx, __shfl_xor(mx, 32));
;       const float m_new = fmaxf(m_run, mx);
;       const float alpha = __builtin_amdgcn_exp2f((m_run - m_new) * sc);
;       m_run = m_new;
;       const float msc = -m_new * sc;
;       float ls = 0.f;
; #pragma unroll
;       for (int kt = 0; kt < 2; ++kt)
; #pragma unroll
;         for (int i = 0; i < 16; ++i) {
;           float pv = __builtin_amdgcn_exp2f(__builtin_fmaf(s[kt][i], sc, msc));
;           if (MODE == 1) pv = (s[kt][i] > -1e29f) ? pv : 0.f;
;           s[kt][i] = pv;
;           ls += pv;
;         }
;       if (__any(alpha != 1.0f)) {
;         l_run *= alpha;
; #pragma unroll
;         for (int t = 0; t < 4; ++t)
; #pragma unroll
;           for (int i = 0; i < 16; ++i) o[t][i] *= alpha;
;       }
	v_mfma_f32_32x32x16_bf16 v[96:111], v[148:151], v[140:143], 0
	ds_read_b128 v[148:151], v0 offset:8896
	s_waitcnt lgkmcnt(5)
	v_mfma_f32_32x32x16_bf16 v[96:111], v[152:155], v[136:139], v[96:111]
	ds_read_b128 v[152:155], v0 offset:8928
	s_waitcnt lgkmcnt(5)
	v_mfma_f32_32x32x16_bf16 v[96:111], v[156:159], v[132:135], v[96:111]
	s_waitcnt lgkmcnt(4)
	v_mfma_f32_32x32x16_bf16 v[96:111], v[162:165], v[128:131], v[96:111]
	s_waitcnt lgkmcnt(3)
	v_mfma_f32_32x32x16_bf16 v[96:111], v[12:15], v[124:127], v[96:111]
	s_waitcnt lgkmcnt(2)
	v_mfma_f32_32x32x16_bf16 v[96:111], v[144:147], v[120:123], v[96:111]
	s_waitcnt lgkmcnt(1)
	v_mfma_f32_32x32x16_bf16 v[96:111], v[148:151], v[116:119], v[96:111]
	s_waitcnt vmcnt(0)
	v_lshrrev_b32_e32 v0, v160, v10
	v_and_b32_e32 v0, 1, v0
	v_cmp_eq_u32_e32 vcc, 1, v0
	s_nop 1
	v_cndmask_b32_e32 v121, v225, v80, vcc
	s_waitcnt lgkmcnt(0)
	v_mfma_f32_32x32x16_bf16 v[96:111], v[152:155], v[112:115], v[96:111]
	v_lshrrev_b64 v[2:3], v160, v[10:11]
	v_and_b32_e32 v0, 2, v2
	v_cmp_ne_u32_e32 vcc, 0, v0
	v_and_b32_e32 v0, 4, v2
	s_nop 0
	v_cndmask_b32_e32 v118, v225, v81, vcc
	v_cmp_ne_u32_e32 vcc, 0, v0
	v_and_b32_e32 v0, 8, v2
	s_nop 0
	v_cndmask_b32_e32 v120, v225, v82, vcc
	v_cmp_ne_u32_e32 vcc, 0, v0
	v_and_b32_e32 v0, 16, v2
	s_nop 0
	v_cndmask_b32_e32 v119, v225, v83, vcc
	v_cmp_ne_u32_e32 vcc, 0, v0
	v_and_b32_e32 v0, 32, v2
	s_nop 0
	v_cndmask_b32_e32 v122, v225, v84, vcc
	v_cmp_ne_u32_e32 vcc, 0, v0
	v_and_b32_e32 v0, 64, v2
	s_nop 0
	v_cndmask_b32_e32 v116, v225, v85, vcc
	v_cmp_ne_u32_e32 vcc, 0, v0
	v_and_b32_e32 v0, 0x80, v2
	s_nop 0
	v_cndmask_b32_e32 v117, v225, v86, vcc
	v_cmp_ne_u32_e32 vcc, 0, v0
	v_and_b32_e32 v0, 0x10000, v2
	s_nop 0
	v_cndmask_b32_e32 v115, v225, v87, vcc
	v_cmp_ne_u32_e32 vcc, 0, v0
	v_and_b32_e32 v0, 0x20000, v2
	s_nop 0
	v_cndmask_b32_e32 v85, v225, v88, vcc
	v_cmp_ne_u32_e32 vcc, 0, v0
	v_and_b32_e32 v0, 0x40000, v2
	s_nop 0
	v_cndmask_b32_e32 v87, v225, v89, vcc
	v_cmp_ne_u32_e32 vcc, 0, v0
	v_and_b32_e32 v0, 0x80000, v2
	s_nop 0
	v_cndmask_b32_e32 v88, v225, v90, vcc
	v_cmp_ne_u32_e32 vcc, 0, v0
	v_and_b32_e32 v0, 0x100000, v2
	s_nop 0
	v_cndmask_b32_e32 v91, v225, v91, vcc
	v_cmp_ne_u32_e32 vcc, 0, v0
	v_and_b32_e32 v0, 0x200000, v2
	s_nop 0
	v_cndmask_b32_e32 v92, v225, v92, vcc
	v_cmp_ne_u32_e32 vcc, 0, v0
	v_and_b32_e32 v0, 0x400000, v2
	s_nop 0
	v_cndmask_b32_e32 v13, v225, v93, vcc
	v_cmp_ne_u32_e32 vcc, 0, v0
	v_and_b32_e32 v0, 0x800000, v2
	v_mbcnt_hi_u32_b32 v2, -1, v223
	v_cndmask_b32_e32 v113, v225, v94, vcc
	v_cmp_ne_u32_e32 vcc, 0, v0
	v_and_b32_e32 v0, 1, v3
	v_and_b32_e32 v4, 64, v2
	v_cndmask_b32_e32 v14, v225, v95, vcc
	v_cmp_eq_u32_e32 vcc, 1, v0
	v_and_b32_e32 v0, 2, v3
	v_add_u32_e32 v4, 64, v4
	v_cndmask_b32_e32 v114, v225, v96, vcc
	v_cmp_ne_u32_e32 vcc, 0, v0
	v_and_b32_e32 v0, 4, v3
	s_nop 0
	v_cndmask_b32_e32 v112, v225, v97, vcc
	v_cmp_ne_u32_e32 vcc, 0, v0
	v_and_b32_e32 v0, 8, v3
	s_nop 0
	v_cndmask_b32_e32 v15, v225, v98, vcc
	v_cmp_ne_u32_e32 vcc, 0, v0
	v_and_b32_e32 v0, 16, v3
	s_nop 0
	v_cndmask_b32_e32 v80, v225, v99, vcc
	v_cmp_ne_u32_e32 vcc, 0, v0
	v_and_b32_e32 v0, 32, v3
	s_nop 0
	v_cndmask_b32_e32 v81, v225, v100, vcc
	v_cmp_ne_u32_e32 vcc, 0, v0
	v_and_b32_e32 v0, 64, v3
	s_nop 0
	v_cndmask_b32_e32 v82, v225, v101, vcc
	v_cmp_ne_u32_e32 vcc, 0, v0
	v_and_b32_e32 v0, 0x80, v3
	s_nop 0
	v_cndmask_b32_e32 v83, v225, v102, vcc
	v_cmp_ne_u32_e32 vcc, 0, v0
	v_and_b32_e32 v0, 0x10000, v3
	s_nop 0
	v_cndmask_b32_e32 v84, v225, v103, vcc
	v_cmp_ne_u32_e32 vcc, 0, v0
	v_and_b32_e32 v0, 0x20000, v3
	s_nop 0
	v_cndmask_b32_e32 v5, v225, v104, vcc
	v_cmp_ne_u32_e32 vcc, 0, v0
	v_and_b32_e32 v0, 0x40000, v3
	s_nop 0
	v_cndmask_b32_e32 v6, v225, v105, vcc
	v_cmp_ne_u32_e32 vcc, 0, v0
	v_and_b32_e32 v0, 0x80000, v3
	s_nop 0
	v_cndmask_b32_e32 v7, v225, v106, vcc
	v_cmp_ne_u32_e32 vcc, 0, v0
	v_and_b32_e32 v0, 0x100000, v3
	s_nop 0
	v_cndmask_b32_e32 v8, v225, v107, vcc
	v_cmp_ne_u32_e32 vcc, 0, v0
	v_and_b32_e32 v0, 0x200000, v3
	s_nop 0
	v_cndmask_b32_e32 v9, v225, v108, vcc
	v_cmp_ne_u32_e32 vcc, 0, v0
	v_and_b32_e32 v0, 0x400000, v3
	s_nop 0
	v_cndmask_b32_e32 v10, v225, v109, vcc
	v_cmp_ne_u32_e32 vcc, 0, v0
	v_and_b32_e32 v0, 0x800000, v3
	v_xor_b32_e32 v3, 32, v2
	v_cndmask_b32_e32 v11, v225, v110, vcc
	v_cmp_ne_u32_e32 vcc, 0, v0
	v_max3_f32 v0, v121, s58, v118
	v_max3_f32 v0, v0, v120, v119
	v_max3_f32 v0, v0, v122, v116
	v_max3_f32 v0, v0, v117, v115
	v_max3_f32 v0, v0, v85, v87
	v_max3_f32 v0, v0, v88, v91
	v_max3_f32 v0, v0, v92, v13
	v_max3_f32 v0, v0, v113, v14
	v_max3_f32 v0, v0, v114, v112
	v_max3_f32 v0, v0, v15, v80
	v_max3_f32 v0, v0, v81, v82
	v_max3_f32 v0, v0, v83, v84
	v_max3_f32 v0, v0, v5, v6
	v_cndmask_b32_e32 v12, v225, v111, vcc
	v_max3_f32 v0, v0, v7, v8
	v_cmp_lt_i32_e32 vcc, v3, v4
	v_max3_f32 v0, v0, v9, v10
	v_max3_f32 v0, v0, v11, v12
	v_cndmask_b32_e32 v86, v2, v3, vcc
	v_lshlrev_b32_e32 v86, 2, v86
	ds_bpermute_b32 v86, v86, v0
	s_waitcnt lgkmcnt(0)
	v_max3_f32 v86, v184, v0, v86
	v_sub_f32_e32 v0, v184, v86
	v_mul_f32_e32 v0, 0x3e0293ee, v0
	v_exp_f32_e32 v0, v0
	s_nop 0
	v_cmp_neq_f32_e32 vcc, 1.0, v0
	s_cbranch_vccz .LBB0_162
	v_mul_f32_e32 v101, v161, v0
	v_pk_mul_f32 v[78:79], v[0:1], v[78:79] op_sel_hi:[0,1]
	v_pk_mul_f32 v[76:77], v[0:1], v[76:77] op_sel_hi:[0,1]
	v_pk_mul_f32 v[74:75], v[0:1], v[74:75] op_sel_hi:[0,1]
	v_pk_mul_f32 v[72:73], v[0:1], v[72:73] op_sel_hi:[0,1]
	v_pk_mul_f32 v[70:71], v[0:1], v[70:71] op_sel_hi:[0,1]
	v_pk_mul_f32 v[68:69], v[0:1], v[68:69] op_sel_hi:[0,1]
	v_pk_mul_f32 v[66:67], v[0:1], v[66:67] op_sel_hi:[0,1]
	v_pk_mul_f32 v[64:65], v[0:1], v[64:65] op_sel_hi:[0,1]
	v_pk_mul_f32 v[62:63], v[0:1], v[62:63] op_sel_hi:[0,1]
	v_pk_mul_f32 v[60:61], v[0:1], v[60:61] op_sel_hi:[0,1]
	v_pk_mul_f32 v[58:59], v[0:1], v[58:59] op_sel_hi:[0,1]
	v_pk_mul_f32 v[56:57], v[0:1], v[56:57] op_sel_hi:[0,1]
	v_pk_mul_f32 v[54:55], v[0:1], v[54:55] op_sel_hi:[0,1]
	v_pk_mul_f32 v[52:53], v[0:1], v[52:53] op_sel_hi:[0,1]
	v_pk_mul_f32 v[50:51], v[0:1], v[50:51] op_sel_hi:[0,1]
	v_pk_mul_f32 v[48:49], v[0:1], v[48:49] op_sel_hi:[0,1]
	v_pk_mul_f32 v[46:47], v[0:1], v[46:47] op_sel_hi:[0,1]
	v_pk_mul_f32 v[44:45], v[0:1], v[44:45] op_sel_hi:[0,1]
	v_pk_mul_f32 v[42:43], v[0:1], v[42:43] op_sel_hi:[0,1]
	v_pk_mul_f32 v[40:41], v[0:1], v[40:41] op_sel_hi:[0,1]
	v_pk_mul_f32 v[38:39], v[0:1], v[38:39] op_sel_hi:[0,1]
	v_pk_mul_f32 v[36:37], v[0:1], v[36:37] op_sel_hi:[0,1]
	v_pk_mul_f32 v[34:35], v[0:1], v[34:35] op_sel_hi:[0,1]
	v_pk_mul_f32 v[32:33], v[0:1], v[32:33] op_sel_hi:[0,1]
	v_pk_mul_f32 v[30:31], v[0:1], v[30:31] op_sel_hi:[0,1]
	v_pk_mul_f32 v[28:29], v[0:1], v[28:29] op_sel_hi:[0,1]
	v_pk_mul_f32 v[26:27], v[0:1], v[26:27] op_sel_hi:[0,1]
	v_pk_mul_f32 v[24:25], v[0:1], v[24:25] op_sel_hi:[0,1]
	v_pk_mul_f32 v[22:23], v[0:1], v[22:23] op_sel_hi:[0,1]
	v_pk_mul_f32 v[20:21], v[0:1], v[20:21] op_sel_hi:[0,1]
	v_pk_mul_f32 v[18:19], v[0:1], v[18:19] op_sel_hi:[0,1]
	v_pk_mul_f32 v[16:17], v[0:1], v[16:17] op_sel_hi:[0,1]
	s_branch .LBB0_163

; #define MFMA32(a, b, c) __builtin_amdgcn_mfma_f32_32x32x16_bf16((a), (b), (c), 0, 0, 0)
; template <int DQK, int MODE>
; DI void attn_core(const u16* __restrict__ Qg, int ldq, const u16* __restrict__ Kg, int ldk, const u16* __restrict__ Vtg,
;                   const u64* __restrict__ maskg, int q0, float scale, char* smem, int* sflags, f32x16 (&o)[4], float& l_run) {
;     ...
;       const float m_new = fmaxf(m_run, mx);
;       const float alpha = __builtin_amdgcn_exp2f((m_run - m_new) * sc);
;       m_run = m_new;
;       const float msc = -m_new * sc;
;       float ls = 0.f;
; #pragma unroll
;       for (int kt = 0; kt < 2; ++kt)
; #pragma unroll
;         for (int i = 0; i < 16; ++i) {
;           float pv = __builtin_amdgcn_exp2f(__builtin_fmaf(s[kt][i], sc, msc));
;           if (MODE == 1) pv = (s[kt][i] > -1e29f) ? pv : 0.f;
;           s[kt][i] = pv;
;           ls += pv;
;         }
;       if (__any(alpha != 1.0f)) {
;         l_run *= alpha;
; #pragma unroll
;         for (int t = 0; t < 4; ++t)
; #pragma unroll
;           for (int i = 0; i < 16; ++i) o[t][i] *= alpha;
;       }
;       l_run += ls;
;     ...
; #pragma unroll
;     for (int kt = 0; kt < 2; ++kt)
; #pragma unroll
;       for (int sb = 0; sb < 2; ++sb) {
;         const bf16x8 pf = pack8(s[kt][8 * sb + 0], s[kt][8 * sb + 1], s[kt][8 * sb + 2], s[kt][8 * sb + 3],
;                                 s[kt][8 * sb + 4], s[kt][8 * sb + 5], s[kt][8 * sb + 6], s[kt][8 * sb + 7]);
; #pragma unroll
;         for (int t = 0; t < 4; ++t) {
;           const bf16x8 vf = *(const bf16x8*)(Vs + (32 * t + l31) * 72 + 32 * kt + 16 * sb + hh * 8);
;           o[t] = MFMA32(vf, pf, o[t]);
;         }
;       }
.LBB0_163:
	v_mul_f32_e32 v0, 0xbe0293ee, v86
	v_fmamk_f32 v86, v121, 0x3e0293ee, v0
	v_exp_f32_e32 v86, v86
	v_fmamk_f32 v89, v118, 0x3e0293ee, v0
	v_exp_f32_e32 v89, v89
	v_cmp_lt_f32_e32 vcc, s18, v121
	v_fmamk_f32 v96, v116, 0x3e0293ee, v0
	v_exp_f32_e32 v96, v96
	v_cndmask_b32_e32 v86, 0, v86, vcc
	v_cmp_lt_f32_e32 vcc, s18, v118
	v_add_f32_e32 v90, 0, v86
	v_fmamk_f32 v97, v14, 0x3e0293ee, v0
	v_cndmask_b32_e32 v89, 0, v89, vcc
	v_add_f32_e32 v93, v89, v90
	v_fmamk_f32 v90, v120, 0x3e0293ee, v0
	v_exp_f32_e32 v90, v90
	v_cmp_lt_f32_e32 vcc, s18, v120
	v_exp_f32_e32 v97, v97
	v_fmamk_f32 v103, v15, 0x3e0293ee, v0
	v_cndmask_b32_e32 v90, 0, v90, vcc
	v_add_f32_e32 v94, v90, v93
	v_fmamk_f32 v93, v119, 0x3e0293ee, v0
	v_exp_f32_e32 v93, v93
	v_cmp_lt_f32_e32 vcc, s18, v119
	v_exp_f32_e32 v103, v103
	s_nop 0
	v_cndmask_b32_e32 v93, 0, v93, vcc
	v_add_f32_e32 v95, v93, v94
	v_fmamk_f32 v94, v122, 0x3e0293ee, v0
	v_exp_f32_e32 v94, v94
	v_cmp_lt_f32_e32 vcc, s18, v122
	s_nop 1
	v_cndmask_b32_e32 v94, 0, v94, vcc
	v_cmp_lt_f32_e32 vcc, s18, v116
	v_add_f32_e32 v95, v94, v95
	s_nop 0
	v_cndmask_b32_e32 v98, 0, v96, vcc
	v_fmamk_f32 v96, v117, 0x3e0293ee, v0
	v_exp_f32_e32 v96, v96
	v_cmp_lt_f32_e32 vcc, s18, v117
	v_add_f32_e32 v95, v98, v95
	s_nop 0
	v_cndmask_b32_e32 v99, 0, v96, vcc
	v_fmamk_f32 v96, v115, 0x3e0293ee, v0
	v_exp_f32_e32 v96, v96
	v_cmp_lt_f32_e32 vcc, s18, v115
	v_add_f32_e32 v95, v99, v95
	s_nop 0
	v_cndmask_b32_e32 v100, 0, v96, vcc
	v_fmamk_f32 v96, v85, 0x3e0293ee, v0
	v_exp_f32_e32 v96, v96
	v_cmp_lt_f32_e32 vcc, s18, v85
	v_add_f32_e32 v95, v100, v95
	s_nop 0
	v_cndmask_b32_e32 v85, 0, v96, vcc
	v_fmamk_f32 v96, v87, 0x3e0293ee, v0
	v_exp_f32_e32 v96, v96
	v_cmp_lt_f32_e32 vcc, s18, v87
	v_add_f32_e32 v95, v85, v95
	s_nop 0
	v_cndmask_b32_e32 v87, 0, v96, vcc
	v_fmamk_f32 v96, v88, 0x3e0293ee, v0
	v_exp_f32_e32 v96, v96
	v_cmp_lt_f32_e32 vcc, s18, v88
	v_add_f32_e32 v95, v87, v95
	s_nop 0
	v_cndmask_b32_e32 v88, 0, v96, vcc
	v_fmamk_f32 v96, v91, 0x3e0293ee, v0
	v_exp_f32_e32 v96, v96
	v_cmp_lt_f32_e32 vcc, s18, v91
	v_add_f32_e32 v95, v88, v95
	s_nop 0
	v_cndmask_b32_e32 v91, 0, v96, vcc
	v_fmamk_f32 v96, v92, 0x3e0293ee, v0
	v_exp_f32_e32 v96, v96
	v_cmp_lt_f32_e32 vcc, s18, v92
	v_add_f32_e32 v95, v91, v95
	s_nop 0
	v_cndmask_b32_e32 v92, 0, v96, vcc
	v_add_f32_e32 v96, v92, v95
	v_fmamk_f32 v95, v13, 0x3e0293ee, v0
	v_exp_f32_e32 v95, v95
	v_cmp_lt_f32_e32 vcc, s18, v13
	s_nop 1
	v_cndmask_b32_e32 v95, 0, v95, vcc
	v_add_f32_e32 v13, v95, v96
	v_fmamk_f32 v96, v113, 0x3e0293ee, v0
	v_exp_f32_e32 v96, v96
	v_cmp_lt_f32_e32 vcc, s18, v113
	s_nop 1
	v_cndmask_b32_e32 v96, 0, v96, vcc
	v_cmp_lt_f32_e32 vcc, s18, v14
	v_add_f32_e32 v13, v96, v13
	s_nop 0
	v_cndmask_b32_e32 v97, 0, v97, vcc
	v_add_f32_e32 v14, v97, v13
	v_fmamk_f32 v13, v114, 0x3e0293ee, v0
	v_exp_f32_e32 v13, v13
	v_cmp_lt_f32_e32 vcc, s18, v114
	s_nop 1
	v_cndmask_b32_e32 v13, 0, v13, vcc
	v_add_f32_e32 v102, v13, v14
	v_fmamk_f32 v14, v112, 0x3e0293ee, v0
	v_exp_f32_e32 v14, v14
	v_cmp_lt_f32_e32 vcc, s18, v112
	s_nop 1
	v_cndmask_b32_e32 v14, 0, v14, vcc
	v_cmp_lt_f32_e32 vcc, s18, v15
	v_add_f32_e32 v102, v14, v102
	s_nop 0
	v_cndmask_b32_e32 v15, 0, v103, vcc
	v_fmamk_f32 v103, v80, 0x3e0293ee, v0
	v_exp_f32_e32 v103, v103
	v_cmp_lt_f32_e32 vcc, s18, v80
	v_add_f32_e32 v102, v15, v102
	s_nop 0
	v_cndmask_b32_e32 v80, 0, v103, vcc
	v_fmamk_f32 v103, v81, 0x3e0293ee, v0
	v_exp_f32_e32 v103, v103
	v_cmp_lt_f32_e32 vcc, s18, v81
	v_add_f32_e32 v102, v80, v102
	s_nop 0
	v_cndmask_b32_e32 v81, 0, v103, vcc
	v_fmamk_f32 v103, v82, 0x3e0293ee, v0
	v_exp_f32_e32 v103, v103
	v_cmp_lt_f32_e32 vcc, s18, v82
	v_add_f32_e32 v102, v81, v102
	s_nop 0
	v_cndmask_b32_e32 v82, 0, v103, vcc
	v_fmamk_f32 v103, v83, 0x3e0293ee, v0
	v_exp_f32_e32 v103, v103
	v_cmp_lt_f32_e32 vcc, s18, v83
	v_add_f32_e32 v102, v82, v102
	s_nop 0
	v_cndmask_b32_e32 v83, 0, v103, vcc
	v_fmamk_f32 v103, v84, 0x3e0293ee, v0
	v_exp_f32_e32 v103, v103
	v_cmp_lt_f32_e32 vcc, s18, v84
	v_add_f32_e32 v102, v83, v102
	s_nop 0
	v_cndmask_b32_e32 v84, 0, v103, vcc
	v_fmamk_f32 v103, v5, 0x3e0293ee, v0
	v_exp_f32_e32 v103, v103
	v_cmp_lt_f32_e32 vcc, s18, v5
	v_add_f32_e32 v102, v84, v102
	s_nop 0
	v_cndmask_b32_e32 v5, 0, v103, vcc
	v_fmamk_f32 v103, v6, 0x3e0293ee, v0
	v_exp_f32_e32 v103, v103
	v_cmp_lt_f32_e32 vcc, s18, v6
	v_add_f32_e32 v102, v5, v102
	s_nop 0
	v_cndmask_b32_e32 v6, 0, v103, vcc
	v_fmamk_f32 v103, v7, 0x3e0293ee, v0
	v_exp_f32_e32 v103, v103
	v_cmp_lt_f32_e32 vcc, s18, v7
	v_add_f32_e32 v102, v6, v102
	s_nop 0
	v_cndmask_b32_e32 v7, 0, v103, vcc
	v_fmamk_f32 v103, v8, 0x3e0293ee, v0
	v_exp_f32_e32 v103, v103
	v_cmp_lt_f32_e32 vcc, s18, v8
	v_add_f32_e32 v102, v7, v102
	s_nop 0
	v_cndmask_b32_e32 v8, 0, v103, vcc
	v_fmamk_f32 v103, v9, 0x3e0293ee, v0
	v_exp_f32_e32 v103, v103
	v_cmp_lt_f32_e32 vcc, s18, v9
	v_add_f32_e32 v102, v8, v102
	s_nop 0
	v_cndmask_b32_e32 v9, 0, v103, vcc
	v_fmamk_f32 v103, v10, 0x3e0293ee, v0
	v_exp_f32_e32 v103, v103
	v_cmp_lt_f32_e32 vcc, s18, v10
	v_add_f32_e32 v102, v9, v102
	s_nop 0
	v_cndmask_b32_e32 v10, 0, v103, vcc
	v_fmamk_f32 v103, v11, 0x3e0293ee, v0
	v_exp_f32_e32 v103, v103
	v_fmac_f32_e32 v0, 0x3e0293ee, v12
	v_exp_f32_e32 v0, v0
	v_cmp_lt_f32_e32 vcc, s18, v11
	v_add_f32_e32 v102, v10, v102
	s_nop 0
	v_cndmask_b32_e32 v11, 0, v103, vcc
	v_cmp_lt_f32_e32 vcc, s18, v12
	v_add_f32_e32 v102, v11, v102
	s_nop 0
	v_cndmask_b32_e32 v12, 0, v0, vcc
	v_add_f32_e32 v0, v12, v102
	v_cvt_pk_bf16_f32 v102, v86, v89
	v_cvt_pk_bf16_f32 v103, v90, v93
	v_cvt_pk_bf16_f32 v104, v94, v98
	v_cvt_pk_bf16_f32 v105, v99, v100
	s_nop 1
	v_add_u32_e32 v86, v174, v175
	v_add_f32_e32 v0, v0, v101
	ds_read_b128 v[110:113], v86 offset:17408
	ds_read_b128 v[114:117], v86 offset:22016
	ds_read_b128 v[118:121], v86 offset:26624
	ds_read_b128 v[122:125], v86 offset:31232
	ds_read_b128 v[126:129], v86 offset:17440
	ds_read_b128 v[130:133], v86 offset:22048
	s_waitcnt lgkmcnt(5)
; #define MFMA32(a, b, c) __builtin_amdgcn_mfma_f32_32x32x16_bf16((a), (b), (c), 0, 0, 0)
; template <int DQK, int MODE>
; DI void attn_core(const u16* __restrict__ Qg, int ldq, const u16* __restrict__ Kg, int ldk, const u16* __restrict__ Vtg,
;                   const u64* __restrict__ maskg, int q0, float scale, char* smem, int* sflags, f32x16 (&o)[4], float& l_run) {
;     ...
; #pragma unroll
;     for (int kt = 0; kt < 2; ++kt)
; #pragma unroll
;       for (int sb = 0; sb < 2; ++sb) {
;         const bf16x8 pf = pack8(s[kt][8 * sb + 0], s[kt][8 * sb + 1], s[kt][8 * sb + 2], s[kt][8 * sb + 3],
;                                 s[kt][8 * sb + 4], s[kt][8 * sb + 5], s[kt][8 * sb + 6], s[kt][8 * sb + 7]);
; #pragma unroll
;         for (int t = 0; t < 4; ++t) {
;           const bf16x8 vf = *(const bf16x8*)(Vs + (32 * t + l31) * 72 + 32 * kt + 16 * sb + hh * 8);
;           o[t] = MFMA32(vf, pf, o[t]);
;         }
;       }
	v_mfma_f32_32x32x16_bf16 v[64:79], v[110:113], v[102:105], v[64:79]
	ds_read_b128 v[110:113], v86 offset:26656
	s_waitcnt lgkmcnt(5)
	v_mfma_f32_32x32x16_bf16 v[48:63], v[114:117], v[102:105], v[48:63]
	ds_read_b128 v[114:117], v86 offset:31264
	s_waitcnt lgkmcnt(5)
	v_mfma_f32_32x32x16_bf16 v[32:47], v[118:121], v[102:105], v[32:47]
	ds_read_b128 v[118:121], v86 offset:17472
	s_waitcnt lgkmcnt(5)
	v_mfma_f32_32x32x16_bf16 v[16:31], v[122:125], v[102:105], v[16:31]
	ds_read_b128 v[122:125], v86 offset:22080
	v_cvt_pk_bf16_f32 v98, v85, v87
	v_cvt_pk_bf16_f32 v99, v88, v91
	v_cvt_pk_bf16_f32 v100, v92, v95
	v_cvt_pk_bf16_f32 v101, v96, v97
	s_nop 1
	s_waitcnt lgkmcnt(5)
	v_mfma_f32_32x32x16_bf16 v[64:79], v[126:129], v[98:101], v[64:79]
	ds_read_b128 v[126:129], v86 offset:26688
	s_waitcnt lgkmcnt(5)
	v_mfma_f32_32x32x16_bf16 v[48:63], v[130:133], v[98:101], v[48:63]
	ds_read_b128 v[130:133], v86 offset:31296
	s_waitcnt lgkmcnt(5)
	v_mfma_f32_32x32x16_bf16 v[32:47], v[110:113], v[98:101], v[32:47]
	ds_read_b128 v[110:113], v86 offset:17504
	s_waitcnt lgkmcnt(5)
	v_mfma_f32_32x32x16_bf16 v[16:31], v[114:117], v[98:101], v[16:31]
	ds_read_b128 v[114:117], v86 offset:22112
	v_cvt_pk_bf16_f32 v88, v13, v14
	v_cvt_pk_bf16_f32 v89, v15, v80
	v_cvt_pk_bf16_f32 v90, v81, v82
	v_cvt_pk_bf16_f32 v91, v83, v84
	s_nop 1
	s_waitcnt lgkmcnt(5)
	v_mfma_f32_32x32x16_bf16 v[64:79], v[118:121], v[88:91], v[64:79]
	ds_read_b128 v[118:121], v86 offset:26720
	s_waitcnt lgkmcnt(5)
	v_mfma_f32_32x32x16_bf16 v[48:63], v[122:125], v[88:91], v[48:63]
	ds_read_b128 v[122:125], v86 offset:31328
	s_waitcnt lgkmcnt(5)
	v_mfma_f32_32x32x16_bf16 v[32:47], v[126:129], v[88:91], v[32:47]
	s_waitcnt lgkmcnt(4)
	v_mfma_f32_32x32x16_bf16 v[16:31], v[130:133], v[88:91], v[16:31]
	v_cvt_pk_bf16_f32 v80, v5, v6
	v_cvt_pk_bf16_f32 v81, v7, v8
	v_cvt_pk_bf16_f32 v82, v9, v10
	v_cvt_pk_bf16_f32 v83, v11, v12
	s_nop 1
	s_waitcnt lgkmcnt(3)
	v_mfma_f32_32x32x16_bf16 v[64:79], v[110:113], v[80:83], v[64:79]
	s_waitcnt lgkmcnt(2)
	v_mfma_f32_32x32x16_bf16 v[48:63], v[114:117], v[80:83], v[48:63]
	s_waitcnt lgkmcnt(1)
	v_mfma_f32_32x32x16_bf16 v[32:47], v[118:121], v[80:83], v[32:47]
	s_waitcnt lgkmcnt(0)
	v_mfma_f32_32x32x16_bf16 v[16:31], v[122:125], v[80:83], v[16:31]

; #define MFMA32(a, b, c) __builtin_amdgcn_mfma_f32_32x32x16_bf16((a), (b), (c), 0, 0, 0)
; DI f32x16 zero16() { f32x16 z; for (int i = 0; i < 16; ++i) z[i] = 0.f; return z; }
; template <int DQK, int MODE>
; DI void attn_core(const u16* __restrict__ Qg, int ldq, const u16* __restrict__ Kg, int ldk, const u16* __restrict__ Vtg,
;                   const u64* __restrict__ maskg, int q0, float scale, char* smem, int* sflags, f32x16 (&o)[4], float& l_run) {
;     ...
;   for (int it = 0; it < ntiles; ++it, tau += step) {
;     __syncthreads();
;     if (MODE == 2 && it > 0) {
;       if (!(sflags[0] | sflags[1] | sflags[2] | sflags[3] | sflags[4] | sflags[5] | sflags[6] | sflags[7])) break;
;     }
;     if (MODE == 2) gload(tau);
; #pragma unroll
;     for (int i = 0; i < NVK; ++i) {
;       const int v = tid + NT * i, row = v / VPR, c = v % VPR;
;       *(u32x4*)(Ks + row * KSTR + c * 8) = rk[i];
;     }
; #pragma unroll
;     for (int i = 0; i < 2; ++i) {
;       const int v = tid + NT * i, row = v >> 3, c = v & 7;
;       *(u32x4*)(Vs + row * 72 + c * 8) = rv[i];
;     }
;     __syncthreads();
;     if (MODE != 2 && it + 1 < ntiles) gload(tau + step);
;     if (tau * 64 > q0 + 32 * wid + 31) {
;       if (MODE == 2 && lane == 0) sflags[wid] = 1;
;       continue;
;     }
;     u64 mbits = 0;
;     if (MODE == 1) mbits = maskg[(long)qrow * 64 + tau] >> (8 * hh);
;     f32x16 s[2];
;     s[0] = zero16(); s[1] = zero16();
; #pragma unroll
;     for (int kt = 0; kt < 2; ++kt)
; #pragma unroll
;       for (int ks = 0; ks < NKS; ++ks) {
;         const bf16x8 kf = *(const bf16x8*)(Ks + (32 * kt + krow) * KSTR + ks * 16 + hh * 8);
;         s[kt] = MFMA32(kf, qf[ks], s[kt]);
;       }
.LBB0_169:
	v_add_u32_e32 v0, s14, v220
	v_mad_i64_i32 v[2:3], s[4:5], v0, s95, v[184:185]
	v_add_u32_e32 v0, s14, v219
	s_add_i32 s0, s14, 64
	v_mad_i64_i32 v[4:5], s[4:5], v0, s95, v[186:187]
	v_add_u32_e32 v0, s14, v218
	s_barrier
	s_waitcnt vmcnt(0)
	ds_write_b128 v221, v[176:179]
	ds_write_b128 v226, v[172:175]
	ds_write_b128 v227, v[168:171]
	ds_write_b128 v228, v[164:167] offset:25600
	ds_write_b128 v229, v[160:163] offset:25600
	s_waitcnt lgkmcnt(0)
	s_barrier
	global_load_dwordx4 v[176:179], v[2:3], off
	global_load_dwordx4 v[172:175], v[4:5], off
	v_mad_i64_i32 v[2:3], s[4:5], v0, s95, v[206:207]
	s_ashr_i32 s1, s0, 31
	s_lshl_b64 s[4:5], s[0:1], 1
	global_load_dwordx4 v[168:171], v[2:3], off
	v_lshl_add_u64 v[2:3], v[180:181], 0, s[4:5]
	v_lshl_add_u64 v[4:5], v[182:183], 0, s[4:5]
	global_load_dwordx4 v[164:167], v[2:3], off
	global_load_dwordx4 v[160:163], v[4:5], off
	v_cmp_le_i32_e32 vcc, s14, v217
	s_and_saveexec_b64 s[4:5], vcc
	s_cbranch_execz .LBB0_175
	v_add_u32_e32 v0, v211, v216
	ds_read_b128 v[10:13], v0
	ds_read_b128 v[198:201], v0 offset:32
	ds_read_b128 v[202:205], v0 offset:64
	ds_read_b128 v[232:235], v0 offset:96
	ds_read_b128 v[236:239], v0 offset:128
	ds_read_b128 v[240:243], v0 offset:160
	s_add_i32 s1, s14, 63
	v_cmp_gt_i32_e32 vcc, s1, v214
	s_waitcnt lgkmcnt(5)
	v_mfma_f32_32x32x16_bf16 v[80:95], v[10:13], v[156:159], 0
	ds_read_b128 v[10:13], v0 offset:192
	s_waitcnt lgkmcnt(5)
	v_mfma_f32_32x32x16_bf16 v[80:95], v[198:201], v[152:155], v[80:95]
	ds_read_b128 v[198:201], v0 offset:224
	s_waitcnt lgkmcnt(5)
	v_mfma_f32_32x32x16_bf16 v[80:95], v[202:205], v[148:151], v[80:95]
	ds_read_b128 v[202:205], v0 offset:256
	s_waitcnt lgkmcnt(5)
	v_mfma_f32_32x32x16_bf16 v[80:95], v[232:235], v[144:147], v[80:95]
	ds_read_b128 v[232:235], v0 offset:288
	s_waitcnt lgkmcnt(5)
	v_mfma_f32_32x32x16_bf16 v[80:95], v[236:239], v[140:143], v[80:95]
	ds_read_b128 v[236:239], v0 offset:320
	s_waitcnt lgkmcnt(5)
	v_mfma_f32_32x32x16_bf16 v[80:95], v[240:243], v[136:139], v[80:95]
	ds_read_b128 v[240:243], v0 offset:352
	s_waitcnt lgkmcnt(5)
	v_mfma_f32_32x32x16_bf16 v[80:95], v[10:13], v[132:135], v[80:95]
	ds_read_b128 v[10:13], v0 offset:12800
	s_waitcnt lgkmcnt(5)
	v_mfma_f32_32x32x16_bf16 v[80:95], v[198:201], v[128:131], v[80:95]
	ds_read_b128 v[198:201], v0 offset:12832
	s_waitcnt lgkmcnt(5)
	v_mfma_f32_32x32x16_bf16 v[80:95], v[202:205], v[124:127], v[80:95]
	ds_read_b128 v[202:205], v0 offset:12864
	s_waitcnt lgkmcnt(5)
	v_mfma_f32_32x32x16_bf16 v[80:95], v[232:235], v[120:123], v[80:95]
	ds_read_b128 v[232:235], v0 offset:12896
	s_waitcnt lgkmcnt(5)
	v_mfma_f32_32x32x16_bf16 v[80:95], v[236:239], v[116:119], v[80:95]
	ds_read_b128 v[236:239], v0 offset:12928
	s_waitcnt lgkmcnt(5)
	v_mfma_f32_32x32x16_bf16 v[80:95], v[240:243], v[112:115], v[80:95]
	ds_read_b128 v[240:243], v0 offset:12960
	s_waitcnt lgkmcnt(5)
	v_mfma_f32_32x32x16_bf16 v[96:111], v[10:13], v[156:159], 0
	ds_read_b128 v[10:13], v0 offset:12992
	s_waitcnt lgkmcnt(5)
	v_mfma_f32_32x32x16_bf16 v[96:111], v[198:201], v[152:155], v[96:111]
	ds_read_b128 v[198:201], v0 offset:13024
	s_waitcnt lgkmcnt(5)
	v_mfma_f32_32x32x16_bf16 v[96:111], v[202:205], v[148:151], v[96:111]
	ds_read_b128 v[202:205], v0 offset:13056
	s_waitcnt lgkmcnt(5)
	v_mfma_f32_32x32x16_bf16 v[96:111], v[232:235], v[144:147], v[96:111]
	ds_read_b128 v[232:235], v0 offset:13088
	s_waitcnt lgkmcnt(5)
	v_mfma_f32_32x32x16_bf16 v[96:111], v[236:239], v[140:143], v[96:111]
	ds_read_b128 v[236:239], v0 offset:13120
	s_waitcnt lgkmcnt(5)
	v_mfma_f32_32x32x16_bf16 v[96:111], v[240:243], v[136:139], v[96:111]
	ds_read_b128 v[240:243], v0 offset:13152
	s_waitcnt lgkmcnt(5)
	v_mfma_f32_32x32x16_bf16 v[96:111], v[10:13], v[132:135], v[96:111]
	s_waitcnt lgkmcnt(4)
	v_mfma_f32_32x32x16_bf16 v[96:111], v[198:201], v[128:131], v[96:111]
	s_waitcnt lgkmcnt(3)
	v_mfma_f32_32x32x16_bf16 v[96:111], v[202:205], v[124:127], v[96:111]
	s_waitcnt lgkmcnt(2)
	v_mfma_f32_32x32x16_bf16 v[96:111], v[232:235], v[120:123], v[96:111]
	s_waitcnt lgkmcnt(1)
	v_mfma_f32_32x32x16_bf16 v[96:111], v[236:239], v[116:119], v[96:111]
	s_waitcnt lgkmcnt(0)
	v_mfma_f32_32x32x16_bf16 v[96:111], v[240:243], v[112:115], v[96:111]
	s_and_saveexec_b64 s[6:7], vcc
	s_cbranch_execz .LBB0_172
; template <int DQK, int MODE>
; DI void attn_core(const u16* __restrict__ Qg, int ldq, const u16* __restrict__ Kg, int ldk, const u16* __restrict__ Vtg,
;                   const u64* __restrict__ maskg, int q0, float scale, char* smem, int* sflags, f32x16 (&o)[4], float& l_run) {
;     ...
;       const bool need_mask = (MODE == 1) || (tau * 64 + 63 > q0 + 32 * wid);
;       float mx = -1e30f;
;       if (need_mask) {
; #pragma unroll
;         for (int kt = 0; kt < 2; ++kt)
; #pragma unroll
;           for (int i = 0; i < 16; ++i) {
;             bool valid;
;             if (MODE == 1) valid = (mbits >> (32 * kt + 16 * (i >> 3) + (i & 7))) & 1ull;
;             else valid = (kbase + 32 * kt + 16 * (i >> 3) + (i & 7)) <= qrow;
;             s[kt][i] = valid ? s[kt][i] : -1e30f;
;           }
	v_add_u32_e32 v0, s14, v215
	v_cmp_le_i32_e32 vcc, v0, v213
	v_add_u32_e32 v2, 2, v0
	s_nop 0
	v_cndmask_b32_e32 v80, v225, v80, vcc
	v_cmp_lt_i32_e32 vcc, v0, v213
	s_nop 1
	v_cndmask_b32_e32 v81, v225, v81, vcc
	v_cmp_le_i32_e32 vcc, v2, v213
	v_add_u32_e32 v2, 3, v0
	s_nop 0
	v_cndmask_b32_e32 v82, v225, v82, vcc
	v_cmp_le_i32_e32 vcc, v2, v213
	v_add_u32_e32 v2, 4, v0
	s_nop 0
	v_cndmask_b32_e32 v83, v225, v83, vcc
	v_cmp_le_i32_e32 vcc, v2, v213
	v_add_u32_e32 v2, 5, v0
	s_nop 0
	v_cndmask_b32_e32 v84, v225, v84, vcc
	v_cmp_le_i32_e32 vcc, v2, v213
	v_add_u32_e32 v2, 6, v0
	s_nop 0
	v_cndmask_b32_e32 v85, v225, v85, vcc
	v_cmp_le_i32_e32 vcc, v2, v213
	v_add_u32_e32 v2, 7, v0
	s_nop 0
	v_cndmask_b32_e32 v86, v225, v86, vcc
	v_cmp_le_i32_e32 vcc, v2, v213
	v_add_u32_e32 v2, 16, v0
	s_nop 0
	v_cndmask_b32_e32 v87, v225, v87, vcc
	v_cmp_le_i32_e32 vcc, v2, v213
	v_add_u32_e32 v2, 17, v0
	s_nop 0
	v_cndmask_b32_e32 v88, v225, v88, vcc
	v_cmp_le_i32_e32 vcc, v2, v213
	v_add_u32_e32 v2, 18, v0
	s_nop 0
	v_cndmask_b32_e32 v89, v225, v89, vcc
	v_cmp_le_i32_e32 vcc, v2, v213
	v_add_u32_e32 v2, 19, v0
	s_nop 0
	v_cndmask_b32_e32 v90, v225, v90, vcc
	v_cmp_le_i32_e32 vcc, v2, v213
	v_add_u32_e32 v2, 20, v0
	s_nop 0
	v_cndmask_b32_e32 v91, v225, v91, vcc
	v_cmp_le_i32_e32 vcc, v2, v213
	v_add_u32_e32 v2, 21, v0
	s_nop 0
	v_cndmask_b32_e32 v92, v225, v92, vcc
	v_cmp_le_i32_e32 vcc, v2, v213
	v_add_u32_e32 v2, 22, v0
	s_nop 0
	v_cndmask_b32_e32 v93, v225, v93, vcc
	v_cmp_le_i32_e32 vcc, v2, v213
	v_add_u32_e32 v2, 23, v0
	s_nop 0
	v_cndmask_b32_e32 v94, v225, v94, vcc
	v_cmp_le_i32_e32 vcc, v2, v213
	v_add_u32_e32 v2, 32, v0
	s_nop 0
	v_cndmask_b32_e32 v95, v225, v95, vcc
	v_cmp_le_i32_e32 vcc, v2, v213
	v_add_u32_e32 v2, 33, v0
	s_nop 0
	v_cndmask_b32_e32 v96, v225, v96, vcc
	v_cmp_le_i32_e32 vcc, v2, v213
	v_add_u32_e32 v2, 34, v0
	s_nop 0
	v_cndmask_b32_e32 v97, v225, v97, vcc
	v_cmp_le_i32_e32 vcc, v2, v213
	v_add_u32_e32 v2, 35, v0
	s_nop 0
	v_cndmask_b32_e32 v98, v225, v98, vcc
	v_cmp_le_i32_e32 vcc, v2, v213
	v_add_u32_e32 v2, 36, v0
	s_nop 0
	v_cndmask_b32_e32 v99, v225, v99, vcc
	v_cmp_le_i32_e32 vcc, v2, v213
	v_add_u32_e32 v2, 37, v0
	s_nop 0
	v_cndmask_b32_e32 v100, v225, v100, vcc
	v_cmp_le_i32_e32 vcc, v2, v213
	v_add_u32_e32 v2, 38, v0
	s_nop 0
	v_cndmask_b32_e32 v101, v225, v101, vcc
	v_cmp_le_i32_e32 vcc, v2, v213
	v_add_u32_e32 v2, 39, v0
	s_nop 0
	v_cndmask_b32_e32 v102, v225, v102, vcc
	v_cmp_le_i32_e32 vcc, v2, v213
	v_add_u32_e32 v2, 48, v0
	s_nop 0
	v_cndmask_b32_e32 v103, v225, v103, vcc
	v_cmp_le_i32_e32 vcc, v2, v213
	v_add_u32_e32 v2, 49, v0
	s_nop 0
	v_cndmask_b32_e32 v104, v225, v104, vcc
	v_cmp_le_i32_e32 vcc, v2, v213
	v_add_u32_e32 v2, 50, v0
	s_nop 0
	v_cndmask_b32_e32 v105, v225, v105, vcc
	v_cmp_le_i32_e32 vcc, v2, v213
	v_add_u32_e32 v2, 51, v0
	s_nop 0
	v_cndmask_b32_e32 v106, v225, v106, vcc
	v_cmp_le_i32_e32 vcc, v2, v213
	v_add_u32_e32 v2, 52, v0
	s_nop 0
	v_cndmask_b32_e32 v107, v225, v107, vcc
	v_cmp_le_i32_e32 vcc, v2, v213
	v_add_u32_e32 v2, 53, v0
	s_nop 0
	v_cndmask_b32_e32 v108, v225, v108, vcc
	v_cmp_le_i32_e32 vcc, v2, v213
	v_add_u32_e32 v2, 54, v0
	v_add_u32_e32 v0, 55, v0
	v_cndmask_b32_e32 v109, v225, v109, vcc
	v_cmp_le_i32_e32 vcc, v2, v213
	s_nop 1
	v_cndmask_b32_e32 v110, v225, v110, vcc
	v_cmp_le_i32_e32 vcc, v0, v213
	s_nop 1
	v_cndmask_b32_e32 v111, v225, v111, vcc

; #define MFMA32(a, b, c) __builtin_amdgcn_mfma_f32_32x32x16_bf16((a), (b), (c), 0, 0, 0)
; template <int DQK, int MODE>
; DI void attn_core(const u16* __restrict__ Qg, int ldq, const u16* __restrict__ Kg, int ldk, const u16* __restrict__ Vtg,
;                   const u64* __restrict__ maskg, int q0, float scale, char* smem, int* sflags, f32x16 (&o)[4], float& l_run) {
;     ...
;       const float msc = -m_new * sc;
;       float ls = 0.f;
; #pragma unroll
;       for (int kt = 0; kt < 2; ++kt)
; #pragma unroll
;         for (int i = 0; i < 16; ++i) {
;           float pv = __builtin_amdgcn_exp2f(__builtin_fmaf(s[kt][i], sc, msc));
;           if (MODE == 1) pv = (s[kt][i] > -1e29f) ? pv : 0.f;
;           s[kt][i] = pv;
;           ls += pv;
;         }
;     ...
; #pragma unroll
;     for (int kt = 0; kt < 2; ++kt)
; #pragma unroll
;       for (int sb = 0; sb < 2; ++sb) {
;         const bf16x8 pf = pack8(s[kt][8 * sb + 0], s[kt][8 * sb + 1], s[kt][8 * sb + 2], s[kt][8 * sb + 3],
;                                 s[kt][8 * sb + 4], s[kt][8 * sb + 5], s[kt][8 * sb + 6], s[kt][8 * sb + 7]);
; #pragma unroll
;         for (int t = 0; t < 4; ++t) {
;           const bf16x8 vf = *(const bf16x8*)(Vs + (32 * t + l31) * 72 + 32 * kt + 16 * sb + hh * 8);
;           o[t] = MFMA32(vf, pf, o[t]);
;         }
;       }
.LBB0_174:
	v_mul_f32_e32 v9, 0xbdd53b94, v2
	v_fmamk_f32 v0, v80, 0x3dd53b94, v9
	v_exp_f32_e32 v198, v0
	v_fmamk_f32 v3, v81, 0x3dd53b94, v9
	v_exp_f32_e32 v199, v3
	v_fmamk_f32 v3, v82, 0x3dd53b94, v9
	v_exp_f32_e32 v200, v3
	v_fmamk_f32 v3, v83, 0x3dd53b94, v9
	v_exp_f32_e32 v201, v3
	v_fmamk_f32 v3, v84, 0x3dd53b94, v9
	v_add_f32_e32 v0, 0, v198
	v_exp_f32_e32 v202, v3
	v_fmamk_f32 v3, v85, 0x3dd53b94, v9
	v_add_f32_e32 v0, v199, v0
	v_exp_f32_e32 v203, v3
	v_fmamk_f32 v3, v86, 0x3dd53b94, v9
	v_add_f32_e32 v0, v200, v0
	v_exp_f32_e32 v86, v3
	v_fmamk_f32 v3, v87, 0x3dd53b94, v9
	v_add_f32_e32 v0, v201, v0
	v_exp_f32_e32 v87, v3
	v_fmamk_f32 v3, v88, 0x3dd53b94, v9
	v_add_f32_e32 v0, v202, v0
	v_exp_f32_e32 v204, v3
	v_fmamk_f32 v3, v89, 0x3dd53b94, v9
	v_add_f32_e32 v0, v203, v0
	v_exp_f32_e32 v205, v3
	v_fmamk_f32 v3, v90, 0x3dd53b94, v9
	v_add_f32_e32 v0, v86, v0
	v_exp_f32_e32 v90, v3
	v_fmamk_f32 v3, v91, 0x3dd53b94, v9
	v_add_f32_e32 v0, v87, v0
	v_exp_f32_e32 v91, v3
	v_fmamk_f32 v3, v92, 0x3dd53b94, v9
	v_add_f32_e32 v0, v204, v0
	v_exp_f32_e32 v92, v3
	v_fmamk_f32 v3, v93, 0x3dd53b94, v9
	v_add_f32_e32 v0, v205, v0
	v_exp_f32_e32 v93, v3
	v_fmamk_f32 v3, v94, 0x3dd53b94, v9
	v_add_f32_e32 v0, v90, v0
	v_exp_f32_e32 v94, v3
	v_fmamk_f32 v3, v95, 0x3dd53b94, v9
	v_add_f32_e32 v0, v91, v0
	v_exp_f32_e32 v95, v3
	v_fmamk_f32 v3, v96, 0x3dd53b94, v9
	v_add_f32_e32 v0, v92, v0
	v_exp_f32_e32 v10, v3
	v_fmamk_f32 v3, v97, 0x3dd53b94, v9
	v_add_f32_e32 v0, v93, v0
	v_exp_f32_e32 v11, v3
	v_fmamk_f32 v3, v98, 0x3dd53b94, v9
	v_add_f32_e32 v0, v94, v0
	v_exp_f32_e32 v12, v3
	v_fmamk_f32 v3, v99, 0x3dd53b94, v9
	v_add_f32_e32 v0, v95, v0
	v_exp_f32_e32 v13, v3
	v_fmamk_f32 v3, v100, 0x3dd53b94, v9
	v_add_f32_e32 v0, v10, v0
	v_exp_f32_e32 v14, v3
	v_fmamk_f32 v3, v101, 0x3dd53b94, v9
	v_add_f32_e32 v0, v11, v0
	v_exp_f32_e32 v15, v3
	v_fmamk_f32 v3, v102, 0x3dd53b94, v9
	v_add_f32_e32 v0, v12, v0
	v_exp_f32_e32 v80, v3
	v_fmamk_f32 v3, v103, 0x3dd53b94, v9
	v_add_f32_e32 v0, v13, v0
	v_exp_f32_e32 v81, v3
	v_add_f32_e32 v0, v14, v0
	v_add_f32_e32 v0, v15, v0
	v_add_f32_e32 v0, v80, v0
	v_add_f32_e32 v3, v81, v0
	v_fmamk_f32 v0, v104, 0x3dd53b94, v9
	v_exp_f32_e32 v0, v0
	v_add_u32_e32 v96, v211, v212
	v_mov_b32_e32 v230, v2
	v_add_f32_e32 v4, v0, v3
	v_fmamk_f32 v3, v105, 0x3dd53b94, v9
	v_exp_f32_e32 v3, v3
	s_nop 0
	v_add_f32_e32 v5, v3, v4
	v_fmamk_f32 v4, v106, 0x3dd53b94, v9
	v_exp_f32_e32 v4, v4
	s_nop 0
	v_add_f32_e32 v6, v4, v5
	v_fmamk_f32 v5, v107, 0x3dd53b94, v9
	v_exp_f32_e32 v5, v5
	s_nop 0
	v_add_f32_e32 v7, v5, v6
	v_fmamk_f32 v6, v108, 0x3dd53b94, v9
	v_exp_f32_e32 v6, v6
	s_nop 0
	v_add_f32_e32 v8, v6, v7
	v_fmamk_f32 v7, v109, 0x3dd53b94, v9
	v_exp_f32_e32 v7, v7
	s_nop 0
	v_add_f32_e32 v82, v7, v8
	v_fmamk_f32 v8, v110, 0x3dd53b94, v9
	v_exp_f32_e32 v8, v8
	v_fmac_f32_e32 v9, 0x3dd53b94, v111
	v_exp_f32_e32 v9, v9
	v_add_f32_e32 v82, v8, v82
	v_add_f32_e32 v82, v9, v82
	v_add_f32_e32 v210, v82, v210
	v_cvt_pk_bf16_f32 v82, v198, v199
	v_cvt_pk_bf16_f32 v83, v200, v201
	v_cvt_pk_bf16_f32 v84, v202, v203
	v_cvt_pk_bf16_f32 v85, v86, v87
	s_nop 1
	ds_read_b128 v[98:101], v96 offset:25600
	ds_read_b128 v[102:105], v96 offset:30208
	ds_read_b128 v[198:201], v96 offset:34816
	ds_read_b128 v[232:235], v96 offset:39424
	ds_read_b128 v[236:239], v96 offset:25632
	ds_read_b128 v[240:243], v96 offset:30240
	s_waitcnt lgkmcnt(5)
	v_mfma_f32_32x32x16_bf16 v[64:79], v[98:101], v[82:85], v[64:79]
	ds_read_b128 v[98:101], v96 offset:34848
	s_waitcnt lgkmcnt(5)
	v_mfma_f32_32x32x16_bf16 v[48:63], v[102:105], v[82:85], v[48:63]
	ds_read_b128 v[102:105], v96 offset:39456
	s_waitcnt lgkmcnt(5)
	v_mfma_f32_32x32x16_bf16 v[32:47], v[198:201], v[82:85], v[32:47]
	ds_read_b128 v[198:201], v96 offset:25664
	s_waitcnt lgkmcnt(5)
	v_mfma_f32_32x32x16_bf16 v[16:31], v[232:235], v[82:85], v[16:31]
	ds_read_b128 v[232:235], v96 offset:30272
	v_cvt_pk_bf16_f32 v82, v204, v205
	v_cvt_pk_bf16_f32 v83, v90, v91
	v_cvt_pk_bf16_f32 v84, v92, v93
	v_cvt_pk_bf16_f32 v85, v94, v95
	s_nop 1
	s_waitcnt lgkmcnt(5)
	v_mfma_f32_32x32x16_bf16 v[64:79], v[236:239], v[82:85], v[64:79]
	ds_read_b128 v[236:239], v96 offset:34880
	s_waitcnt lgkmcnt(5)
	v_mfma_f32_32x32x16_bf16 v[48:63], v[240:243], v[82:85], v[48:63]
	ds_read_b128 v[240:243], v96 offset:39488
	s_waitcnt lgkmcnt(5)
	v_mfma_f32_32x32x16_bf16 v[32:47], v[98:101], v[82:85], v[32:47]
	ds_read_b128 v[98:101], v96 offset:25696
	s_waitcnt lgkmcnt(5)
	v_mfma_f32_32x32x16_bf16 v[16:31], v[102:105], v[82:85], v[16:31]
	ds_read_b128 v[102:105], v96 offset:30304
	v_cvt_pk_bf16_f32 v82, v10, v11
	v_cvt_pk_bf16_f32 v83, v12, v13
	v_cvt_pk_bf16_f32 v84, v14, v15
	v_cvt_pk_bf16_f32 v85, v80, v81
	s_nop 1
	s_waitcnt lgkmcnt(5)
	v_mfma_f32_32x32x16_bf16 v[64:79], v[198:201], v[82:85], v[64:79]
	ds_read_b128 v[198:201], v96 offset:34912
	s_waitcnt lgkmcnt(5)
	v_mfma_f32_32x32x16_bf16 v[48:63], v[232:235], v[82:85], v[48:63]
	ds_read_b128 v[232:235], v96 offset:39520
	s_waitcnt lgkmcnt(5)
	v_mfma_f32_32x32x16_bf16 v[32:47], v[236:239], v[82:85], v[32:47]
	s_waitcnt lgkmcnt(4)
	v_mfma_f32_32x32x16_bf16 v[16:31], v[240:243], v[82:85], v[16:31]
	v_cvt_pk_bf16_f32 v10, v0, v3
	v_cvt_pk_bf16_f32 v11, v4, v5
	v_cvt_pk_bf16_f32 v12, v6, v7
	v_cvt_pk_bf16_f32 v13, v8, v9
	s_nop 1
	s_waitcnt lgkmcnt(3)
	v_mfma_f32_32x32x16_bf16 v[64:79], v[98:101], v[10:13], v[64:79]
	s_waitcnt lgkmcnt(2)
	v_mfma_f32_32x32x16_bf16 v[48:63], v[102:105], v[10:13], v[48:63]
	s_waitcnt lgkmcnt(1)
	v_mfma_f32_32x32x16_bf16 v[32:47], v[198:201], v[10:13], v[32:47]
	s_waitcnt lgkmcnt(0)
	v_mfma_f32_32x32x16_bf16 v[16:31], v[232:235], v[10:13], v[16:31]

; #define MFMA32(a, b, c) __builtin_amdgcn_mfma_f32_32x32x16_bf16((a), (b), (c), 0, 0, 0)
; DI f32x16 zero16() { f32x16 z; for (int i = 0; i < 16; ++i) z[i] = 0.f; return z; }
; template <int DQK, int MODE>
; DI void attn_core(const u16* __restrict__ Qg, int ldq, const u16* __restrict__ Kg, int ldk, const u16* __restrict__ Vtg,
;                   const u64* __restrict__ maskg, int q0, float scale, char* smem, int* sflags, f32x16 (&o)[4], float& l_run) {
;     ...
;     __syncthreads();
;     if (MODE == 2 && it > 0) {
;       if (!(sflags[0] | sflags[1] | sflags[2] | sflags[3] | sflags[4] | sflags[5] | sflags[6] | sflags[7])) break;
;     }
;     if (MODE == 2) gload(tau);
; #pragma unroll
;     for (int i = 0; i < NVK; ++i) {
;       const int v = tid + NT * i, row = v / VPR, c = v % VPR;
;       *(u32x4*)(Ks + row * KSTR + c * 8) = rk[i];
;     }
; #pragma unroll
;     for (int i = 0; i < 2; ++i) {
;       const int v = tid + NT * i, row = v >> 3, c = v & 7;
;       *(u32x4*)(Vs + row * 72 + c * 8) = rv[i];
;     }
;     __syncthreads();
;     if (MODE != 2 && it + 1 < ntiles) gload(tau + step);
;     if (tau * 64 > q0 + 32 * wid + 31) {
;       if (MODE == 2 && lane == 0) sflags[wid] = 1;
;       continue;
;     }
;     u64 mbits = 0;
;     if (MODE == 1) mbits = maskg[(long)qrow * 64 + tau] >> (8 * hh);
;     f32x16 s[2];
;     s[0] = zero16(); s[1] = zero16();
; #pragma unroll
;     for (int kt = 0; kt < 2; ++kt)
; #pragma unroll
;       for (int ks = 0; ks < NKS; ++ks) {
;         const bf16x8 kf = *(const bf16x8*)(Ks + (32 * kt + krow) * KSTR + ks * 16 + hh * 8);
;         s[kt] = MFMA32(kf, qf[ks], s[kt]);
;       }
.LBB0_177:
	s_lshl_b32 s6, s12, 6
	v_cmp_le_i32_e32 vcc, s6, v217
	s_barrier
	s_waitcnt vmcnt(4)
	ds_write_b128 v221, v[176:179]
	s_waitcnt vmcnt(3)
	ds_write_b128 v226, v[172:175]
	s_waitcnt vmcnt(2)
	ds_write_b128 v227, v[168:171]
	s_waitcnt vmcnt(1)
	ds_write_b128 v228, v[164:167] offset:25600
	s_waitcnt vmcnt(0)
	ds_write_b128 v229, v[160:163] offset:25600
	s_waitcnt lgkmcnt(0)
	s_barrier
	s_and_saveexec_b64 s[0:1], vcc
	s_xor_b64 s[0:1], exec, s[0:1]
	s_cbranch_execz .LBB0_184
	v_add_u32_e32 v0, v211, v216
	ds_read_b128 v[10:13], v0
	ds_read_b128 v[160:163], v0 offset:32
	ds_read_b128 v[164:167], v0 offset:64
	ds_read_b128 v[168:171], v0 offset:96
	ds_read_b128 v[172:175], v0 offset:128
	ds_read_b128 v[176:179], v0 offset:160
	s_or_b32 s4, s6, 63
	v_cmp_gt_i32_e32 vcc, s4, v214
	s_waitcnt lgkmcnt(5)
	v_mfma_f32_32x32x16_bf16 v[80:95], v[10:13], v[156:159], 0
	ds_read_b128 v[10:13], v0 offset:192
	s_waitcnt lgkmcnt(5)
	v_mfma_f32_32x32x16_bf16 v[80:95], v[160:163], v[152:155], v[80:95]
	ds_read_b128 v[160:163], v0 offset:224
	s_waitcnt lgkmcnt(5)
	v_mfma_f32_32x32x16_bf16 v[80:95], v[164:167], v[148:151], v[80:95]
	ds_read_b128 v[164:167], v0 offset:256
	s_waitcnt lgkmcnt(5)
	v_mfma_f32_32x32x16_bf16 v[80:95], v[168:171], v[144:147], v[80:95]
	ds_read_b128 v[168:171], v0 offset:288
	s_waitcnt lgkmcnt(5)
	v_mfma_f32_32x32x16_bf16 v[80:95], v[172:175], v[140:143], v[80:95]
	ds_read_b128 v[172:175], v0 offset:320
	s_waitcnt lgkmcnt(5)
	v_mfma_f32_32x32x16_bf16 v[80:95], v[176:179], v[136:139], v[80:95]
	ds_read_b128 v[176:179], v0 offset:352
	s_waitcnt lgkmcnt(5)
	v_mfma_f32_32x32x16_bf16 v[80:95], v[10:13], v[132:135], v[80:95]
	ds_read_b128 v[10:13], v0 offset:12800
	s_waitcnt lgkmcnt(5)
	v_mfma_f32_32x32x16_bf16 v[80:95], v[160:163], v[128:131], v[80:95]
	ds_read_b128 v[160:163], v0 offset:12832
	s_waitcnt lgkmcnt(5)
	v_mfma_f32_32x32x16_bf16 v[80:95], v[164:167], v[124:127], v[80:95]
	ds_read_b128 v[164:167], v0 offset:12864
	s_waitcnt lgkmcnt(5)
	v_mfma_f32_32x32x16_bf16 v[80:95], v[168:171], v[120:123], v[80:95]
	ds_read_b128 v[168:171], v0 offset:12896
	s_waitcnt lgkmcnt(5)
	v_mfma_f32_32x32x16_bf16 v[80:95], v[172:175], v[116:119], v[80:95]
	ds_read_b128 v[172:175], v0 offset:12928
	s_waitcnt lgkmcnt(5)
	v_mfma_f32_32x32x16_bf16 v[80:95], v[176:179], v[112:115], v[80:95]
	ds_read_b128 v[176:179], v0 offset:12960
	s_waitcnt lgkmcnt(5)
	v_mfma_f32_32x32x16_bf16 v[96:111], v[10:13], v[156:159], 0
	ds_read_b128 v[10:13], v0 offset:12992
	s_waitcnt lgkmcnt(5)
	v_mfma_f32_32x32x16_bf16 v[96:111], v[160:163], v[152:155], v[96:111]
	ds_read_b128 v[160:163], v0 offset:13024
	s_waitcnt lgkmcnt(5)
	v_mfma_f32_32x32x16_bf16 v[96:111], v[164:167], v[148:151], v[96:111]
	ds_read_b128 v[164:167], v0 offset:13056
	s_waitcnt lgkmcnt(5)
	v_mfma_f32_32x32x16_bf16 v[96:111], v[168:171], v[144:147], v[96:111]
	ds_read_b128 v[168:171], v0 offset:13088
	s_waitcnt lgkmcnt(5)
	v_mfma_f32_32x32x16_bf16 v[96:111], v[172:175], v[140:143], v[96:111]
	ds_read_b128 v[172:175], v0 offset:13120
	s_waitcnt lgkmcnt(5)
	v_mfma_f32_32x32x16_bf16 v[96:111], v[176:179], v[136:139], v[96:111]
	ds_read_b128 v[176:179], v0 offset:13152
	s_waitcnt lgkmcnt(5)
	v_mfma_f32_32x32x16_bf16 v[96:111], v[10:13], v[132:135], v[96:111]
	s_waitcnt lgkmcnt(4)
	v_mfma_f32_32x32x16_bf16 v[96:111], v[160:163], v[128:131], v[96:111]
	s_waitcnt lgkmcnt(3)
	v_mfma_f32_32x32x16_bf16 v[96:111], v[164:167], v[124:127], v[96:111]
	s_waitcnt lgkmcnt(2)
	v_mfma_f32_32x32x16_bf16 v[96:111], v[168:171], v[120:123], v[96:111]
	s_waitcnt lgkmcnt(1)
	v_mfma_f32_32x32x16_bf16 v[96:111], v[172:175], v[116:119], v[96:111]
	s_waitcnt lgkmcnt(0)
	v_mfma_f32_32x32x16_bf16 v[96:111], v[176:179], v[112:115], v[96:111]
	s_and_saveexec_b64 s[4:5], vcc
	s_cbranch_execz .LBB0_180
; template <int DQK, int MODE>
; DI void attn_core(const u16* __restrict__ Qg, int ldq, const u16* __restrict__ Kg, int ldk, const u16* __restrict__ Vtg,
;                   const u64* __restrict__ maskg, int q0, float scale, char* smem, int* sflags, f32x16 (&o)[4], float& l_run) {
;     ...
;       const bool need_mask = (MODE == 1) || (tau * 64 + 63 > q0 + 32 * wid);
;       float mx = -1e30f;
;       if (need_mask) {
; #pragma unroll
;         for (int kt = 0; kt < 2; ++kt)
; #pragma unroll
;           for (int i = 0; i < 16; ++i) {
;             bool valid;
;             if (MODE == 1) valid = (mbits >> (32 * kt + 16 * (i >> 3) + (i & 7))) & 1ull;
;             else valid = (kbase + 32 * kt + 16 * (i >> 3) + (i & 7)) <= qrow;
;             s[kt][i] = valid ? s[kt][i] : -1e30f;
;           }
	v_or_b32_e32 v0, s6, v215
	v_cmp_le_i32_e32 vcc, v0, v213
	v_or_b32_e32 v2, 2, v0
	s_nop 0
	v_cndmask_b32_e32 v80, v225, v80, vcc
	v_cmp_lt_i32_e32 vcc, v0, v213
	s_nop 1
	v_cndmask_b32_e32 v81, v225, v81, vcc
	v_cmp_le_i32_e32 vcc, v2, v213
	v_or_b32_e32 v2, 3, v0
	s_nop 0
	v_cndmask_b32_e32 v82, v225, v82, vcc
	v_cmp_le_i32_e32 vcc, v2, v213
	v_or_b32_e32 v2, 4, v0
	s_nop 0
	v_cndmask_b32_e32 v83, v225, v83, vcc
	v_cmp_le_i32_e32 vcc, v2, v213
	v_or_b32_e32 v2, 5, v0
	s_nop 0
	v_cndmask_b32_e32 v84, v225, v84, vcc
	v_cmp_le_i32_e32 vcc, v2, v213
	v_or_b32_e32 v2, 6, v0
	s_nop 0
	v_cndmask_b32_e32 v85, v225, v85, vcc
	v_cmp_le_i32_e32 vcc, v2, v213
	v_or_b32_e32 v2, 7, v0
	s_nop 0
	v_cndmask_b32_e32 v86, v225, v86, vcc
	v_cmp_le_i32_e32 vcc, v2, v213
	v_or_b32_e32 v2, 16, v0
	s_nop 0
	v_cndmask_b32_e32 v87, v225, v87, vcc
	v_cmp_le_i32_e32 vcc, v2, v213
	v_or_b32_e32 v2, 17, v0
	s_nop 0
	v_cndmask_b32_e32 v88, v225, v88, vcc
	v_cmp_le_i32_e32 vcc, v2, v213
	v_or_b32_e32 v2, 18, v0
	s_nop 0
	v_cndmask_b32_e32 v89, v225, v89, vcc
	v_cmp_le_i32_e32 vcc, v2, v213
	v_or_b32_e32 v2, 19, v0
	s_nop 0
	v_cndmask_b32_e32 v90, v225, v90, vcc
	v_cmp_le_i32_e32 vcc, v2, v213
	v_or_b32_e32 v2, 20, v0
	s_nop 0
	v_cndmask_b32_e32 v91, v225, v91, vcc
	v_cmp_le_i32_e32 vcc, v2, v213
	v_or_b32_e32 v2, 21, v0
	s_nop 0
	v_cndmask_b32_e32 v92, v225, v92, vcc
	v_cmp_le_i32_e32 vcc, v2, v213
	v_or_b32_e32 v2, 22, v0
	s_nop 0
	v_cndmask_b32_e32 v93, v225, v93, vcc
	v_cmp_le_i32_e32 vcc, v2, v213
	v_or_b32_e32 v2, 23, v0
	s_nop 0
	v_cndmask_b32_e32 v94, v225, v94, vcc
	v_cmp_le_i32_e32 vcc, v2, v213
	v_or_b32_e32 v2, 32, v0
	s_nop 0
	v_cndmask_b32_e32 v95, v225, v95, vcc
	v_cmp_le_i32_e32 vcc, v2, v213
	v_or_b32_e32 v2, 33, v0
	s_nop 0
	v_cndmask_b32_e32 v96, v225, v96, vcc
	v_cmp_le_i32_e32 vcc, v2, v213
	v_or_b32_e32 v2, 34, v0
	s_nop 0
	v_cndmask_b32_e32 v97, v225, v97, vcc
	v_cmp_le_i32_e32 vcc, v2, v213
	v_or_b32_e32 v2, 35, v0
	s_nop 0
	v_cndmask_b32_e32 v98, v225, v98, vcc
	v_cmp_le_i32_e32 vcc, v2, v213
	v_or_b32_e32 v2, 36, v0
	s_nop 0
	v_cndmask_b32_e32 v99, v225, v99, vcc
	v_cmp_le_i32_e32 vcc, v2, v213
	v_or_b32_e32 v2, 37, v0
	s_nop 0
	v_cndmask_b32_e32 v100, v225, v100, vcc
	v_cmp_le_i32_e32 vcc, v2, v213
	v_or_b32_e32 v2, 38, v0
	s_nop 0
	v_cndmask_b32_e32 v101, v225, v101, vcc
	v_cmp_le_i32_e32 vcc, v2, v213
	v_or_b32_e32 v2, 39, v0
	s_nop 0
	v_cndmask_b32_e32 v102, v225, v102, vcc
	v_cmp_le_i32_e32 vcc, v2, v213
	v_or_b32_e32 v2, 48, v0
	s_nop 0
	v_cndmask_b32_e32 v103, v225, v103, vcc
	v_cmp_le_i32_e32 vcc, v2, v213
	v_or_b32_e32 v2, 49, v0
	s_nop 0
	v_cndmask_b32_e32 v104, v225, v104, vcc
	v_cmp_le_i32_e32 vcc, v2, v213
	v_or_b32_e32 v2, 50, v0
	s_nop 0
	v_cndmask_b32_e32 v105, v225, v105, vcc
	v_cmp_le_i32_e32 vcc, v2, v213
	v_or_b32_e32 v2, 51, v0
	s_nop 0
	v_cndmask_b32_e32 v106, v225, v106, vcc
	v_cmp_le_i32_e32 vcc, v2, v213
	v_or_b32_e32 v2, 52, v0
	s_nop 0
	v_cndmask_b32_e32 v107, v225, v107, vcc
	v_cmp_le_i32_e32 vcc, v2, v213
	v_or_b32_e32 v2, 53, v0
	s_nop 0
	v_cndmask_b32_e32 v108, v225, v108, vcc
	v_cmp_le_i32_e32 vcc, v2, v213
	v_or_b32_e32 v2, 54, v0
	v_or_b32_e32 v0, 55, v0
	v_cndmask_b32_e32 v109, v225, v109, vcc
	v_cmp_le_i32_e32 vcc, v2, v213
	s_nop 1
	v_cndmask_b32_e32 v110, v225, v110, vcc
	v_cmp_le_i32_e32 vcc, v0, v213
	s_nop 1
	v_cndmask_b32_e32 v111, v225, v111, vcc

; #define MFMA32(a, b, c) __builtin_amdgcn_mfma_f32_32x32x16_bf16((a), (b), (c), 0, 0, 0)
; template <int DQK, int MODE>
; DI void attn_core(const u16* __restrict__ Qg, int ldq, const u16* __restrict__ Kg, int ldk, const u16* __restrict__ Vtg,
;                   const u64* __restrict__ maskg, int q0, float scale, char* smem, int* sflags, f32x16 (&o)[4], float& l_run) {
;     ...
;       const float msc = -m_new * sc;
;       float ls = 0.f;
; #pragma unroll
;       for (int kt = 0; kt < 2; ++kt)
; #pragma unroll
;         for (int i = 0; i < 16; ++i) {
;           float pv = __builtin_amdgcn_exp2f(__builtin_fmaf(s[kt][i], sc, msc));
;           if (MODE == 1) pv = (s[kt][i] > -1e29f) ? pv : 0.f;
;           s[kt][i] = pv;
;           ls += pv;
;         }
;     ...
; #pragma unroll
;     for (int kt = 0; kt < 2; ++kt)
; #pragma unroll
;       for (int sb = 0; sb < 2; ++sb) {
;         const bf16x8 pf = pack8(s[kt][8 * sb + 0], s[kt][8 * sb + 1], s[kt][8 * sb + 2], s[kt][8 * sb + 3],
;                                 s[kt][8 * sb + 4], s[kt][8 * sb + 5], s[kt][8 * sb + 6], s[kt][8 * sb + 7]);
; #pragma unroll
;         for (int t = 0; t < 4; ++t) {
;           const bf16x8 vf = *(const bf16x8*)(Vs + (32 * t + l31) * 72 + 32 * kt + 16 * sb + hh * 8);
;           o[t] = MFMA32(vf, pf, o[t]);
;         }
;       }
.LBB0_183:
	v_mul_f32_e32 v0, 0xbdd53b94, v5
	v_fmamk_f32 v5, v80, 0x3dd53b94, v0
	v_exp_f32_e32 v113, v5
	v_fmamk_f32 v6, v81, 0x3dd53b94, v0
	v_exp_f32_e32 v114, v6
	v_fmamk_f32 v6, v82, 0x3dd53b94, v0
	v_exp_f32_e32 v115, v6
	v_fmamk_f32 v6, v83, 0x3dd53b94, v0
	v_exp_f32_e32 v116, v6
	v_fmamk_f32 v6, v84, 0x3dd53b94, v0
	v_add_f32_e32 v5, 0, v113
	v_exp_f32_e32 v117, v6
	v_fmamk_f32 v6, v85, 0x3dd53b94, v0
	v_add_f32_e32 v5, v114, v5
	v_exp_f32_e32 v85, v6
	v_fmamk_f32 v6, v86, 0x3dd53b94, v0
	v_add_f32_e32 v5, v115, v5
	v_exp_f32_e32 v118, v6
	v_fmamk_f32 v6, v87, 0x3dd53b94, v0
	v_add_f32_e32 v5, v116, v5
	v_exp_f32_e32 v119, v6
	v_fmamk_f32 v6, v88, 0x3dd53b94, v0
	v_add_f32_e32 v5, v117, v5
	v_exp_f32_e32 v120, v6
	v_fmamk_f32 v6, v89, 0x3dd53b94, v0
	v_add_f32_e32 v5, v85, v5
	v_exp_f32_e32 v121, v6
	v_fmamk_f32 v6, v90, 0x3dd53b94, v0
	v_add_f32_e32 v5, v118, v5
	v_exp_f32_e32 v122, v6
	v_fmamk_f32 v6, v91, 0x3dd53b94, v0
	v_add_f32_e32 v5, v119, v5
	v_exp_f32_e32 v123, v6
	v_fmamk_f32 v6, v92, 0x3dd53b94, v0
	v_add_f32_e32 v5, v120, v5
	v_exp_f32_e32 v124, v6
	v_fmamk_f32 v6, v93, 0x3dd53b94, v0
	v_add_f32_e32 v5, v121, v5
	v_exp_f32_e32 v125, v6
	v_fmamk_f32 v6, v94, 0x3dd53b94, v0
	v_add_f32_e32 v5, v122, v5
	v_exp_f32_e32 v94, v6
	v_fmamk_f32 v6, v95, 0x3dd53b94, v0
	v_add_f32_e32 v5, v123, v5
	v_exp_f32_e32 v95, v6
	v_fmamk_f32 v6, v96, 0x3dd53b94, v0
	v_add_f32_e32 v5, v124, v5
	v_exp_f32_e32 v13, v6
	v_fmamk_f32 v6, v97, 0x3dd53b94, v0
	v_add_f32_e32 v5, v125, v5
	v_exp_f32_e32 v14, v6
	v_fmamk_f32 v6, v98, 0x3dd53b94, v0
	v_add_f32_e32 v5, v94, v5
	v_exp_f32_e32 v15, v6
	v_fmamk_f32 v6, v99, 0x3dd53b94, v0
	v_add_f32_e32 v5, v95, v5
	v_exp_f32_e32 v80, v6
	v_fmamk_f32 v6, v100, 0x3dd53b94, v0
	v_add_f32_e32 v5, v13, v5
	v_exp_f32_e32 v81, v6
	v_fmamk_f32 v6, v101, 0x3dd53b94, v0
	v_add_f32_e32 v5, v14, v5
	v_exp_f32_e32 v82, v6
	v_fmamk_f32 v6, v102, 0x3dd53b94, v0
	v_add_f32_e32 v5, v15, v5
	v_exp_f32_e32 v83, v6
	v_fmamk_f32 v6, v103, 0x3dd53b94, v0
	v_add_f32_e32 v5, v80, v5
	v_exp_f32_e32 v84, v6
	v_add_f32_e32 v5, v81, v5
	v_add_f32_e32 v5, v82, v5
	v_add_f32_e32 v5, v83, v5
	v_add_f32_e32 v6, v84, v5
	v_fmamk_f32 v5, v104, 0x3dd53b94, v0
	v_exp_f32_e32 v5, v5
	s_nop 0
	v_add_f32_e32 v7, v5, v6
	v_fmamk_f32 v6, v105, 0x3dd53b94, v0
	v_exp_f32_e32 v6, v6
	s_nop 0
	v_add_f32_e32 v8, v6, v7
	v_fmamk_f32 v7, v106, 0x3dd53b94, v0
	v_exp_f32_e32 v7, v7
	s_nop 0
	v_add_f32_e32 v9, v7, v8
	v_fmamk_f32 v8, v107, 0x3dd53b94, v0
	v_exp_f32_e32 v8, v8
	s_nop 0
	v_add_f32_e32 v10, v8, v9
	v_fmamk_f32 v9, v108, 0x3dd53b94, v0
	v_exp_f32_e32 v9, v9
	s_nop 0
	v_add_f32_e32 v11, v9, v10
	v_fmamk_f32 v10, v109, 0x3dd53b94, v0
	v_exp_f32_e32 v10, v10
	s_nop 0
	v_add_f32_e32 v12, v10, v11
	v_fmamk_f32 v11, v110, 0x3dd53b94, v0
	v_exp_f32_e32 v11, v11
	v_fmac_f32_e32 v0, 0x3dd53b94, v111
	v_add_f32_e32 v86, v11, v12
	v_exp_f32_e32 v12, v0
	s_nop 0
	v_add_f32_e32 v0, v12, v86
	v_cvt_pk_bf16_f32 v86, v113, v114
	v_cvt_pk_bf16_f32 v87, v115, v116
	v_cvt_pk_bf16_f32 v88, v117, v85
	v_cvt_pk_bf16_f32 v89, v118, v119
	s_nop 1
	v_add_u32_e32 v85, v211, v212
	ds_read_b128 v[96:99], v85 offset:25600
	ds_read_b128 v[100:103], v85 offset:30208
	ds_read_b128 v[114:117], v85 offset:34816
	ds_read_b128 v[126:129], v85 offset:39424
	ds_read_b128 v[130:133], v85 offset:25632
	ds_read_b128 v[134:137], v85 offset:30240
	s_waitcnt lgkmcnt(5)
	v_mfma_f32_32x32x16_bf16 v[64:79], v[96:99], v[86:89], v[64:79]
	ds_read_b128 v[96:99], v85 offset:34848
	v_add_f32_e32 v0, v0, v112
	s_waitcnt lgkmcnt(5)
	v_mfma_f32_32x32x16_bf16 v[48:63], v[100:103], v[86:89], v[48:63]
	ds_read_b128 v[100:103], v85 offset:39456
	s_waitcnt lgkmcnt(5)
	v_mfma_f32_32x32x16_bf16 v[32:47], v[114:117], v[86:89], v[32:47]
	ds_read_b128 v[114:117], v85 offset:25664
	s_waitcnt lgkmcnt(5)
	v_mfma_f32_32x32x16_bf16 v[16:31], v[126:129], v[86:89], v[16:31]
	ds_read_b128 v[126:129], v85 offset:30272
	v_cvt_pk_bf16_f32 v86, v120, v121
	v_cvt_pk_bf16_f32 v87, v122, v123
	v_cvt_pk_bf16_f32 v88, v124, v125
	v_cvt_pk_bf16_f32 v89, v94, v95
	s_nop 1
	s_waitcnt lgkmcnt(5)
	v_mfma_f32_32x32x16_bf16 v[64:79], v[130:133], v[86:89], v[64:79]
	ds_read_b128 v[130:133], v85 offset:34880
	s_waitcnt lgkmcnt(5)
	v_mfma_f32_32x32x16_bf16 v[48:63], v[134:137], v[86:89], v[48:63]
	ds_read_b128 v[134:137], v85 offset:39488
	s_waitcnt lgkmcnt(5)
	v_mfma_f32_32x32x16_bf16 v[32:47], v[96:99], v[86:89], v[32:47]
	ds_read_b128 v[96:99], v85 offset:25696
	s_waitcnt lgkmcnt(5)
	v_mfma_f32_32x32x16_bf16 v[16:31], v[100:103], v[86:89], v[16:31]
	ds_read_b128 v[100:103], v85 offset:30304
	v_cvt_pk_bf16_f32 v86, v13, v14
	v_cvt_pk_bf16_f32 v87, v15, v80
	v_cvt_pk_bf16_f32 v88, v81, v82
	v_cvt_pk_bf16_f32 v89, v83, v84
	s_nop 1
	s_waitcnt lgkmcnt(5)
	v_mfma_f32_32x32x16_bf16 v[64:79], v[114:117], v[86:89], v[64:79]
	ds_read_b128 v[114:117], v85 offset:34912
	s_waitcnt lgkmcnt(5)
	v_mfma_f32_32x32x16_bf16 v[48:63], v[126:129], v[86:89], v[48:63]
	ds_read_b128 v[126:129], v85 offset:39520
	s_waitcnt lgkmcnt(5)
	v_mfma_f32_32x32x16_bf16 v[32:47], v[130:133], v[86:89], v[32:47]
	s_waitcnt lgkmcnt(4)
	v_mfma_f32_32x32x16_bf16 v[16:31], v[134:137], v[86:89], v[16:31]
	v_cvt_pk_bf16_f32 v80, v5, v6
	v_cvt_pk_bf16_f32 v81, v7, v8
	v_cvt_pk_bf16_f32 v82, v9, v10
	v_cvt_pk_bf16_f32 v83, v11, v12
	s_nop 1
	s_waitcnt lgkmcnt(3)
	v_mfma_f32_32x32x16_bf16 v[64:79], v[96:99], v[80:83], v[64:79]
	s_waitcnt lgkmcnt(2)
	v_mfma_f32_32x32x16_bf16 v[48:63], v[100:103], v[80:83], v[48:63]
	s_waitcnt lgkmcnt(1)
	v_mfma_f32_32x32x16_bf16 v[32:47], v[114:117], v[80:83], v[32:47]
	s_waitcnt lgkmcnt(0)
	v_mfma_f32_32x32x16_bf16 v[16:31], v[126:129], v[80:83], v[16:31]

; #define MFMA32(a, b, c) __builtin_amdgcn_mfma_f32_32x32x16_bf16((a), (b), (c), 0, 0, 0)
; template <int DQK, int MODE>
; DI void attn_core(const u16* __restrict__ Qg, int ldq, const u16* __restrict__ Kg, int ldk, const u16* __restrict__ Vtg,
;                   const u64* __restrict__ maskg, int q0, float scale, char* smem, int* sflags, f32x16 (&o)[4], float& l_run) {
;     ...
;       const float msc = -m_new * sc;
;       float ls = 0.f;
; #pragma unroll
;       for (int kt = 0; kt < 2; ++kt)
; #pragma unroll
;         for (int i = 0; i < 16; ++i) {
;           float pv = __builtin_amdgcn_exp2f(__builtin_fmaf(s[kt][i], sc, msc));
;           if (MODE == 1) pv = (s[kt][i] > -1e29f) ? pv : 0.f;
;           s[kt][i] = pv;
;           ls += pv;
;         }
;     ...
; #pragma unroll
;     for (int kt = 0; kt < 2; ++kt)
; #pragma unroll
;       for (int sb = 0; sb < 2; ++sb) {
;         const bf16x8 pf = pack8(s[kt][8 * sb + 0], s[kt][8 * sb + 1], s[kt][8 * sb + 2], s[kt][8 * sb + 3],
;                                 s[kt][8 * sb + 4], s[kt][8 * sb + 5], s[kt][8 * sb + 6], s[kt][8 * sb + 7]);
; #pragma unroll
;         for (int t = 0; t < 4; ++t) {
;           const bf16x8 vf = *(const bf16x8*)(Vs + (32 * t + l31) * 72 + 32 * kt + 16 * sb + hh * 8);
;           o[t] = MFMA32(vf, pf, o[t]);
;         }
;       }
.LBB0_200:
	v_mul_f32_e32 v8, 0xbe38aa3b, v2
	v_fmamk_f32 v0, v96, 0x3e38aa3b, v8
	v_exp_f32_e32 v96, v0
	v_fmamk_f32 v2, v97, 0x3e38aa3b, v8
	v_exp_f32_e32 v97, v2
	v_fmamk_f32 v2, v98, 0x3e38aa3b, v8
	v_exp_f32_e32 v98, v2
	v_fmamk_f32 v2, v99, 0x3e38aa3b, v8
	v_exp_f32_e32 v99, v2
	v_fmamk_f32 v2, v100, 0x3e38aa3b, v8
	v_add_f32_e32 v0, 0, v96
	v_exp_f32_e32 v100, v2
	v_fmamk_f32 v2, v101, 0x3e38aa3b, v8
	v_add_f32_e32 v0, v97, v0
	v_exp_f32_e32 v101, v2
	v_fmamk_f32 v2, v102, 0x3e38aa3b, v8
	v_add_f32_e32 v0, v98, v0
	v_exp_f32_e32 v102, v2
	v_fmamk_f32 v2, v103, 0x3e38aa3b, v8
	v_add_f32_e32 v0, v99, v0
	v_exp_f32_e32 v103, v2
	v_fmamk_f32 v2, v104, 0x3e38aa3b, v8
	v_add_f32_e32 v0, v100, v0
	v_exp_f32_e32 v104, v2
	v_fmamk_f32 v2, v105, 0x3e38aa3b, v8
	v_add_f32_e32 v0, v101, v0
	v_exp_f32_e32 v105, v2
	v_fmamk_f32 v2, v106, 0x3e38aa3b, v8
	v_add_f32_e32 v0, v102, v0
	v_exp_f32_e32 v106, v2
	v_fmamk_f32 v2, v107, 0x3e38aa3b, v8
	v_add_f32_e32 v0, v103, v0
	v_exp_f32_e32 v107, v2
	v_fmamk_f32 v2, v108, 0x3e38aa3b, v8
	v_add_f32_e32 v0, v104, v0
	v_exp_f32_e32 v108, v2
	v_fmamk_f32 v2, v109, 0x3e38aa3b, v8
	v_add_f32_e32 v0, v105, v0
	v_exp_f32_e32 v109, v2
	v_fmamk_f32 v2, v110, 0x3e38aa3b, v8
	v_add_f32_e32 v0, v106, v0
	v_exp_f32_e32 v110, v2
	v_fmamk_f32 v2, v111, 0x3e38aa3b, v8
	v_add_f32_e32 v0, v107, v0
	v_exp_f32_e32 v111, v2
	v_fmamk_f32 v2, v80, 0x3e38aa3b, v8
	v_add_f32_e32 v0, v108, v0
	v_exp_f32_e32 v9, v2
	v_fmamk_f32 v2, v81, 0x3e38aa3b, v8
	v_add_f32_e32 v0, v109, v0
	v_exp_f32_e32 v10, v2
	v_fmamk_f32 v2, v82, 0x3e38aa3b, v8
	v_add_f32_e32 v0, v110, v0
	v_exp_f32_e32 v11, v2
	v_fmamk_f32 v2, v83, 0x3e38aa3b, v8
	v_add_f32_e32 v0, v111, v0
	v_exp_f32_e32 v12, v2
	v_fmamk_f32 v2, v84, 0x3e38aa3b, v8
	v_add_f32_e32 v0, v9, v0
	v_exp_f32_e32 v13, v2
	v_fmamk_f32 v2, v85, 0x3e38aa3b, v8
	v_add_f32_e32 v0, v10, v0
	v_exp_f32_e32 v14, v2
	v_fmamk_f32 v2, v86, 0x3e38aa3b, v8
	v_add_f32_e32 v0, v11, v0
	v_exp_f32_e32 v15, v2
	v_fmamk_f32 v2, v87, 0x3e38aa3b, v8
	v_add_f32_e32 v0, v12, v0
	v_exp_f32_e32 v80, v2
	v_add_f32_e32 v0, v13, v0
	v_add_f32_e32 v0, v14, v0
	v_add_f32_e32 v0, v15, v0
	v_add_f32_e32 v2, v80, v0
	v_fmamk_f32 v0, v88, 0x3e38aa3b, v8
	v_exp_f32_e32 v0, v0
	v_cvt_pk_bf16_f32 v82, v96, v97
	v_cvt_pk_bf16_f32 v83, v98, v99
	v_cvt_pk_bf16_f32 v84, v100, v101
	v_cvt_pk_bf16_f32 v85, v102, v103
	s_nop 1
	s_nop 0
	v_add_f32_e32 v3, v0, v2
	v_fmamk_f32 v2, v89, 0x3e38aa3b, v8
	v_exp_f32_e32 v2, v2
	s_nop 0
	v_add_f32_e32 v4, v2, v3
	v_fmamk_f32 v3, v90, 0x3e38aa3b, v8
	v_exp_f32_e32 v3, v3
	s_nop 0
	v_add_f32_e32 v5, v3, v4
	v_fmamk_f32 v4, v91, 0x3e38aa3b, v8
	v_exp_f32_e32 v4, v4
	s_nop 0
	v_add_f32_e32 v6, v4, v5
	v_fmamk_f32 v5, v92, 0x3e38aa3b, v8
	v_exp_f32_e32 v5, v5
	s_nop 0
	v_add_f32_e32 v7, v5, v6
	v_fmamk_f32 v6, v93, 0x3e38aa3b, v8
	v_exp_f32_e32 v6, v6
	s_nop 0
	v_add_f32_e32 v81, v6, v7
	v_fmamk_f32 v7, v94, 0x3e38aa3b, v8
	v_exp_f32_e32 v7, v7
	v_fmac_f32_e32 v8, 0x3e38aa3b, v95
	v_exp_f32_e32 v8, v8
	v_add_f32_e32 v81, v7, v81
	v_add_f32_e32 v81, v8, v81
	v_add_f32_e32 v143, v81, v143
	v_add_u32_e32 v81, v142, v152
	ds_read_b128 v[90:93], v81 offset:9216
	ds_read_b128 v[94:97], v81 offset:13824
	ds_read_b128 v[98:101], v81 offset:18432
	ds_read_b128 v[112:115], v81 offset:23040
	ds_read_b128 v[116:119], v81 offset:9248
	ds_read_b128 v[120:123], v81 offset:13856
	s_waitcnt lgkmcnt(5)
	v_mfma_f32_32x32x16_bf16 v[64:79], v[90:93], v[82:85], v[64:79]
	ds_read_b128 v[90:93], v81 offset:18464
	s_waitcnt lgkmcnt(5)
	v_mfma_f32_32x32x16_bf16 v[48:63], v[94:97], v[82:85], v[48:63]
	ds_read_b128 v[94:97], v81 offset:23072
	s_waitcnt lgkmcnt(5)
	v_mfma_f32_32x32x16_bf16 v[32:47], v[98:101], v[82:85], v[32:47]
	ds_read_b128 v[98:101], v81 offset:9280
	s_waitcnt lgkmcnt(5)
	v_mfma_f32_32x32x16_bf16 v[16:31], v[112:115], v[82:85], v[16:31]
	ds_read_b128 v[112:115], v81 offset:13888
	v_cvt_pk_bf16_f32 v82, v104, v105
	v_cvt_pk_bf16_f32 v83, v106, v107
	v_cvt_pk_bf16_f32 v84, v108, v109
	v_cvt_pk_bf16_f32 v85, v110, v111
	s_nop 1
	s_waitcnt lgkmcnt(5)
	v_mfma_f32_32x32x16_bf16 v[64:79], v[116:119], v[82:85], v[64:79]
	ds_read_b128 v[116:119], v81 offset:18496
	s_waitcnt lgkmcnt(5)
	v_mfma_f32_32x32x16_bf16 v[48:63], v[120:123], v[82:85], v[48:63]
	ds_read_b128 v[120:123], v81 offset:23104
	s_waitcnt lgkmcnt(5)
	v_mfma_f32_32x32x16_bf16 v[32:47], v[90:93], v[82:85], v[32:47]
	ds_read_b128 v[90:93], v81 offset:9312
	s_waitcnt lgkmcnt(5)
	v_mfma_f32_32x32x16_bf16 v[16:31], v[94:97], v[82:85], v[16:31]
	ds_read_b128 v[94:97], v81 offset:13920
	v_cvt_pk_bf16_f32 v82, v9, v10
	v_cvt_pk_bf16_f32 v83, v11, v12
	v_cvt_pk_bf16_f32 v84, v13, v14
	v_cvt_pk_bf16_f32 v85, v15, v80
	s_nop 1
	s_waitcnt lgkmcnt(5)
	v_mfma_f32_32x32x16_bf16 v[64:79], v[98:101], v[82:85], v[64:79]
	ds_read_b128 v[98:101], v81 offset:18528
	s_waitcnt lgkmcnt(5)
	v_mfma_f32_32x32x16_bf16 v[48:63], v[112:115], v[82:85], v[48:63]
	ds_read_b128 v[112:115], v81 offset:23136
	s_waitcnt lgkmcnt(5)
	v_mfma_f32_32x32x16_bf16 v[32:47], v[116:119], v[82:85], v[32:47]
	s_waitcnt lgkmcnt(4)
	v_mfma_f32_32x32x16_bf16 v[16:31], v[120:123], v[82:85], v[16:31]
	v_cvt_pk_bf16_f32 v10, v0, v2
	v_cvt_pk_bf16_f32 v11, v3, v4
	v_cvt_pk_bf16_f32 v12, v5, v6
	v_cvt_pk_bf16_f32 v13, v7, v8
	s_nop 1
	s_waitcnt lgkmcnt(3)
	v_mfma_f32_32x32x16_bf16 v[64:79], v[90:93], v[10:13], v[64:79]
	s_waitcnt lgkmcnt(2)
	v_mfma_f32_32x32x16_bf16 v[48:63], v[94:97], v[10:13], v[48:63]
	s_waitcnt lgkmcnt(1)
	v_mfma_f32_32x32x16_bf16 v[32:47], v[98:101], v[10:13], v[32:47]
	s_waitcnt lgkmcnt(0)
	v_mfma_f32_32x32x16_bf16 v[16:31], v[112:115], v[10:13], v[16:31]

; #define MFMA32(a, b, c) __builtin_amdgcn_mfma_f32_32x32x16_bf16((a), (b), (c), 0, 0, 0)
; DI f32x16 zero16() { f32x16 z; for (int i = 0; i < 16; ++i) z[i] = 0.f; return z; }
; template <int DQK, int MODE>
; DI void attn_core(const u16* __restrict__ Qg, int ldq, const u16* __restrict__ Kg, int ldk, const u16* __restrict__ Vtg,
;                   const u64* __restrict__ maskg, int q0, float scale, char* smem, int* sflags, f32x16 (&o)[4], float& l_run) {
;     ...
;   for (int it = 0; it < ntiles; ++it, tau += step) {
;     __syncthreads();
;     if (MODE == 2 && it > 0) {
;       if (!(sflags[0] | sflags[1] | sflags[2] | sflags[3] | sflags[4] | sflags[5] | sflags[6] | sflags[7])) break;
;     }
;     if (MODE == 2) gload(tau);
; #pragma unroll
;     for (int i = 0; i < NVK; ++i) {
;       const int v = tid + NT * i, row = v / VPR, c = v % VPR;
;       *(u32x4*)(Ks + row * KSTR + c * 8) = rk[i];
;     }
; #pragma unroll
;     for (int i = 0; i < 2; ++i) {
;       const int v = tid + NT * i, row = v >> 3, c = v & 7;
;       *(u32x4*)(Vs + row * 72 + c * 8) = rv[i];
;     }
;     __syncthreads();
;     if (MODE != 2 && it + 1 < ntiles) gload(tau + step);
;     if (tau * 64 > q0 + 32 * wid + 31) {
;       if (MODE == 2 && lane == 0) sflags[wid] = 1;
;       continue;
;     }
;     u64 mbits = 0;
;     if (MODE == 1) mbits = maskg[(long)qrow * 64 + tau] >> (8 * hh);
;     f32x16 s[2];
;     s[0] = zero16(); s[1] = zero16();
; #pragma unroll
;     for (int kt = 0; kt < 2; ++kt)
; #pragma unroll
;       for (int ks = 0; ks < NKS; ++ks) {
;         const bf16x8 kf = *(const bf16x8*)(Ks + (32 * kt + krow) * KSTR + ks * 16 + hh * 8);
;         s[kt] = MFMA32(kf, qf[ks], s[kt]);
;       }
;     const int kbase = tau * 64 + 8 * hh;
;     if (MODE == 0 || MODE == 1) {
;       const bool need_mask = (MODE == 1) || (tau * 64 + 63 > q0 + 32 * wid);
;       float mx = -1e30f;
;       if (need_mask) {
; #pragma unroll
;         for (int kt = 0; kt < 2; ++kt)
; #pragma unroll
;           for (int i = 0; i < 16; ++i) {
;             bool valid;
;             if (MODE == 1) valid = (mbits >> (32 * kt + 16 * (i >> 3) + (i & 7))) & 1ull;
;             else valid = (kbase + 32 * kt + 16 * (i >> 3) + (i & 7)) <= qrow;
;             s[kt][i] = valid ? s[kt][i] : -1e30f;
;           }
.LBB0_240:
	s_add_i32 s4, s15, 64
	v_add_u32_e32 v0, s15, v156
	v_mad_i64_i32 v[2:3], s[6:7], v0, s75, v[146:147]
	s_ashr_i32 s5, s4, 31
	s_lshl_b64 s[6:7], s[4:5], 1
	s_waitcnt lgkmcnt(0)
	s_barrier
	s_waitcnt vmcnt(0)
	ds_write_b128 v157, v[128:131]
	ds_write_b128 v158, v[136:139] offset:9216
	ds_write_b128 v159, v[132:135] offset:9216
	s_waitcnt lgkmcnt(0)
	s_barrier
	global_load_dwordx4 v[128:131], v[2:3], off offset:1024
	v_lshl_add_u64 v[2:3], v[142:143], 0, s[6:7]
	v_lshl_add_u64 v[4:5], v[144:145], 0, s[6:7]
	global_load_dwordx4 v[136:139], v[2:3], off
	global_load_dwordx4 v[132:135], v[4:5], off
	v_cmp_le_i32_e32 vcc, s15, v155
	s_and_saveexec_b64 s[6:7], vcc
	s_cbranch_execz .LBB0_246
	v_add_u32_e32 v0, v149, v154
	ds_read_b128 v[10:13], v0
	ds_read_b128 v[162:165], v0 offset:32
	ds_read_b128 v[166:169], v0 offset:64
	ds_read_b128 v[170:173], v0 offset:96
	ds_read_b128 v[174:177], v0 offset:4608
	ds_read_b128 v[178:181], v0 offset:4640
	s_add_i32 s5, s15, 63
	v_cmp_gt_i32_e32 vcc, s5, v152
	s_waitcnt lgkmcnt(5)
	v_mfma_f32_32x32x16_bf16 v[96:111], v[10:13], v[124:127], 0
	ds_read_b128 v[10:13], v0 offset:4672
	s_waitcnt lgkmcnt(5)
	v_mfma_f32_32x32x16_bf16 v[96:111], v[162:165], v[120:123], v[96:111]
	ds_read_b128 v[162:165], v0 offset:4704
	s_waitcnt lgkmcnt(5)
	v_mfma_f32_32x32x16_bf16 v[96:111], v[166:169], v[116:119], v[96:111]
	s_waitcnt lgkmcnt(4)
	v_mfma_f32_32x32x16_bf16 v[96:111], v[170:173], v[112:115], v[96:111]
	s_waitcnt lgkmcnt(3)
	v_mfma_f32_32x32x16_bf16 v[80:95], v[174:177], v[124:127], 0
	s_waitcnt lgkmcnt(2)
	v_mfma_f32_32x32x16_bf16 v[80:95], v[178:181], v[120:123], v[80:95]
	s_waitcnt lgkmcnt(1)
	v_mfma_f32_32x32x16_bf16 v[80:95], v[10:13], v[116:119], v[80:95]
	s_waitcnt lgkmcnt(0)
	v_mfma_f32_32x32x16_bf16 v[80:95], v[162:165], v[112:115], v[80:95]
	s_and_saveexec_b64 s[8:9], vcc
	s_cbranch_execz .LBB0_243
	v_add_u32_e32 v0, s15, v153
	v_cmp_le_i32_e32 vcc, v0, v151
	v_add_u32_e32 v2, 2, v0
	s_nop 0
	v_cndmask_b32_e32 v96, v225, v96, vcc
	v_cmp_lt_i32_e32 vcc, v0, v151
	s_nop 1
	v_cndmask_b32_e32 v97, v225, v97, vcc
	v_cmp_le_i32_e32 vcc, v2, v151
	v_add_u32_e32 v2, 3, v0
	s_nop 0
	v_cndmask_b32_e32 v98, v225, v98, vcc
	v_cmp_le_i32_e32 vcc, v2, v151
	v_add_u32_e32 v2, 4, v0
	s_nop 0
	v_cndmask_b32_e32 v99, v225, v99, vcc
	v_cmp_le_i32_e32 vcc, v2, v151
	v_add_u32_e32 v2, 5, v0
	s_nop 0
	v_cndmask_b32_e32 v100, v225, v100, vcc
	v_cmp_le_i32_e32 vcc, v2, v151
	v_add_u32_e32 v2, 6, v0
	s_nop 0
	v_cndmask_b32_e32 v101, v225, v101, vcc
	v_cmp_le_i32_e32 vcc, v2, v151
	v_add_u32_e32 v2, 7, v0
	s_nop 0
	v_cndmask_b32_e32 v102, v225, v102, vcc
	v_cmp_le_i32_e32 vcc, v2, v151
	v_add_u32_e32 v2, 16, v0
	s_nop 0
	v_cndmask_b32_e32 v103, v225, v103, vcc
	v_cmp_le_i32_e32 vcc, v2, v151
	v_add_u32_e32 v2, 17, v0
	s_nop 0
	v_cndmask_b32_e32 v104, v225, v104, vcc
	v_cmp_le_i32_e32 vcc, v2, v151
	v_add_u32_e32 v2, 18, v0
	s_nop 0
	v_cndmask_b32_e32 v105, v225, v105, vcc
	v_cmp_le_i32_e32 vcc, v2, v151
	v_add_u32_e32 v2, 19, v0
	s_nop 0
	v_cndmask_b32_e32 v106, v225, v106, vcc
	v_cmp_le_i32_e32 vcc, v2, v151
	v_add_u32_e32 v2, 20, v0
	s_nop 0
	v_cndmask_b32_e32 v107, v225, v107, vcc
	v_cmp_le_i32_e32 vcc, v2, v151
	v_add_u32_e32 v2, 21, v0
	s_nop 0
	v_cndmask_b32_e32 v108, v225, v108, vcc
	v_cmp_le_i32_e32 vcc, v2, v151
	v_add_u32_e32 v2, 22, v0
	s_nop 0
	v_cndmask_b32_e32 v109, v225, v109, vcc
	v_cmp_le_i32_e32 vcc, v2, v151
	v_add_u32_e32 v2, 23, v0
	s_nop 0
	v_cndmask_b32_e32 v110, v225, v110, vcc
	v_cmp_le_i32_e32 vcc, v2, v151
	v_add_u32_e32 v2, 32, v0
	s_nop 0
	v_cndmask_b32_e32 v111, v225, v111, vcc
	v_cmp_le_i32_e32 vcc, v2, v151
	v_add_u32_e32 v2, 33, v0
	s_nop 0
	v_cndmask_b32_e32 v80, v225, v80, vcc
	v_cmp_le_i32_e32 vcc, v2, v151
	v_add_u32_e32 v2, 34, v0
	s_nop 0
	v_cndmask_b32_e32 v81, v225, v81, vcc
	v_cmp_le_i32_e32 vcc, v2, v151
	v_add_u32_e32 v2, 35, v0
	s_nop 0
	v_cndmask_b32_e32 v82, v225, v82, vcc
	v_cmp_le_i32_e32 vcc, v2, v151
	v_add_u32_e32 v2, 36, v0
	s_nop 0
	v_cndmask_b32_e32 v83, v225, v83, vcc
	v_cmp_le_i32_e32 vcc, v2, v151
	v_add_u32_e32 v2, 37, v0
	s_nop 0
	v_cndmask_b32_e32 v84, v225, v84, vcc
	v_cmp_le_i32_e32 vcc, v2, v151
	v_add_u32_e32 v2, 38, v0
	s_nop 0
	v_cndmask_b32_e32 v85, v225, v85, vcc
	v_cmp_le_i32_e32 vcc, v2, v151
	v_add_u32_e32 v2, 39, v0
	s_nop 0
	v_cndmask_b32_e32 v86, v225, v86, vcc
	v_cmp_le_i32_e32 vcc, v2, v151
	v_add_u32_e32 v2, 48, v0
	s_nop 0
	v_cndmask_b32_e32 v87, v225, v87, vcc
	v_cmp_le_i32_e32 vcc, v2, v151
	v_add_u32_e32 v2, 49, v0
	s_nop 0
	v_cndmask_b32_e32 v88, v225, v88, vcc
	v_cmp_le_i32_e32 vcc, v2, v151
	v_add_u32_e32 v2, 50, v0
	s_nop 0
	v_cndmask_b32_e32 v89, v225, v89, vcc
	v_cmp_le_i32_e32 vcc, v2, v151
	v_add_u32_e32 v2, 51, v0
	s_nop 0
	v_cndmask_b32_e32 v90, v225, v90, vcc
	v_cmp_le_i32_e32 vcc, v2, v151
	v_add_u32_e32 v2, 52, v0
	s_nop 0
	v_cndmask_b32_e32 v91, v225, v91, vcc
	v_cmp_le_i32_e32 vcc, v2, v151
	v_add_u32_e32 v2, 53, v0
	s_nop 0
	v_cndmask_b32_e32 v92, v225, v92, vcc
	v_cmp_le_i32_e32 vcc, v2, v151
	v_add_u32_e32 v2, 54, v0
	v_add_u32_e32 v0, 55, v0
	v_cndmask_b32_e32 v93, v225, v93, vcc
	v_cmp_le_i32_e32 vcc, v2, v151
	s_nop 1
	v_cndmask_b32_e32 v94, v225, v94, vcc
	v_cmp_le_i32_e32 vcc, v0, v151
	s_nop 1
	v_cndmask_b32_e32 v95, v225, v95, vcc

; #define MFMA32(a, b, c) __builtin_amdgcn_mfma_f32_32x32x16_bf16((a), (b), (c), 0, 0, 0)
; template <int DQK, int MODE>
; DI void attn_core(const u16* __restrict__ Qg, int ldq, const u16* __restrict__ Kg, int ldk, const u16* __restrict__ Vtg,
;                   const u64* __restrict__ maskg, int q0, float scale, char* smem, int* sflags, f32x16 (&o)[4], float& l_run) {
;     ...
;       const float msc = -m_new * sc;
;       float ls = 0.f;
; #pragma unroll
;       for (int kt = 0; kt < 2; ++kt)
; #pragma unroll
;         for (int i = 0; i < 16; ++i) {
;           float pv = __builtin_amdgcn_exp2f(__builtin_fmaf(s[kt][i], sc, msc));
;           if (MODE == 1) pv = (s[kt][i] > -1e29f) ? pv : 0.f;
;           s[kt][i] = pv;
;           ls += pv;
;         }
;     ...
; #pragma unroll
;     for (int kt = 0; kt < 2; ++kt)
; #pragma unroll
;       for (int sb = 0; sb < 2; ++sb) {
;         const bf16x8 pf = pack8(s[kt][8 * sb + 0], s[kt][8 * sb + 1], s[kt][8 * sb + 2], s[kt][8 * sb + 3],
;                                 s[kt][8 * sb + 4], s[kt][8 * sb + 5], s[kt][8 * sb + 6], s[kt][8 * sb + 7]);
; #pragma unroll
;         for (int t = 0; t < 4; ++t) {
;           const bf16x8 vf = *(const bf16x8*)(Vs + (32 * t + l31) * 72 + 32 * kt + 16 * sb + hh * 8);
;           o[t] = MFMA32(vf, pf, o[t]);
;         }
;       }
.LBB0_245:
	v_mul_f32_e32 v9, 0xbe38aa3b, v2
	v_fmamk_f32 v0, v96, 0x3e38aa3b, v9
	v_exp_f32_e32 v96, v0
	v_fmamk_f32 v3, v97, 0x3e38aa3b, v9
	v_exp_f32_e32 v97, v3
	v_fmamk_f32 v3, v98, 0x3e38aa3b, v9
	v_exp_f32_e32 v98, v3
	v_fmamk_f32 v3, v99, 0x3e38aa3b, v9
	v_exp_f32_e32 v99, v3
	v_fmamk_f32 v3, v100, 0x3e38aa3b, v9
	v_add_f32_e32 v0, 0, v96
	v_exp_f32_e32 v100, v3
	v_fmamk_f32 v3, v101, 0x3e38aa3b, v9
	v_add_f32_e32 v0, v97, v0
	v_exp_f32_e32 v101, v3
	v_fmamk_f32 v3, v102, 0x3e38aa3b, v9
	v_add_f32_e32 v0, v98, v0
	v_exp_f32_e32 v102, v3
	v_fmamk_f32 v3, v103, 0x3e38aa3b, v9
	v_add_f32_e32 v0, v99, v0
	v_exp_f32_e32 v103, v3
	v_fmamk_f32 v3, v104, 0x3e38aa3b, v9
	v_add_f32_e32 v0, v100, v0
	v_exp_f32_e32 v104, v3
	v_fmamk_f32 v3, v105, 0x3e38aa3b, v9
	v_add_f32_e32 v0, v101, v0
	v_exp_f32_e32 v105, v3
	v_fmamk_f32 v3, v106, 0x3e38aa3b, v9
	v_add_f32_e32 v0, v102, v0
	v_exp_f32_e32 v106, v3
	v_fmamk_f32 v3, v107, 0x3e38aa3b, v9
	v_add_f32_e32 v0, v103, v0
	v_exp_f32_e32 v107, v3
	v_fmamk_f32 v3, v108, 0x3e38aa3b, v9
	v_add_f32_e32 v0, v104, v0
	v_exp_f32_e32 v108, v3
	v_fmamk_f32 v3, v109, 0x3e38aa3b, v9
	v_add_f32_e32 v0, v105, v0
	v_exp_f32_e32 v109, v3
	v_fmamk_f32 v3, v110, 0x3e38aa3b, v9
	v_add_f32_e32 v0, v106, v0
	v_exp_f32_e32 v110, v3
	v_fmamk_f32 v3, v111, 0x3e38aa3b, v9
	v_add_f32_e32 v0, v107, v0
	v_exp_f32_e32 v111, v3
	v_fmamk_f32 v3, v80, 0x3e38aa3b, v9
	v_add_f32_e32 v0, v108, v0
	v_exp_f32_e32 v10, v3
	v_fmamk_f32 v3, v81, 0x3e38aa3b, v9
	v_add_f32_e32 v0, v109, v0
	v_exp_f32_e32 v11, v3
	v_fmamk_f32 v3, v82, 0x3e38aa3b, v9
	v_add_f32_e32 v0, v110, v0
	v_exp_f32_e32 v12, v3
	v_fmamk_f32 v3, v83, 0x3e38aa3b, v9
	v_add_f32_e32 v0, v111, v0
	v_exp_f32_e32 v13, v3
	v_fmamk_f32 v3, v84, 0x3e38aa3b, v9
	v_add_f32_e32 v0, v10, v0
	v_exp_f32_e32 v14, v3
	v_fmamk_f32 v3, v85, 0x3e38aa3b, v9
	v_add_f32_e32 v0, v11, v0
	v_exp_f32_e32 v15, v3
	v_fmamk_f32 v3, v86, 0x3e38aa3b, v9
	v_add_f32_e32 v0, v12, v0
	v_exp_f32_e32 v80, v3
	v_fmamk_f32 v3, v87, 0x3e38aa3b, v9
	v_add_f32_e32 v0, v13, v0
	v_exp_f32_e32 v81, v3
	v_add_f32_e32 v0, v14, v0
	v_add_f32_e32 v0, v15, v0
	v_add_f32_e32 v0, v80, v0
	v_add_f32_e32 v3, v81, v0
	v_fmamk_f32 v0, v88, 0x3e38aa3b, v9
	v_exp_f32_e32 v0, v0
	v_mov_b32_e32 v160, v2
	v_add_f32_e32 v4, v0, v3
	v_fmamk_f32 v3, v89, 0x3e38aa3b, v9
	v_exp_f32_e32 v3, v3
	s_nop 0
	v_add_f32_e32 v5, v3, v4
	v_fmamk_f32 v4, v90, 0x3e38aa3b, v9
	v_exp_f32_e32 v4, v4
	v_add_u32_e32 v90, v149, v150
	v_add_f32_e32 v6, v4, v5
	v_fmamk_f32 v5, v91, 0x3e38aa3b, v9
	v_exp_f32_e32 v5, v5
	s_nop 0
	v_add_f32_e32 v7, v5, v6
	v_fmamk_f32 v6, v92, 0x3e38aa3b, v9
	v_exp_f32_e32 v6, v6
	s_nop 0
	v_add_f32_e32 v8, v6, v7
	v_fmamk_f32 v7, v93, 0x3e38aa3b, v9
	v_exp_f32_e32 v7, v7
	s_nop 0
	v_add_f32_e32 v82, v7, v8
	v_fmamk_f32 v8, v94, 0x3e38aa3b, v9
	v_exp_f32_e32 v8, v8
	v_fmac_f32_e32 v9, 0x3e38aa3b, v95
	v_exp_f32_e32 v9, v9
	v_add_f32_e32 v82, v8, v82
	v_add_f32_e32 v82, v9, v82
	v_add_f32_e32 v148, v82, v148
	v_cvt_pk_bf16_f32 v82, v96, v97
	v_cvt_pk_bf16_f32 v83, v98, v99
	v_cvt_pk_bf16_f32 v84, v100, v101
	v_cvt_pk_bf16_f32 v85, v102, v103
	s_nop 1
	ds_read_b128 v[92:95], v90 offset:9216
	ds_read_b128 v[96:99], v90 offset:13824
	ds_read_b128 v[100:103], v90 offset:18432
	ds_read_b128 v[162:165], v90 offset:23040
	ds_read_b128 v[166:169], v90 offset:9248
	ds_read_b128 v[170:173], v90 offset:13856
	s_waitcnt lgkmcnt(5)
	v_mfma_f32_32x32x16_bf16 v[64:79], v[92:95], v[82:85], v[64:79]
	ds_read_b128 v[92:95], v90 offset:18464
	s_waitcnt lgkmcnt(5)
	v_mfma_f32_32x32x16_bf16 v[48:63], v[96:99], v[82:85], v[48:63]
	ds_read_b128 v[96:99], v90 offset:23072
	s_waitcnt lgkmcnt(5)
	v_mfma_f32_32x32x16_bf16 v[32:47], v[100:103], v[82:85], v[32:47]
	ds_read_b128 v[100:103], v90 offset:9280
	s_waitcnt lgkmcnt(5)
	v_mfma_f32_32x32x16_bf16 v[16:31], v[162:165], v[82:85], v[16:31]
	ds_read_b128 v[162:165], v90 offset:13888
	v_cvt_pk_bf16_f32 v82, v104, v105
	v_cvt_pk_bf16_f32 v83, v106, v107
	v_cvt_pk_bf16_f32 v84, v108, v109
	v_cvt_pk_bf16_f32 v85, v110, v111
	s_nop 1
	s_waitcnt lgkmcnt(5)
	v_mfma_f32_32x32x16_bf16 v[64:79], v[166:169], v[82:85], v[64:79]
	ds_read_b128 v[166:169], v90 offset:18496
	s_waitcnt lgkmcnt(5)
	v_mfma_f32_32x32x16_bf16 v[48:63], v[170:173], v[82:85], v[48:63]
	ds_read_b128 v[170:173], v90 offset:23104
	s_waitcnt lgkmcnt(5)
	v_mfma_f32_32x32x16_bf16 v[32:47], v[92:95], v[82:85], v[32:47]
	ds_read_b128 v[92:95], v90 offset:9312
	s_waitcnt lgkmcnt(5)
	v_mfma_f32_32x32x16_bf16 v[16:31], v[96:99], v[82:85], v[16:31]
	ds_read_b128 v[96:99], v90 offset:13920
	v_cvt_pk_bf16_f32 v82, v10, v11
	v_cvt_pk_bf16_f32 v83, v12, v13
	v_cvt_pk_bf16_f32 v84, v14, v15
	v_cvt_pk_bf16_f32 v85, v80, v81
	s_nop 1
	s_waitcnt lgkmcnt(5)
	v_mfma_f32_32x32x16_bf16 v[64:79], v[100:103], v[82:85], v[64:79]
	ds_read_b128 v[100:103], v90 offset:18528
	s_waitcnt lgkmcnt(5)
	v_mfma_f32_32x32x16_bf16 v[48:63], v[162:165], v[82:85], v[48:63]
	ds_read_b128 v[162:165], v90 offset:23136
	s_waitcnt lgkmcnt(5)
	v_mfma_f32_32x32x16_bf16 v[32:47], v[166:169], v[82:85], v[32:47]
	s_waitcnt lgkmcnt(4)
	v_mfma_f32_32x32x16_bf16 v[16:31], v[170:173], v[82:85], v[16:31]
	v_cvt_pk_bf16_f32 v10, v0, v3
	v_cvt_pk_bf16_f32 v11, v4, v5
	v_cvt_pk_bf16_f32 v12, v6, v7
	v_cvt_pk_bf16_f32 v13, v8, v9
	s_nop 1
	s_waitcnt lgkmcnt(3)
	v_mfma_f32_32x32x16_bf16 v[64:79], v[92:95], v[10:13], v[64:79]
	s_waitcnt lgkmcnt(2)
	v_mfma_f32_32x32x16_bf16 v[48:63], v[96:99], v[10:13], v[48:63]
	s_waitcnt lgkmcnt(1)
	v_mfma_f32_32x32x16_bf16 v[32:47], v[100:103], v[10:13], v[32:47]
	s_waitcnt lgkmcnt(0)
	v_mfma_f32_32x32x16_bf16 v[16:31], v[162:165], v[10:13], v[16:31]

; #define MFMA32(a, b, c) __builtin_amdgcn_mfma_f32_32x32x16_bf16((a), (b), (c), 0, 0, 0)
; DI f32x16 zero16() { f32x16 z; for (int i = 0; i < 16; ++i) z[i] = 0.f; return z; }
; template <int DQK, int MODE>
; DI void attn_core(const u16* __restrict__ Qg, int ldq, const u16* __restrict__ Kg, int ldk, const u16* __restrict__ Vtg,
;                   const u64* __restrict__ maskg, int q0, float scale, char* smem, int* sflags, f32x16 (&o)[4], float& l_run) {
;     ...
;     __syncthreads();
;     if (MODE == 2 && it > 0) {
;       if (!(sflags[0] | sflags[1] | sflags[2] | sflags[3] | sflags[4] | sflags[5] | sflags[6] | sflags[7])) break;
;     }
;     if (MODE == 2) gload(tau);
; #pragma unroll
;     for (int i = 0; i < NVK; ++i) {
;       const int v = tid + NT * i, row = v / VPR, c = v % VPR;
;       *(u32x4*)(Ks + row * KSTR + c * 8) = rk[i];
;     }
; #pragma unroll
;     for (int i = 0; i < 2; ++i) {
;       const int v = tid + NT * i, row = v >> 3, c = v & 7;
;       *(u32x4*)(Vs + row * 72 + c * 8) = rv[i];
;     }
;     __syncthreads();
;     if (MODE != 2 && it + 1 < ntiles) gload(tau + step);
;     if (tau * 64 > q0 + 32 * wid + 31) {
;       if (MODE == 2 && lane == 0) sflags[wid] = 1;
;       continue;
;     }
;     u64 mbits = 0;
;     if (MODE == 1) mbits = maskg[(long)qrow * 64 + tau] >> (8 * hh);
;     f32x16 s[2];
;     s[0] = zero16(); s[1] = zero16();
; #pragma unroll
;     for (int kt = 0; kt < 2; ++kt)
; #pragma unroll
;       for (int ks = 0; ks < NKS; ++ks) {
;         const bf16x8 kf = *(const bf16x8*)(Ks + (32 * kt + krow) * KSTR + ks * 16 + hh * 8);
;         s[kt] = MFMA32(kf, qf[ks], s[kt]);
;       }
;     const int kbase = tau * 64 + 8 * hh;
;     if (MODE == 0 || MODE == 1) {
;       const bool need_mask = (MODE == 1) || (tau * 64 + 63 > q0 + 32 * wid);
;       float mx = -1e30f;
;       if (need_mask) {
; #pragma unroll
;         for (int kt = 0; kt < 2; ++kt)
; #pragma unroll
;           for (int i = 0; i < 16; ++i) {
;             bool valid;
;             if (MODE == 1) valid = (mbits >> (32 * kt + 16 * (i >> 3) + (i & 7))) & 1ull;
;             else valid = (kbase + 32 * kt + 16 * (i >> 3) + (i & 7)) <= qrow;
;             s[kt][i] = valid ? s[kt][i] : -1e30f;
;           }
.LBB0_248:
	s_lshl_b32 s8, s13, 6
	v_cmp_le_i32_e32 vcc, s8, v155
	s_barrier
	s_waitcnt vmcnt(2)
	ds_write_b128 v157, v[128:131]
	s_waitcnt vmcnt(1)
	ds_write_b128 v158, v[136:139] offset:9216
	s_waitcnt vmcnt(0)
	ds_write_b128 v159, v[132:135] offset:9216
	s_waitcnt lgkmcnt(0)
	s_barrier
	s_and_saveexec_b64 s[4:5], vcc
	s_xor_b64 s[4:5], exec, s[4:5]
	s_cbranch_execz .LBB0_255
	v_add_u32_e32 v0, v149, v154
	ds_read_b128 v[10:13], v0
	ds_read_b128 v[128:131], v0 offset:32
	ds_read_b128 v[132:135], v0 offset:64
	ds_read_b128 v[136:139], v0 offset:96
	ds_read_b128 v[142:145], v0 offset:4608
	ds_read_b128 v[154:157], v0 offset:4640
	s_or_b32 s6, s8, 63
	v_cmp_gt_i32_e32 vcc, s6, v152
	s_waitcnt lgkmcnt(5)
	v_mfma_f32_32x32x16_bf16 v[96:111], v[10:13], v[124:127], 0
	ds_read_b128 v[10:13], v0 offset:4672
	s_waitcnt lgkmcnt(5)
	v_mfma_f32_32x32x16_bf16 v[96:111], v[128:131], v[120:123], v[96:111]
	ds_read_b128 v[128:131], v0 offset:4704
	s_waitcnt lgkmcnt(5)
	v_mfma_f32_32x32x16_bf16 v[96:111], v[132:135], v[116:119], v[96:111]
	s_waitcnt lgkmcnt(4)
	v_mfma_f32_32x32x16_bf16 v[96:111], v[136:139], v[112:115], v[96:111]
	s_waitcnt lgkmcnt(3)
	v_mfma_f32_32x32x16_bf16 v[80:95], v[142:145], v[124:127], 0
	s_waitcnt lgkmcnt(2)
	v_mfma_f32_32x32x16_bf16 v[80:95], v[154:157], v[120:123], v[80:95]
	s_waitcnt lgkmcnt(1)
	v_mfma_f32_32x32x16_bf16 v[80:95], v[10:13], v[116:119], v[80:95]
	s_waitcnt lgkmcnt(0)
	v_mfma_f32_32x32x16_bf16 v[80:95], v[128:131], v[112:115], v[80:95]
	s_and_saveexec_b64 s[6:7], vcc
	s_cbranch_execz .LBB0_251
	v_or_b32_e32 v0, s8, v153
	v_cmp_le_i32_e32 vcc, v0, v151
	v_or_b32_e32 v2, 2, v0
	s_nop 0
	v_cndmask_b32_e32 v96, v225, v96, vcc
	v_cmp_lt_i32_e32 vcc, v0, v151
	s_nop 1
	v_cndmask_b32_e32 v97, v225, v97, vcc
	v_cmp_le_i32_e32 vcc, v2, v151
	v_or_b32_e32 v2, 3, v0
	s_nop 0
	v_cndmask_b32_e32 v98, v225, v98, vcc
	v_cmp_le_i32_e32 vcc, v2, v151
	v_or_b32_e32 v2, 4, v0
	s_nop 0
	v_cndmask_b32_e32 v99, v225, v99, vcc
	v_cmp_le_i32_e32 vcc, v2, v151
	v_or_b32_e32 v2, 5, v0
	s_nop 0
	v_cndmask_b32_e32 v100, v225, v100, vcc
	v_cmp_le_i32_e32 vcc, v2, v151
	v_or_b32_e32 v2, 6, v0
	s_nop 0
	v_cndmask_b32_e32 v101, v225, v101, vcc
	v_cmp_le_i32_e32 vcc, v2, v151
	v_or_b32_e32 v2, 7, v0
	s_nop 0
	v_cndmask_b32_e32 v102, v225, v102, vcc
	v_cmp_le_i32_e32 vcc, v2, v151
	v_or_b32_e32 v2, 16, v0
	s_nop 0
	v_cndmask_b32_e32 v103, v225, v103, vcc
	v_cmp_le_i32_e32 vcc, v2, v151
	v_or_b32_e32 v2, 17, v0
	s_nop 0
	v_cndmask_b32_e32 v104, v225, v104, vcc
	v_cmp_le_i32_e32 vcc, v2, v151
	v_or_b32_e32 v2, 18, v0
	s_nop 0
	v_cndmask_b32_e32 v105, v225, v105, vcc
	v_cmp_le_i32_e32 vcc, v2, v151
	v_or_b32_e32 v2, 19, v0
	s_nop 0
	v_cndmask_b32_e32 v106, v225, v106, vcc
	v_cmp_le_i32_e32 vcc, v2, v151
	v_or_b32_e32 v2, 20, v0
	s_nop 0
	v_cndmask_b32_e32 v107, v225, v107, vcc
	v_cmp_le_i32_e32 vcc, v2, v151
	v_or_b32_e32 v2, 21, v0
	s_nop 0
	v_cndmask_b32_e32 v108, v225, v108, vcc
	v_cmp_le_i32_e32 vcc, v2, v151
	v_or_b32_e32 v2, 22, v0
	s_nop 0
	v_cndmask_b32_e32 v109, v225, v109, vcc
	v_cmp_le_i32_e32 vcc, v2, v151
	v_or_b32_e32 v2, 23, v0
	s_nop 0
	v_cndmask_b32_e32 v110, v225, v110, vcc
	v_cmp_le_i32_e32 vcc, v2, v151
	v_or_b32_e32 v2, 32, v0
	s_nop 0
	v_cndmask_b32_e32 v111, v225, v111, vcc
	v_cmp_le_i32_e32 vcc, v2, v151
	v_or_b32_e32 v2, 33, v0
	s_nop 0
	v_cndmask_b32_e32 v80, v225, v80, vcc
	v_cmp_le_i32_e32 vcc, v2, v151
	v_or_b32_e32 v2, 34, v0
	s_nop 0
	v_cndmask_b32_e32 v81, v225, v81, vcc
	v_cmp_le_i32_e32 vcc, v2, v151
	v_or_b32_e32 v2, 35, v0
	s_nop 0
	v_cndmask_b32_e32 v82, v225, v82, vcc
	v_cmp_le_i32_e32 vcc, v2, v151
	v_or_b32_e32 v2, 36, v0
	s_nop 0
	v_cndmask_b32_e32 v83, v225, v83, vcc
	v_cmp_le_i32_e32 vcc, v2, v151
	v_or_b32_e32 v2, 37, v0
	s_nop 0
	v_cndmask_b32_e32 v84, v225, v84, vcc
	v_cmp_le_i32_e32 vcc, v2, v151
	v_or_b32_e32 v2, 38, v0
	s_nop 0
	v_cndmask_b32_e32 v85, v225, v85, vcc
	v_cmp_le_i32_e32 vcc, v2, v151
	v_or_b32_e32 v2, 39, v0
	s_nop 0
	v_cndmask_b32_e32 v86, v225, v86, vcc
	v_cmp_le_i32_e32 vcc, v2, v151
	v_or_b32_e32 v2, 48, v0
	s_nop 0
	v_cndmask_b32_e32 v87, v225, v87, vcc
	v_cmp_le_i32_e32 vcc, v2, v151
	v_or_b32_e32 v2, 49, v0
	s_nop 0
	v_cndmask_b32_e32 v88, v225, v88, vcc
	v_cmp_le_i32_e32 vcc, v2, v151
	v_or_b32_e32 v2, 50, v0
	s_nop 0
	v_cndmask_b32_e32 v89, v225, v89, vcc
	v_cmp_le_i32_e32 vcc, v2, v151
	v_or_b32_e32 v2, 51, v0
	s_nop 0
	v_cndmask_b32_e32 v90, v225, v90, vcc
	v_cmp_le_i32_e32 vcc, v2, v151
	v_or_b32_e32 v2, 52, v0
	s_nop 0
	v_cndmask_b32_e32 v91, v225, v91, vcc
	v_cmp_le_i32_e32 vcc, v2, v151
	v_or_b32_e32 v2, 53, v0
	s_nop 0
	v_cndmask_b32_e32 v92, v225, v92, vcc
	v_cmp_le_i32_e32 vcc, v2, v151
	v_or_b32_e32 v2, 54, v0
	v_or_b32_e32 v0, 55, v0
	v_cndmask_b32_e32 v93, v225, v93, vcc
	v_cmp_le_i32_e32 vcc, v2, v151
	s_nop 1
	v_cndmask_b32_e32 v94, v225, v94, vcc
	v_cmp_le_i32_e32 vcc, v0, v151
	s_nop 1
	v_cndmask_b32_e32 v95, v225, v95, vcc

; #define MFMA32(a, b, c) __builtin_amdgcn_mfma_f32_32x32x16_bf16((a), (b), (c), 0, 0, 0)
; template <int DQK, int MODE>
; DI void attn_core(const u16* __restrict__ Qg, int ldq, const u16* __restrict__ Kg, int ldk, const u16* __restrict__ Vtg,
;                   const u64* __restrict__ maskg, int q0, float scale, char* smem, int* sflags, f32x16 (&o)[4], float& l_run) {
;     ...
;       const float msc = -m_new * sc;
;       float ls = 0.f;
; #pragma unroll
;       for (int kt = 0; kt < 2; ++kt)
; #pragma unroll
;         for (int i = 0; i < 16; ++i) {
;           float pv = __builtin_amdgcn_exp2f(__builtin_fmaf(s[kt][i], sc, msc));
;           if (MODE == 1) pv = (s[kt][i] > -1e29f) ? pv : 0.f;
;           s[kt][i] = pv;
;           ls += pv;
;         }
;     ...
; #pragma unroll
;     for (int kt = 0; kt < 2; ++kt)
; #pragma unroll
;       for (int sb = 0; sb < 2; ++sb) {
;         const bf16x8 pf = pack8(s[kt][8 * sb + 0], s[kt][8 * sb + 1], s[kt][8 * sb + 2], s[kt][8 * sb + 3],
;                                 s[kt][8 * sb + 4], s[kt][8 * sb + 5], s[kt][8 * sb + 6], s[kt][8 * sb + 7]);
; #pragma unroll
;         for (int t = 0; t < 4; ++t) {
;           const bf16x8 vf = *(const bf16x8*)(Vs + (32 * t + l31) * 72 + 32 * kt + 16 * sb + hh * 8);
;           o[t] = MFMA32(vf, pf, o[t]);
;         }
;       }
.LBB0_254:
	v_mul_f32_e32 v0, 0xbe38aa3b, v5
	v_fmamk_f32 v5, v96, 0x3e38aa3b, v0
	v_exp_f32_e32 v96, v5
	v_fmamk_f32 v6, v97, 0x3e38aa3b, v0
	v_exp_f32_e32 v97, v6
	v_fmamk_f32 v6, v98, 0x3e38aa3b, v0
	v_exp_f32_e32 v98, v6
	v_fmamk_f32 v6, v99, 0x3e38aa3b, v0
	v_exp_f32_e32 v99, v6
	v_fmamk_f32 v6, v100, 0x3e38aa3b, v0
	v_add_f32_e32 v5, 0, v96
	v_exp_f32_e32 v100, v6
	v_fmamk_f32 v6, v101, 0x3e38aa3b, v0
	v_add_f32_e32 v5, v97, v5
	v_exp_f32_e32 v101, v6
	v_fmamk_f32 v6, v102, 0x3e38aa3b, v0
	v_add_f32_e32 v5, v98, v5
	v_exp_f32_e32 v102, v6
	v_fmamk_f32 v6, v103, 0x3e38aa3b, v0
	v_add_f32_e32 v5, v99, v5
	v_exp_f32_e32 v103, v6
	v_fmamk_f32 v6, v104, 0x3e38aa3b, v0
	v_add_f32_e32 v5, v100, v5
	v_exp_f32_e32 v104, v6
	v_fmamk_f32 v6, v105, 0x3e38aa3b, v0
	v_add_f32_e32 v5, v101, v5
	v_exp_f32_e32 v105, v6
	v_fmamk_f32 v6, v106, 0x3e38aa3b, v0
	v_add_f32_e32 v5, v102, v5
	v_exp_f32_e32 v106, v6
	v_fmamk_f32 v6, v107, 0x3e38aa3b, v0
	v_add_f32_e32 v5, v103, v5
	v_exp_f32_e32 v107, v6
	v_fmamk_f32 v6, v108, 0x3e38aa3b, v0
	v_add_f32_e32 v5, v104, v5
	v_exp_f32_e32 v108, v6
	v_fmamk_f32 v6, v109, 0x3e38aa3b, v0
	v_add_f32_e32 v5, v105, v5
	v_exp_f32_e32 v109, v6
	v_fmamk_f32 v6, v110, 0x3e38aa3b, v0
	v_add_f32_e32 v5, v106, v5
	v_exp_f32_e32 v110, v6
	v_fmamk_f32 v6, v111, 0x3e38aa3b, v0
	v_add_f32_e32 v5, v107, v5
	v_exp_f32_e32 v111, v6
	v_fmamk_f32 v6, v80, 0x3e38aa3b, v0
	v_add_f32_e32 v5, v108, v5
	v_exp_f32_e32 v13, v6
	v_fmamk_f32 v6, v81, 0x3e38aa3b, v0
	v_add_f32_e32 v5, v109, v5
	v_exp_f32_e32 v14, v6
	v_fmamk_f32 v6, v82, 0x3e38aa3b, v0
	v_add_f32_e32 v5, v110, v5
	v_exp_f32_e32 v15, v6
	v_fmamk_f32 v6, v83, 0x3e38aa3b, v0
	v_add_f32_e32 v5, v111, v5
	v_exp_f32_e32 v80, v6
	v_fmamk_f32 v6, v84, 0x3e38aa3b, v0
	v_add_f32_e32 v5, v13, v5
	v_exp_f32_e32 v81, v6
	v_fmamk_f32 v6, v85, 0x3e38aa3b, v0
	v_add_f32_e32 v5, v14, v5
	v_exp_f32_e32 v82, v6
	v_fmamk_f32 v6, v86, 0x3e38aa3b, v0
	v_add_f32_e32 v5, v15, v5
	v_exp_f32_e32 v83, v6
	v_fmamk_f32 v6, v87, 0x3e38aa3b, v0
	v_add_f32_e32 v5, v80, v5
	v_exp_f32_e32 v84, v6
	v_add_f32_e32 v5, v81, v5
	v_add_f32_e32 v5, v82, v5
	v_add_f32_e32 v5, v83, v5
	v_add_f32_e32 v6, v84, v5
	v_fmamk_f32 v5, v88, 0x3e38aa3b, v0
	v_exp_f32_e32 v5, v5
	s_nop 0
	v_add_f32_e32 v7, v5, v6
	v_fmamk_f32 v6, v89, 0x3e38aa3b, v0
	v_exp_f32_e32 v6, v6
	v_cvt_pk_bf16_f32 v86, v96, v97
	v_cvt_pk_bf16_f32 v87, v98, v99
	v_cvt_pk_bf16_f32 v88, v100, v101
	v_cvt_pk_bf16_f32 v89, v102, v103
	s_nop 1
	s_nop 0
	v_add_f32_e32 v8, v6, v7
	v_fmamk_f32 v7, v90, 0x3e38aa3b, v0
	v_exp_f32_e32 v7, v7
	s_nop 0
	v_add_f32_e32 v9, v7, v8
	v_fmamk_f32 v8, v91, 0x3e38aa3b, v0
	v_exp_f32_e32 v8, v8
	s_nop 0
	v_add_f32_e32 v10, v8, v9
	v_fmamk_f32 v9, v92, 0x3e38aa3b, v0
	v_exp_f32_e32 v9, v9
	s_nop 0
	v_add_f32_e32 v11, v9, v10
	v_fmamk_f32 v10, v93, 0x3e38aa3b, v0
	v_exp_f32_e32 v10, v10
	s_nop 0
	v_add_f32_e32 v12, v10, v11
	v_fmamk_f32 v11, v94, 0x3e38aa3b, v0
	v_exp_f32_e32 v11, v11
	v_fmac_f32_e32 v0, 0x3e38aa3b, v95
	v_add_f32_e32 v85, v11, v12
	v_exp_f32_e32 v12, v0
	s_nop 0
	v_add_f32_e32 v0, v12, v85
	v_add_u32_e32 v85, v149, v150
	ds_read_b128 v[94:97], v85 offset:9216
	ds_read_b128 v[98:101], v85 offset:13824
	ds_read_b128 v[114:117], v85 offset:18432
	ds_read_b128 v[118:121], v85 offset:23040
	ds_read_b128 v[122:125], v85 offset:9248
	ds_read_b128 v[126:129], v85 offset:13856
	s_waitcnt lgkmcnt(5)
	v_mfma_f32_32x32x16_bf16 v[64:79], v[94:97], v[86:89], v[64:79]
	ds_read_b128 v[94:97], v85 offset:18464
	v_add_f32_e32 v0, v0, v112
	s_waitcnt lgkmcnt(5)
	v_mfma_f32_32x32x16_bf16 v[48:63], v[98:101], v[86:89], v[48:63]
	ds_read_b128 v[98:101], v85 offset:23072
	s_waitcnt lgkmcnt(5)
	v_mfma_f32_32x32x16_bf16 v[32:47], v[114:117], v[86:89], v[32:47]
	ds_read_b128 v[114:117], v85 offset:9280
	s_waitcnt lgkmcnt(5)
	v_mfma_f32_32x32x16_bf16 v[16:31], v[118:121], v[86:89], v[16:31]
	ds_read_b128 v[118:121], v85 offset:13888
	v_cvt_pk_bf16_f32 v86, v104, v105
	v_cvt_pk_bf16_f32 v87, v106, v107
	v_cvt_pk_bf16_f32 v88, v108, v109
	v_cvt_pk_bf16_f32 v89, v110, v111
	s_nop 1
	s_waitcnt lgkmcnt(5)
	v_mfma_f32_32x32x16_bf16 v[64:79], v[122:125], v[86:89], v[64:79]
	ds_read_b128 v[122:125], v85 offset:18496
	s_waitcnt lgkmcnt(5)
	v_mfma_f32_32x32x16_bf16 v[48:63], v[126:129], v[86:89], v[48:63]
	ds_read_b128 v[126:129], v85 offset:23104
	s_waitcnt lgkmcnt(5)
	v_mfma_f32_32x32x16_bf16 v[32:47], v[94:97], v[86:89], v[32:47]
	ds_read_b128 v[94:97], v85 offset:9312
	s_waitcnt lgkmcnt(5)
	v_mfma_f32_32x32x16_bf16 v[16:31], v[98:101], v[86:89], v[16:31]
	ds_read_b128 v[98:101], v85 offset:13920
	v_cvt_pk_bf16_f32 v86, v13, v14
	v_cvt_pk_bf16_f32 v87, v15, v80
	v_cvt_pk_bf16_f32 v88, v81, v82
	v_cvt_pk_bf16_f32 v89, v83, v84
	s_nop 1
	s_waitcnt lgkmcnt(5)
	v_mfma_f32_32x32x16_bf16 v[64:79], v[114:117], v[86:89], v[64:79]
	ds_read_b128 v[114:117], v85 offset:18528
	s_waitcnt lgkmcnt(5)
	v_mfma_f32_32x32x16_bf16 v[48:63], v[118:121], v[86:89], v[48:63]
	ds_read_b128 v[118:121], v85 offset:23136
	s_waitcnt lgkmcnt(5)
	v_mfma_f32_32x32x16_bf16 v[32:47], v[122:125], v[86:89], v[32:47]
	s_waitcnt lgkmcnt(4)
	v_mfma_f32_32x32x16_bf16 v[16:31], v[126:129], v[86:89], v[16:31]
	v_cvt_pk_bf16_f32 v80, v5, v6
	v_cvt_pk_bf16_f32 v81, v7, v8
	v_cvt_pk_bf16_f32 v82, v9, v10
	v_cvt_pk_bf16_f32 v83, v11, v12
	s_nop 1
	s_waitcnt lgkmcnt(3)
	v_mfma_f32_32x32x16_bf16 v[64:79], v[94:97], v[80:83], v[64:79]
	s_waitcnt lgkmcnt(2)
	v_mfma_f32_32x32x16_bf16 v[48:63], v[98:101], v[80:83], v[48:63]
	s_waitcnt lgkmcnt(1)
	v_mfma_f32_32x32x16_bf16 v[32:47], v[114:117], v[80:83], v[32:47]
	s_waitcnt lgkmcnt(0)
	v_mfma_f32_32x32x16_bf16 v[16:31], v[118:121], v[80:83], v[16:31]

; #define MFMA32(a, b, c) __builtin_amdgcn_mfma_f32_32x32x16_bf16((a), (b), (c), 0, 0, 0)
; DI f32x16 zero16() { f32x16 z; for (int i = 0; i < 16; ++i) z[i] = 0.f; return z; }
; template <int DQK, int MODE>
; DI void attn_core(const u16* __restrict__ Qg, int ldq, const u16* __restrict__ Kg, int ldk, const u16* __restrict__ Vtg,
;                   const u64* __restrict__ maskg, int q0, float scale, char* smem, int* sflags, f32x16 (&o)[4], float& l_run) {
;     ...
;   for (int it = 0; it < ntiles; ++it, tau += step) {
;     __syncthreads();
;     if (MODE == 2 && it > 0) {
;       if (!(sflags[0] | sflags[1] | sflags[2] | sflags[3] | sflags[4] | sflags[5] | sflags[6] | sflags[7])) break;
;     }
;     if (MODE == 2) gload(tau);
; #pragma unroll
;     for (int i = 0; i < NVK; ++i) {
;       const int v = tid + NT * i, row = v / VPR, c = v % VPR;
;       *(u32x4*)(Ks + row * KSTR + c * 8) = rk[i];
;     }
; #pragma unroll
;     for (int i = 0; i < 2; ++i) {
;       const int v = tid + NT * i, row = v >> 3, c = v & 7;
;       *(u32x4*)(Vs + row * 72 + c * 8) = rv[i];
;     }
;     __syncthreads();
;     if (MODE != 2 && it + 1 < ntiles) gload(tau + step);
;     if (tau * 64 > q0 + 32 * wid + 31) {
;       if (MODE == 2 && lane == 0) sflags[wid] = 1;
;       continue;
;     }
;     u64 mbits = 0;
;     if (MODE == 1) mbits = maskg[(long)qrow * 64 + tau] >> (8 * hh);
;     f32x16 s[2];
;     s[0] = zero16(); s[1] = zero16();
; #pragma unroll
;     for (int kt = 0; kt < 2; ++kt)
; #pragma unroll
;       for (int ks = 0; ks < NKS; ++ks) {
;         const bf16x8 kf = *(const bf16x8*)(Ks + (32 * kt + krow) * KSTR + ks * 16 + hh * 8);
;         s[kt] = MFMA32(kf, qf[ks], s[kt]);
;       }
;     const int kbase = tau * 64 + 8 * hh;
;     if (MODE == 0 || MODE == 1) {
;       const bool need_mask = (MODE == 1) || (tau * 64 + 63 > q0 + 32 * wid);
;       float mx = -1e30f;
;       if (need_mask) {
; #pragma unroll
;         for (int kt = 0; kt < 2; ++kt)
; #pragma unroll
;           for (int i = 0; i < 16; ++i) {
;             bool valid;
;             if (MODE == 1) valid = (mbits >> (32 * kt + 16 * (i >> 3) + (i & 7))) & 1ull;
;             else valid = (kbase + 32 * kt + 16 * (i >> 3) + (i & 7)) <= qrow;
;             s[kt][i] = valid ? s[kt][i] : -1e30f;
;           }
.LBB0_258:
	s_add_i32 s0, s7, 64
	v_add_u32_e32 v0, s7, v158
	v_mad_i64_i32 v[2:3], s[2:3], v0, s75, v[150:151]
	s_ashr_i32 s1, s0, 31
	s_lshl_b64 s[2:3], s[0:1], 1
	s_barrier
	s_waitcnt vmcnt(0)
	ds_write_b128 v159, v[128:131]
	ds_write_b128 v160, v[136:139] offset:9216
	ds_write_b128 v161, v[132:135] offset:9216
	s_waitcnt lgkmcnt(0)
	s_barrier
	global_load_dwordx4 v[128:131], v[2:3], off offset:1152
	v_lshl_add_u64 v[2:3], v[146:147], 0, s[2:3]
	v_lshl_add_u64 v[4:5], v[148:149], 0, s[2:3]
	global_load_dwordx4 v[136:139], v[2:3], off
	global_load_dwordx4 v[132:135], v[4:5], off
	v_cmp_le_i32_e32 vcc, s7, v157
	s_and_saveexec_b64 s[2:3], vcc
	s_cbranch_execz .LBB0_264
	v_add_u32_e32 v0, v142, v156
	ds_read_b128 v[10:13], v0
	ds_read_b128 v[164:167], v0 offset:32
	ds_read_b128 v[168:171], v0 offset:64
	ds_read_b128 v[172:175], v0 offset:96
	ds_read_b128 v[176:179], v0 offset:4608
	ds_read_b128 v[180:183], v0 offset:4640
	s_add_i32 s1, s7, 63
	v_cmp_gt_i32_e32 vcc, s1, v154
	s_waitcnt lgkmcnt(5)
	v_mfma_f32_32x32x16_bf16 v[96:111], v[10:13], v[124:127], 0
	ds_read_b128 v[10:13], v0 offset:4672
	s_waitcnt lgkmcnt(5)
	v_mfma_f32_32x32x16_bf16 v[96:111], v[164:167], v[120:123], v[96:111]
	ds_read_b128 v[164:167], v0 offset:4704
	s_waitcnt lgkmcnt(5)
	v_mfma_f32_32x32x16_bf16 v[96:111], v[168:171], v[116:119], v[96:111]
	s_waitcnt lgkmcnt(4)
	v_mfma_f32_32x32x16_bf16 v[96:111], v[172:175], v[112:115], v[96:111]
	s_waitcnt lgkmcnt(3)
	v_mfma_f32_32x32x16_bf16 v[80:95], v[176:179], v[124:127], 0
	s_waitcnt lgkmcnt(2)
	v_mfma_f32_32x32x16_bf16 v[80:95], v[180:183], v[120:123], v[80:95]
	s_waitcnt lgkmcnt(1)
	v_mfma_f32_32x32x16_bf16 v[80:95], v[10:13], v[116:119], v[80:95]
	s_waitcnt lgkmcnt(0)
	v_mfma_f32_32x32x16_bf16 v[80:95], v[164:167], v[112:115], v[80:95]
	s_and_saveexec_b64 s[4:5], vcc
	s_cbranch_execz .LBB0_261
	v_add_u32_e32 v0, s7, v155
	v_cmp_le_i32_e32 vcc, v0, v153
	v_add_u32_e32 v2, 2, v0
	s_nop 0
	v_cndmask_b32_e32 v96, v225, v96, vcc
	v_cmp_lt_i32_e32 vcc, v0, v153
	s_nop 1
	v_cndmask_b32_e32 v97, v225, v97, vcc
	v_cmp_le_i32_e32 vcc, v2, v153
	v_add_u32_e32 v2, 3, v0
	s_nop 0
	v_cndmask_b32_e32 v98, v225, v98, vcc
	v_cmp_le_i32_e32 vcc, v2, v153
	v_add_u32_e32 v2, 4, v0
	s_nop 0
	v_cndmask_b32_e32 v99, v225, v99, vcc
	v_cmp_le_i32_e32 vcc, v2, v153
	v_add_u32_e32 v2, 5, v0
	s_nop 0
	v_cndmask_b32_e32 v100, v225, v100, vcc
	v_cmp_le_i32_e32 vcc, v2, v153
	v_add_u32_e32 v2, 6, v0
	s_nop 0
	v_cndmask_b32_e32 v101, v225, v101, vcc
	v_cmp_le_i32_e32 vcc, v2, v153
	v_add_u32_e32 v2, 7, v0
	s_nop 0
	v_cndmask_b32_e32 v102, v225, v102, vcc
	v_cmp_le_i32_e32 vcc, v2, v153
	v_add_u32_e32 v2, 16, v0
	s_nop 0
	v_cndmask_b32_e32 v103, v225, v103, vcc
	v_cmp_le_i32_e32 vcc, v2, v153
	v_add_u32_e32 v2, 17, v0
	s_nop 0
	v_cndmask_b32_e32 v104, v225, v104, vcc
	v_cmp_le_i32_e32 vcc, v2, v153
	v_add_u32_e32 v2, 18, v0
	s_nop 0
	v_cndmask_b32_e32 v105, v225, v105, vcc
	v_cmp_le_i32_e32 vcc, v2, v153
	v_add_u32_e32 v2, 19, v0
	s_nop 0
	v_cndmask_b32_e32 v106, v225, v106, vcc
	v_cmp_le_i32_e32 vcc, v2, v153
	v_add_u32_e32 v2, 20, v0
	s_nop 0
	v_cndmask_b32_e32 v107, v225, v107, vcc
	v_cmp_le_i32_e32 vcc, v2, v153
	v_add_u32_e32 v2, 21, v0
	s_nop 0
	v_cndmask_b32_e32 v108, v225, v108, vcc
	v_cmp_le_i32_e32 vcc, v2, v153
	v_add_u32_e32 v2, 22, v0
	s_nop 0
	v_cndmask_b32_e32 v109, v225, v109, vcc
	v_cmp_le_i32_e32 vcc, v2, v153
	v_add_u32_e32 v2, 23, v0
	s_nop 0
	v_cndmask_b32_e32 v110, v225, v110, vcc
	v_cmp_le_i32_e32 vcc, v2, v153
	v_add_u32_e32 v2, 32, v0
	s_nop 0
	v_cndmask_b32_e32 v111, v225, v111, vcc
	v_cmp_le_i32_e32 vcc, v2, v153
	v_add_u32_e32 v2, 33, v0
	s_nop 0
	v_cndmask_b32_e32 v80, v225, v80, vcc
	v_cmp_le_i32_e32 vcc, v2, v153
	v_add_u32_e32 v2, 34, v0
	s_nop 0
	v_cndmask_b32_e32 v81, v225, v81, vcc
	v_cmp_le_i32_e32 vcc, v2, v153
	v_add_u32_e32 v2, 35, v0
	s_nop 0
	v_cndmask_b32_e32 v82, v225, v82, vcc
	v_cmp_le_i32_e32 vcc, v2, v153
	v_add_u32_e32 v2, 36, v0
	s_nop 0
	v_cndmask_b32_e32 v83, v225, v83, vcc
	v_cmp_le_i32_e32 vcc, v2, v153
	v_add_u32_e32 v2, 37, v0
	s_nop 0
	v_cndmask_b32_e32 v84, v225, v84, vcc
	v_cmp_le_i32_e32 vcc, v2, v153
	v_add_u32_e32 v2, 38, v0
	s_nop 0
	v_cndmask_b32_e32 v85, v225, v85, vcc
	v_cmp_le_i32_e32 vcc, v2, v153
	v_add_u32_e32 v2, 39, v0
	s_nop 0
	v_cndmask_b32_e32 v86, v225, v86, vcc
	v_cmp_le_i32_e32 vcc, v2, v153
	v_add_u32_e32 v2, 48, v0
	s_nop 0
	v_cndmask_b32_e32 v87, v225, v87, vcc
	v_cmp_le_i32_e32 vcc, v2, v153
	v_add_u32_e32 v2, 49, v0
	s_nop 0
	v_cndmask_b32_e32 v88, v225, v88, vcc
	v_cmp_le_i32_e32 vcc, v2, v153
	v_add_u32_e32 v2, 50, v0
	s_nop 0
	v_cndmask_b32_e32 v89, v225, v89, vcc
	v_cmp_le_i32_e32 vcc, v2, v153
	v_add_u32_e32 v2, 51, v0
	s_nop 0
	v_cndmask_b32_e32 v90, v225, v90, vcc
	v_cmp_le_i32_e32 vcc, v2, v153
	v_add_u32_e32 v2, 52, v0
	s_nop 0
	v_cndmask_b32_e32 v91, v225, v91, vcc
	v_cmp_le_i32_e32 vcc, v2, v153
	v_add_u32_e32 v2, 53, v0
	s_nop 0
	v_cndmask_b32_e32 v92, v225, v92, vcc
	v_cmp_le_i32_e32 vcc, v2, v153
	v_add_u32_e32 v2, 54, v0
	v_add_u32_e32 v0, 55, v0
	v_cndmask_b32_e32 v93, v225, v93, vcc
	v_cmp_le_i32_e32 vcc, v2, v153
	s_nop 1
	v_cndmask_b32_e32 v94, v225, v94, vcc
	v_cmp_le_i32_e32 vcc, v0, v153
	s_nop 1
	v_cndmask_b32_e32 v95, v225, v95, vcc

; #define MFMA32(a, b, c) __builtin_amdgcn_mfma_f32_32x32x16_bf16((a), (b), (c), 0, 0, 0)
; template <int DQK, int MODE>
; DI void attn_core(const u16* __restrict__ Qg, int ldq, const u16* __restrict__ Kg, int ldk, const u16* __restrict__ Vtg,
;                   const u64* __restrict__ maskg, int q0, float scale, char* smem, int* sflags, f32x16 (&o)[4], float& l_run) {
;     ...
;       const float alpha = __builtin_amdgcn_exp2f((m_run - m_new) * sc);
;       m_run = m_new;
;       const float msc = -m_new * sc;
;       float ls = 0.f;
; #pragma unroll
;       for (int kt = 0; kt < 2; ++kt)
; #pragma unroll
;         for (int i = 0; i < 16; ++i) {
;           float pv = __builtin_amdgcn_exp2f(__builtin_fmaf(s[kt][i], sc, msc));
;           if (MODE == 1) pv = (s[kt][i] > -1e29f) ? pv : 0.f;
;           s[kt][i] = pv;
;           ls += pv;
;         }
;     ...
; #pragma unroll
;     for (int kt = 0; kt < 2; ++kt)
; #pragma unroll
;       for (int sb = 0; sb < 2; ++sb) {
;         const bf16x8 pf = pack8(s[kt][8 * sb + 0], s[kt][8 * sb + 1], s[kt][8 * sb + 2], s[kt][8 * sb + 3],
;                                 s[kt][8 * sb + 4], s[kt][8 * sb + 5], s[kt][8 * sb + 6], s[kt][8 * sb + 7]);
; #pragma unroll
;         for (int t = 0; t < 4; ++t) {
;           const bf16x8 vf = *(const bf16x8*)(Vs + (32 * t + l31) * 72 + 32 * kt + 16 * sb + hh * 8);
;           o[t] = MFMA32(vf, pf, o[t]);
;         }
;       }
.LBB0_263:
	v_mul_f32_e32 v9, 0xbe38aa3b, v2
	v_fmamk_f32 v0, v96, 0x3e38aa3b, v9
	v_exp_f32_e32 v96, v0
	v_fmamk_f32 v3, v97, 0x3e38aa3b, v9
	v_exp_f32_e32 v97, v3
	v_fmamk_f32 v3, v98, 0x3e38aa3b, v9
	v_exp_f32_e32 v98, v3
	v_fmamk_f32 v3, v99, 0x3e38aa3b, v9
	v_exp_f32_e32 v99, v3
	v_fmamk_f32 v3, v100, 0x3e38aa3b, v9
	v_add_f32_e32 v0, 0, v96
	v_exp_f32_e32 v100, v3
	v_fmamk_f32 v3, v101, 0x3e38aa3b, v9
	v_add_f32_e32 v0, v97, v0
	v_exp_f32_e32 v101, v3
	v_fmamk_f32 v3, v102, 0x3e38aa3b, v9
	v_add_f32_e32 v0, v98, v0
	v_exp_f32_e32 v102, v3
	v_fmamk_f32 v3, v103, 0x3e38aa3b, v9
	v_add_f32_e32 v0, v99, v0
	v_exp_f32_e32 v103, v3
	v_fmamk_f32 v3, v104, 0x3e38aa3b, v9
	v_add_f32_e32 v0, v100, v0
	v_exp_f32_e32 v104, v3
	v_fmamk_f32 v3, v105, 0x3e38aa3b, v9
	v_add_f32_e32 v0, v101, v0
	v_exp_f32_e32 v105, v3
	v_fmamk_f32 v3, v106, 0x3e38aa3b, v9
	v_add_f32_e32 v0, v102, v0
	v_exp_f32_e32 v106, v3
	v_fmamk_f32 v3, v107, 0x3e38aa3b, v9
	v_add_f32_e32 v0, v103, v0
	v_exp_f32_e32 v107, v3
	v_fmamk_f32 v3, v108, 0x3e38aa3b, v9
	v_add_f32_e32 v0, v104, v0
	v_exp_f32_e32 v108, v3
	v_fmamk_f32 v3, v109, 0x3e38aa3b, v9
	v_add_f32_e32 v0, v105, v0
	v_exp_f32_e32 v109, v3
	v_fmamk_f32 v3, v110, 0x3e38aa3b, v9
	v_add_f32_e32 v0, v106, v0
	v_exp_f32_e32 v110, v3
	v_fmamk_f32 v3, v111, 0x3e38aa3b, v9
	v_add_f32_e32 v0, v107, v0
	v_exp_f32_e32 v111, v3
	v_fmamk_f32 v3, v80, 0x3e38aa3b, v9
	v_add_f32_e32 v0, v108, v0
	v_exp_f32_e32 v10, v3
	v_fmamk_f32 v3, v81, 0x3e38aa3b, v9
	v_add_f32_e32 v0, v109, v0
	v_exp_f32_e32 v11, v3
	v_fmamk_f32 v3, v82, 0x3e38aa3b, v9
	v_add_f32_e32 v0, v110, v0
	v_exp_f32_e32 v12, v3
	v_fmamk_f32 v3, v83, 0x3e38aa3b, v9
	v_add_f32_e32 v0, v111, v0
	v_exp_f32_e32 v13, v3
	v_fmamk_f32 v3, v84, 0x3e38aa3b, v9
	v_add_f32_e32 v0, v10, v0
	v_exp_f32_e32 v14, v3
	v_fmamk_f32 v3, v85, 0x3e38aa3b, v9
	v_add_f32_e32 v0, v11, v0
	v_exp_f32_e32 v15, v3
	v_fmamk_f32 v3, v86, 0x3e38aa3b, v9
	v_add_f32_e32 v0, v12, v0
	v_exp_f32_e32 v80, v3
	v_fmamk_f32 v3, v87, 0x3e38aa3b, v9
	v_add_f32_e32 v0, v13, v0
	v_exp_f32_e32 v81, v3
	v_add_f32_e32 v0, v14, v0
	v_add_f32_e32 v0, v15, v0
	v_add_f32_e32 v0, v80, v0
	v_add_f32_e32 v3, v81, v0
	v_fmamk_f32 v0, v88, 0x3e38aa3b, v9
	v_exp_f32_e32 v0, v0
	v_mov_b32_e32 v162, v2
	v_add_f32_e32 v4, v0, v3
	v_fmamk_f32 v3, v89, 0x3e38aa3b, v9
	v_exp_f32_e32 v3, v3
	s_nop 0
	v_add_f32_e32 v5, v3, v4
	v_fmamk_f32 v4, v90, 0x3e38aa3b, v9
	v_exp_f32_e32 v4, v4
	v_add_u32_e32 v90, v142, v152
	v_add_f32_e32 v6, v4, v5
	v_fmamk_f32 v5, v91, 0x3e38aa3b, v9
	v_exp_f32_e32 v5, v5
	s_nop 0
	v_add_f32_e32 v7, v5, v6
	v_fmamk_f32 v6, v92, 0x3e38aa3b, v9
	v_exp_f32_e32 v6, v6
	s_nop 0
	v_add_f32_e32 v8, v6, v7
	v_fmamk_f32 v7, v93, 0x3e38aa3b, v9
	v_exp_f32_e32 v7, v7
	s_nop 0
	v_add_f32_e32 v82, v7, v8
	v_fmamk_f32 v8, v94, 0x3e38aa3b, v9
	v_exp_f32_e32 v8, v8
	v_fmac_f32_e32 v9, 0x3e38aa3b, v95
	v_exp_f32_e32 v9, v9
	v_add_f32_e32 v82, v8, v82
	v_add_f32_e32 v82, v9, v82
	v_add_f32_e32 v143, v82, v143
	v_cvt_pk_bf16_f32 v82, v96, v97
	v_cvt_pk_bf16_f32 v83, v98, v99
	v_cvt_pk_bf16_f32 v84, v100, v101
	v_cvt_pk_bf16_f32 v85, v102, v103
	s_nop 1
	ds_read_b128 v[92:95], v90 offset:9216
	ds_read_b128 v[96:99], v90 offset:13824
	ds_read_b128 v[100:103], v90 offset:18432
	ds_read_b128 v[164:167], v90 offset:23040
	ds_read_b128 v[168:171], v90 offset:9248
	ds_read_b128 v[172:175], v90 offset:13856
	s_waitcnt lgkmcnt(5)
	v_mfma_f32_32x32x16_bf16 v[64:79], v[92:95], v[82:85], v[64:79]
	ds_read_b128 v[92:95], v90 offset:18464
	s_waitcnt lgkmcnt(5)
	v_mfma_f32_32x32x16_bf16 v[48:63], v[96:99], v[82:85], v[48:63]
	ds_read_b128 v[96:99], v90 offset:23072
	s_waitcnt lgkmcnt(5)
	v_mfma_f32_32x32x16_bf16 v[32:47], v[100:103], v[82:85], v[32:47]
	ds_read_b128 v[100:103], v90 offset:9280
	s_waitcnt lgkmcnt(5)
	v_mfma_f32_32x32x16_bf16 v[16:31], v[164:167], v[82:85], v[16:31]
	ds_read_b128 v[164:167], v90 offset:13888
	v_cvt_pk_bf16_f32 v82, v104, v105
	v_cvt_pk_bf16_f32 v83, v106, v107
	v_cvt_pk_bf16_f32 v84, v108, v109
	v_cvt_pk_bf16_f32 v85, v110, v111
	s_nop 1
	s_waitcnt lgkmcnt(5)
	v_mfma_f32_32x32x16_bf16 v[64:79], v[168:171], v[82:85], v[64:79]
	ds_read_b128 v[168:171], v90 offset:18496
	s_waitcnt lgkmcnt(5)
	v_mfma_f32_32x32x16_bf16 v[48:63], v[172:175], v[82:85], v[48:63]
	ds_read_b128 v[172:175], v90 offset:23104
	s_waitcnt lgkmcnt(5)
	v_mfma_f32_32x32x16_bf16 v[32:47], v[92:95], v[82:85], v[32:47]
	ds_read_b128 v[92:95], v90 offset:9312
	s_waitcnt lgkmcnt(5)
	v_mfma_f32_32x32x16_bf16 v[16:31], v[96:99], v[82:85], v[16:31]
	ds_read_b128 v[96:99], v90 offset:13920
	v_cvt_pk_bf16_f32 v82, v10, v11
	v_cvt_pk_bf16_f32 v83, v12, v13
	v_cvt_pk_bf16_f32 v84, v14, v15
	v_cvt_pk_bf16_f32 v85, v80, v81
	s_nop 1
	s_waitcnt lgkmcnt(5)
	v_mfma_f32_32x32x16_bf16 v[64:79], v[100:103], v[82:85], v[64:79]
	ds_read_b128 v[100:103], v90 offset:18528
	s_waitcnt lgkmcnt(5)
	v_mfma_f32_32x32x16_bf16 v[48:63], v[164:167], v[82:85], v[48:63]
	ds_read_b128 v[164:167], v90 offset:23136
	s_waitcnt lgkmcnt(5)
	v_mfma_f32_32x32x16_bf16 v[32:47], v[168:171], v[82:85], v[32:47]
	s_waitcnt lgkmcnt(4)
	v_mfma_f32_32x32x16_bf16 v[16:31], v[172:175], v[82:85], v[16:31]
	v_cvt_pk_bf16_f32 v10, v0, v3
	v_cvt_pk_bf16_f32 v11, v4, v5
	v_cvt_pk_bf16_f32 v12, v6, v7
	v_cvt_pk_bf16_f32 v13, v8, v9
	s_nop 1
	s_waitcnt lgkmcnt(3)
	v_mfma_f32_32x32x16_bf16 v[64:79], v[92:95], v[10:13], v[64:79]
	s_waitcnt lgkmcnt(2)
	v_mfma_f32_32x32x16_bf16 v[48:63], v[96:99], v[10:13], v[48:63]
	s_waitcnt lgkmcnt(1)
	v_mfma_f32_32x32x16_bf16 v[32:47], v[100:103], v[10:13], v[32:47]
	s_waitcnt lgkmcnt(0)
	v_mfma_f32_32x32x16_bf16 v[16:31], v[164:167], v[10:13], v[16:31]

; #define MFMA32(a, b, c) __builtin_amdgcn_mfma_f32_32x32x16_bf16((a), (b), (c), 0, 0, 0)
; DI f32x16 zero16() { f32x16 z; for (int i = 0; i < 16; ++i) z[i] = 0.f; return z; }
; template <int DQK, int MODE>
; DI void attn_core(const u16* __restrict__ Qg, int ldq, const u16* __restrict__ Kg, int ldk, const u16* __restrict__ Vtg,
;                   const u64* __restrict__ maskg, int q0, float scale, char* smem, int* sflags, f32x16 (&o)[4], float& l_run) {
;     ...
; #pragma unroll
;     for (int i = 0; i < NVK; ++i) {
;       const int v = tid + NT * i, row = v / VPR, c = v % VPR;
;       *(u32x4*)(Ks + row * KSTR + c * 8) = rk[i];
;     }
; #pragma unroll
;     for (int i = 0; i < 2; ++i) {
;       const int v = tid + NT * i, row = v >> 3, c = v & 7;
;       *(u32x4*)(Vs + row * 72 + c * 8) = rv[i];
;     }
;     __syncthreads();
;     if (MODE != 2 && it + 1 < ntiles) gload(tau + step);
;     if (tau * 64 > q0 + 32 * wid + 31) {
;       if (MODE == 2 && lane == 0) sflags[wid] = 1;
;       continue;
;     }
;     u64 mbits = 0;
;     if (MODE == 1) mbits = maskg[(long)qrow * 64 + tau] >> (8 * hh);
;     f32x16 s[2];
;     s[0] = zero16(); s[1] = zero16();
; #pragma unroll
;     for (int kt = 0; kt < 2; ++kt)
; #pragma unroll
;       for (int ks = 0; ks < NKS; ++ks) {
;         const bf16x8 kf = *(const bf16x8*)(Ks + (32 * kt + krow) * KSTR + ks * 16 + hh * 8);
;         s[kt] = MFMA32(kf, qf[ks], s[kt]);
;       }
;     const int kbase = tau * 64 + 8 * hh;
;     if (MODE == 0 || MODE == 1) {
;       const bool need_mask = (MODE == 1) || (tau * 64 + 63 > q0 + 32 * wid);
;       float mx = -1e30f;
;       if (need_mask) {
; #pragma unroll
;         for (int kt = 0; kt < 2; ++kt)
; #pragma unroll
;           for (int i = 0; i < 16; ++i) {
;             bool valid;
;             if (MODE == 1) valid = (mbits >> (32 * kt + 16 * (i >> 3) + (i & 7))) & 1ull;
;             else valid = (kbase + 32 * kt + 16 * (i >> 3) + (i & 7)) <= qrow;
;             s[kt][i] = valid ? s[kt][i] : -1e30f;
;           }
.LBB0_266:
	v_cmp_le_i32_e32 vcc, s8, v157
	s_barrier
	s_waitcnt vmcnt(2)
	ds_write_b128 v159, v[128:131]
	s_waitcnt vmcnt(1)
	ds_write_b128 v160, v[136:139] offset:9216
	s_waitcnt vmcnt(0)
	ds_write_b128 v161, v[132:135] offset:9216
	s_waitcnt lgkmcnt(0)
	s_barrier
	s_and_saveexec_b64 s[0:1], vcc
	s_cbranch_execz .LBB0_201
	v_add_u32_e32 v0, v142, v156
	ds_read_b128 v[10:13], v0
	ds_read_b128 v[128:131], v0 offset:32
	ds_read_b128 v[132:135], v0 offset:64
	ds_read_b128 v[136:139], v0 offset:96
	ds_read_b128 v[146:149], v0 offset:4608
	ds_read_b128 v[156:159], v0 offset:4640
	s_or_b32 s2, s8, 63
	v_cmp_gt_i32_e32 vcc, s2, v154
	s_waitcnt lgkmcnt(5)
	v_mfma_f32_32x32x16_bf16 v[96:111], v[10:13], v[124:127], 0
	ds_read_b128 v[10:13], v0 offset:4672
	s_waitcnt lgkmcnt(5)
	v_mfma_f32_32x32x16_bf16 v[96:111], v[128:131], v[120:123], v[96:111]
	ds_read_b128 v[128:131], v0 offset:4704
	s_waitcnt lgkmcnt(5)
	v_mfma_f32_32x32x16_bf16 v[96:111], v[132:135], v[116:119], v[96:111]
	s_waitcnt lgkmcnt(4)
	v_mfma_f32_32x32x16_bf16 v[96:111], v[136:139], v[112:115], v[96:111]
	s_waitcnt lgkmcnt(3)
	v_mfma_f32_32x32x16_bf16 v[80:95], v[146:149], v[124:127], 0
	s_waitcnt lgkmcnt(2)
	v_mfma_f32_32x32x16_bf16 v[80:95], v[156:159], v[120:123], v[80:95]
	s_waitcnt lgkmcnt(1)
	v_mfma_f32_32x32x16_bf16 v[80:95], v[10:13], v[116:119], v[80:95]
	s_waitcnt lgkmcnt(0)
	v_mfma_f32_32x32x16_bf16 v[80:95], v[128:131], v[112:115], v[80:95]
	s_and_saveexec_b64 s[2:3], vcc
	s_cbranch_execz .LBB0_269
	v_or_b32_e32 v0, s8, v155
	v_cmp_le_i32_e32 vcc, v0, v153
	v_or_b32_e32 v2, 2, v0
	s_nop 0
	v_cndmask_b32_e32 v96, v225, v96, vcc
	v_cmp_lt_i32_e32 vcc, v0, v153
	s_nop 1
	v_cndmask_b32_e32 v97, v225, v97, vcc
	v_cmp_le_i32_e32 vcc, v2, v153
	v_or_b32_e32 v2, 3, v0
	s_nop 0
	v_cndmask_b32_e32 v98, v225, v98, vcc
	v_cmp_le_i32_e32 vcc, v2, v153
	v_or_b32_e32 v2, 4, v0
	s_nop 0
	v_cndmask_b32_e32 v99, v225, v99, vcc
	v_cmp_le_i32_e32 vcc, v2, v153
	v_or_b32_e32 v2, 5, v0
	s_nop 0
	v_cndmask_b32_e32 v100, v225, v100, vcc
	v_cmp_le_i32_e32 vcc, v2, v153
	v_or_b32_e32 v2, 6, v0
	s_nop 0
	v_cndmask_b32_e32 v101, v225, v101, vcc
	v_cmp_le_i32_e32 vcc, v2, v153
	v_or_b32_e32 v2, 7, v0
	s_nop 0
	v_cndmask_b32_e32 v102, v225, v102, vcc
	v_cmp_le_i32_e32 vcc, v2, v153
	v_or_b32_e32 v2, 16, v0
	s_nop 0
	v_cndmask_b32_e32 v103, v225, v103, vcc
	v_cmp_le_i32_e32 vcc, v2, v153
	v_or_b32_e32 v2, 17, v0
	s_nop 0
	v_cndmask_b32_e32 v104, v225, v104, vcc
	v_cmp_le_i32_e32 vcc, v2, v153
	v_or_b32_e32 v2, 18, v0
	s_nop 0
	v_cndmask_b32_e32 v105, v225, v105, vcc
	v_cmp_le_i32_e32 vcc, v2, v153
	v_or_b32_e32 v2, 19, v0
	s_nop 0
	v_cndmask_b32_e32 v106, v225, v106, vcc
	v_cmp_le_i32_e32 vcc, v2, v153
	v_or_b32_e32 v2, 20, v0
	s_nop 0
	v_cndmask_b32_e32 v107, v225, v107, vcc
	v_cmp_le_i32_e32 vcc, v2, v153
	v_or_b32_e32 v2, 21, v0
	s_nop 0
	v_cndmask_b32_e32 v108, v225, v108, vcc
	v_cmp_le_i32_e32 vcc, v2, v153
	v_or_b32_e32 v2, 22, v0
	s_nop 0
	v_cndmask_b32_e32 v109, v225, v109, vcc
	v_cmp_le_i32_e32 vcc, v2, v153
	v_or_b32_e32 v2, 23, v0
	s_nop 0
	v_cndmask_b32_e32 v110, v225, v110, vcc
	v_cmp_le_i32_e32 vcc, v2, v153
	v_or_b32_e32 v2, 32, v0
	s_nop 0
	v_cndmask_b32_e32 v111, v225, v111, vcc
	v_cmp_le_i32_e32 vcc, v2, v153
	v_or_b32_e32 v2, 33, v0
	s_nop 0
	v_cndmask_b32_e32 v80, v225, v80, vcc
	v_cmp_le_i32_e32 vcc, v2, v153
	v_or_b32_e32 v2, 34, v0
	s_nop 0
	v_cndmask_b32_e32 v81, v225, v81, vcc
	v_cmp_le_i32_e32 vcc, v2, v153
	v_or_b32_e32 v2, 35, v0
	s_nop 0
	v_cndmask_b32_e32 v82, v225, v82, vcc
	v_cmp_le_i32_e32 vcc, v2, v153
	v_or_b32_e32 v2, 36, v0
	s_nop 0
	v_cndmask_b32_e32 v83, v225, v83, vcc
	v_cmp_le_i32_e32 vcc, v2, v153
	v_or_b32_e32 v2, 37, v0
	s_nop 0
	v_cndmask_b32_e32 v84, v225, v84, vcc
	v_cmp_le_i32_e32 vcc, v2, v153
	v_or_b32_e32 v2, 38, v0
	s_nop 0
	v_cndmask_b32_e32 v85, v225, v85, vcc
	v_cmp_le_i32_e32 vcc, v2, v153
	v_or_b32_e32 v2, 39, v0
	s_nop 0
	v_cndmask_b32_e32 v86, v225, v86, vcc
	v_cmp_le_i32_e32 vcc, v2, v153
	v_or_b32_e32 v2, 48, v0
	s_nop 0
	v_cndmask_b32_e32 v87, v225, v87, vcc
	v_cmp_le_i32_e32 vcc, v2, v153
	v_or_b32_e32 v2, 49, v0
	s_nop 0
	v_cndmask_b32_e32 v88, v225, v88, vcc
	v_cmp_le_i32_e32 vcc, v2, v153
	v_or_b32_e32 v2, 50, v0
	s_nop 0
	v_cndmask_b32_e32 v89, v225, v89, vcc
	v_cmp_le_i32_e32 vcc, v2, v153
	v_or_b32_e32 v2, 51, v0
	s_nop 0
	v_cndmask_b32_e32 v90, v225, v90, vcc
	v_cmp_le_i32_e32 vcc, v2, v153
	v_or_b32_e32 v2, 52, v0
	s_nop 0
	v_cndmask_b32_e32 v91, v225, v91, vcc
	v_cmp_le_i32_e32 vcc, v2, v153
	v_or_b32_e32 v2, 53, v0
	s_nop 0
	v_cndmask_b32_e32 v92, v225, v92, vcc
	v_cmp_le_i32_e32 vcc, v2, v153
	v_or_b32_e32 v2, 54, v0
	v_or_b32_e32 v0, 55, v0
	v_cndmask_b32_e32 v93, v225, v93, vcc
	v_cmp_le_i32_e32 vcc, v2, v153
	s_nop 1
	v_cndmask_b32_e32 v94, v225, v94, vcc
	v_cmp_le_i32_e32 vcc, v0, v153
	s_nop 1
	v_cndmask_b32_e32 v95, v225, v95, vcc
